# GEMM K-loop MFMA order: consecutive MFMAs always share one operand (n snake); retention epilogue deferred
# baseline (speedup 1.0000x reference)
.LBB0_285:
	ds_read_b128 v[154:157], v151
	ds_read_b128 v[158:161], v151 offset:1024
	ds_read_b128 v[164:167], v151 offset:2048
	ds_read_b128 v[168:171], v151 offset:3072
	ds_read_b128 v[172:175], v152
	ds_read_b128 v[176:179], v152 offset:1024
	ds_read_b128 v[180:183], v152 offset:2048
	ds_read_b128 v[184:187], v152 offset:3072
	s_add_u32 s36, s34, 0xfff80080
	s_addc_u32 s37, s35, -1
	s_cmp_eq_u32 s53, 28
	s_cselect_b32 s39, s16, s37
	s_cselect_b32 s38, s17, s36
	s_cselect_b32 s37, s18, s25
	s_cselect_b32 s36, s19, s23
	v_lshl_add_u64 v[146:147], s[34:35], 0, v[138:139]
	s_add_i32 m0, s31, 0xc000
	ds_read_b128 v[188:191], v153
	ds_read_b128 v[192:195], v153 offset:1024
	ds_read_b128 v[196:199], v153 offset:2048
	ds_read_b128 v[200:203], v153 offset:3072
	ds_read_b128 v[204:207], v153 offset:4096
	ds_read_b128 v[208:211], v153 offset:5120
	ds_read_b128 v[212:215], v153 offset:6144
	ds_read_b128 v[216:219], v153 offset:7168
	global_load_lds_dwordx4 v[146:147], off
	v_lshl_add_u64 v[146:147], s[34:35], 0, v[140:141]
	s_add_i32 m0, s31, 0xe000
	s_nop 0
	global_load_lds_dwordx4 v[146:147], off
	s_waitcnt vmcnt(8)
	s_waitcnt lgkmcnt(0)
	s_barrier
	s_setprio 1
	s_waitcnt lgkmcnt(0)
	v_mfma_f32_16x16x32_bf16 v[126:129], v[154:157], v[188:191], v[126:129]
	v_mfma_f32_16x16x32_bf16 v[122:125], v[164:167], v[188:191], v[122:125]
	v_mfma_f32_16x16x32_bf16 v[106:109], v[164:167], v[196:199], v[106:109]
	v_mfma_f32_16x16x32_bf16 v[110:113], v[154:157], v[196:199], v[110:113]
	v_mfma_f32_16x16x32_bf16 v[94:97], v[154:157], v[204:207], v[94:97]
	v_mfma_f32_16x16x32_bf16 v[90:93], v[164:167], v[204:207], v[90:93]
	v_mfma_f32_16x16x32_bf16 v[74:77], v[164:167], v[212:215], v[74:77]
	v_mfma_f32_16x16x32_bf16 v[78:81], v[154:157], v[212:215], v[78:81]
	v_mfma_f32_16x16x32_bf16 v[126:129], v[158:161], v[192:195], v[126:129]
	v_mfma_f32_16x16x32_bf16 v[122:125], v[168:171], v[192:195], v[122:125]
	v_mfma_f32_16x16x32_bf16 v[106:109], v[168:171], v[200:203], v[106:109]
	v_mfma_f32_16x16x32_bf16 v[110:113], v[158:161], v[200:203], v[110:113]
	v_mfma_f32_16x16x32_bf16 v[94:97], v[158:161], v[208:211], v[94:97]
	v_mfma_f32_16x16x32_bf16 v[90:93], v[168:171], v[208:211], v[90:93]
	v_mfma_f32_16x16x32_bf16 v[74:77], v[168:171], v[216:219], v[74:77]
	v_mfma_f32_16x16x32_bf16 v[78:81], v[158:161], v[216:219], v[78:81]
	s_setprio 0
	s_setprio 1
	v_mfma_f32_16x16x32_bf16 v[118:121], v[172:175], v[188:191], v[118:121]
	v_mfma_f32_16x16x32_bf16 v[114:117], v[180:183], v[188:191], v[114:117]
	v_mfma_f32_16x16x32_bf16 v[98:101], v[180:183], v[196:199], v[98:101]
	v_mfma_f32_16x16x32_bf16 v[102:105], v[172:175], v[196:199], v[102:105]
	v_mfma_f32_16x16x32_bf16 v[86:89], v[172:175], v[204:207], v[86:89]
	v_mfma_f32_16x16x32_bf16 v[82:85], v[180:183], v[204:207], v[82:85]
	v_mfma_f32_16x16x32_bf16 v[66:69], v[180:183], v[212:215], v[66:69]
	v_mfma_f32_16x16x32_bf16 v[70:73], v[172:175], v[212:215], v[70:73]
	v_mfma_f32_16x16x32_bf16 v[118:121], v[176:179], v[192:195], v[118:121]
	v_mfma_f32_16x16x32_bf16 v[114:117], v[184:187], v[192:195], v[114:117]
	v_mfma_f32_16x16x32_bf16 v[98:101], v[184:187], v[200:203], v[98:101]
	v_mfma_f32_16x16x32_bf16 v[102:105], v[176:179], v[200:203], v[102:105]
	v_mfma_f32_16x16x32_bf16 v[86:89], v[176:179], v[208:211], v[86:89]
	v_mfma_f32_16x16x32_bf16 v[82:85], v[184:187], v[208:211], v[82:85]
	v_mfma_f32_16x16x32_bf16 v[66:69], v[184:187], v[216:219], v[66:69]
	v_mfma_f32_16x16x32_bf16 v[70:73], v[176:179], v[216:219], v[70:73]
	s_setprio 0
	s_barrier
	s_add_i32 s54, s15, s44
	v_lshl_add_u64 v[146:147], s[36:37], 0, v[134:135]
	s_mov_b32 m0, s54
	ds_read_b128 v[188:191], v153 offset:16384
	ds_read_b128 v[192:195], v153 offset:17408
	ds_read_b128 v[196:199], v153 offset:18432
	ds_read_b128 v[200:203], v153 offset:19456
	ds_read_b128 v[204:207], v153 offset:20480
	ds_read_b128 v[208:211], v153 offset:21504
	ds_read_b128 v[212:215], v153 offset:22528
	ds_read_b128 v[216:219], v153 offset:23552
	global_load_lds_dwordx4 v[146:147], off
	s_add_i32 m0, s54, 0x2000
	s_add_u32 s54, s36, 0x80000
	v_lshl_add_u64 v[220:221], s[36:37], 0, v[130:131]
	s_addc_u32 s55, s37, 0
	s_add_i32 s56, s51, s44
	global_load_lds_dwordx4 v[220:221], off
	v_lshl_add_u64 v[222:223], s[54:55], 0, v[134:135]
	s_mov_b32 m0, s56
	v_lshl_add_u64 v[224:225], s[38:39], 0, v[132:133]
	global_load_lds_dwordx4 v[222:223], off
	v_lshl_add_u64 v[222:223], s[54:55], 0, v[130:131]
	s_add_i32 m0, s56, 0x2000
	s_nop 0
	global_load_lds_dwordx4 v[222:223], off
	v_lshl_add_u64 v[222:223], s[38:39], 0, v[136:137]
	s_mov_b32 m0, s31
	s_nop 0
	global_load_lds_dwordx4 v[222:223], off
	s_mov_b32 m0, s47
	s_nop 0
	global_load_lds_dwordx4 v[224:225], off
	s_waitcnt vmcnt(8)
	s_waitcnt lgkmcnt(0)
	s_barrier
	s_setprio 1
	s_waitcnt lgkmcnt(0)
	v_mfma_f32_16x16x32_bf16 v[62:65], v[154:157], v[188:191], v[62:65]
	v_mfma_f32_16x16x32_bf16 v[58:61], v[164:167], v[188:191], v[58:61]
	v_mfma_f32_16x16x32_bf16 v[42:45], v[164:167], v[196:199], v[42:45]
	v_mfma_f32_16x16x32_bf16 v[46:49], v[154:157], v[196:199], v[46:49]
	v_mfma_f32_16x16x32_bf16 v[30:33], v[154:157], v[204:207], v[30:33]
	v_mfma_f32_16x16x32_bf16 v[26:29], v[164:167], v[204:207], v[26:29]
	v_mfma_f32_16x16x32_bf16 v[10:13], v[164:167], v[212:215], v[10:13]
	v_mfma_f32_16x16x32_bf16 v[14:17], v[154:157], v[212:215], v[14:17]
	v_mfma_f32_16x16x32_bf16 v[62:65], v[158:161], v[192:195], v[62:65]
	v_mfma_f32_16x16x32_bf16 v[58:61], v[168:171], v[192:195], v[58:61]
	v_mfma_f32_16x16x32_bf16 v[42:45], v[168:171], v[200:203], v[42:45]
	v_mfma_f32_16x16x32_bf16 v[46:49], v[158:161], v[200:203], v[46:49]
	v_mfma_f32_16x16x32_bf16 v[30:33], v[158:161], v[208:211], v[30:33]
	v_mfma_f32_16x16x32_bf16 v[26:29], v[168:171], v[208:211], v[26:29]
	v_mfma_f32_16x16x32_bf16 v[10:13], v[168:171], v[216:219], v[10:13]
	v_mfma_f32_16x16x32_bf16 v[14:17], v[158:161], v[216:219], v[14:17]
	s_setprio 0
	s_setprio 1
	v_mfma_f32_16x16x32_bf16 v[54:57], v[172:175], v[188:191], v[54:57]
	v_mfma_f32_16x16x32_bf16 v[50:53], v[180:183], v[188:191], v[50:53]
	v_mfma_f32_16x16x32_bf16 v[34:37], v[180:183], v[196:199], v[34:37]
	v_mfma_f32_16x16x32_bf16 v[38:41], v[172:175], v[196:199], v[38:41]
	v_mfma_f32_16x16x32_bf16 v[22:25], v[172:175], v[204:207], v[22:25]
	v_mfma_f32_16x16x32_bf16 v[18:21], v[180:183], v[204:207], v[18:21]
	v_mfma_f32_16x16x32_bf16 v[2:5], v[180:183], v[212:215], v[2:5]
	v_mfma_f32_16x16x32_bf16 v[6:9], v[172:175], v[212:215], v[6:9]
	v_mfma_f32_16x16x32_bf16 v[54:57], v[176:179], v[192:195], v[54:57]
	v_mfma_f32_16x16x32_bf16 v[50:53], v[184:187], v[192:195], v[50:53]
	v_mfma_f32_16x16x32_bf16 v[34:37], v[184:187], v[200:203], v[34:37]
	v_mfma_f32_16x16x32_bf16 v[38:41], v[176:179], v[200:203], v[38:41]
	v_mfma_f32_16x16x32_bf16 v[22:25], v[176:179], v[208:211], v[22:25]
	v_mfma_f32_16x16x32_bf16 v[18:21], v[184:187], v[208:211], v[18:21]
	v_mfma_f32_16x16x32_bf16 v[2:5], v[184:187], v[216:219], v[2:5]
	v_mfma_f32_16x16x32_bf16 v[6:9], v[176:179], v[216:219], v[6:9]
	s_setprio 0
	s_barrier
	s_add_i32 s54, 0, 0x18000
	v_add_u32_e32 v163, s54, v149
	s_add_i32 s55, 0, 0x1c000
	ds_read_b128 v[154:157], v163
	ds_read_b128 v[158:161], v163 offset:1024
	ds_read_b128 v[164:167], v163 offset:2048
	ds_read_b128 v[168:171], v163 offset:3072
	v_add_u32_e32 v163, s55, v149
	ds_read_b128 v[172:175], v163
	ds_read_b128 v[176:179], v163 offset:1024
	ds_read_b128 v[180:183], v163 offset:2048
	ds_read_b128 v[184:187], v163 offset:3072
	s_add_u32 s38, s38, 0x80000
	s_addc_u32 s39, s39, 0
	s_mov_b32 m0, s48
	v_lshl_add_u64 v[226:227], s[38:39], 0, v[136:137]
	ds_read_b128 v[188:191], v153 offset:32768
	ds_read_b128 v[192:195], v153 offset:33792
	ds_read_b128 v[196:199], v153 offset:34816
	ds_read_b128 v[200:203], v153 offset:35840
	ds_read_b128 v[204:207], v153 offset:36864
	ds_read_b128 v[208:211], v153 offset:37888
	ds_read_b128 v[212:215], v153 offset:38912
	ds_read_b128 v[216:219], v153 offset:39936
	global_load_lds_dwordx4 v[226:227], off
	v_lshl_add_u64 v[226:227], s[38:39], 0, v[132:133]
	s_mov_b32 m0, s49
	s_nop 0
	global_load_lds_dwordx4 v[226:227], off
	s_waitcnt vmcnt(8)
	s_waitcnt lgkmcnt(0)
	s_barrier
	s_setprio 1
	s_waitcnt lgkmcnt(0)
	v_mfma_f32_16x16x32_bf16 v[126:129], v[154:157], v[188:191], v[126:129]
	v_mfma_f32_16x16x32_bf16 v[122:125], v[164:167], v[188:191], v[122:125]
	v_mfma_f32_16x16x32_bf16 v[106:109], v[164:167], v[196:199], v[106:109]
	v_mfma_f32_16x16x32_bf16 v[110:113], v[154:157], v[196:199], v[110:113]
	v_mfma_f32_16x16x32_bf16 v[94:97], v[154:157], v[204:207], v[94:97]
	v_mfma_f32_16x16x32_bf16 v[90:93], v[164:167], v[204:207], v[90:93]
	v_mfma_f32_16x16x32_bf16 v[74:77], v[164:167], v[212:215], v[74:77]
	v_mfma_f32_16x16x32_bf16 v[78:81], v[154:157], v[212:215], v[78:81]
	v_mfma_f32_16x16x32_bf16 v[126:129], v[158:161], v[192:195], v[126:129]
	v_mfma_f32_16x16x32_bf16 v[122:125], v[168:171], v[192:195], v[122:125]
	v_mfma_f32_16x16x32_bf16 v[106:109], v[168:171], v[200:203], v[106:109]
	v_mfma_f32_16x16x32_bf16 v[110:113], v[158:161], v[200:203], v[110:113]
	v_mfma_f32_16x16x32_bf16 v[94:97], v[158:161], v[208:211], v[94:97]
	v_mfma_f32_16x16x32_bf16 v[90:93], v[168:171], v[208:211], v[90:93]
	v_mfma_f32_16x16x32_bf16 v[74:77], v[168:171], v[216:219], v[74:77]
	v_mfma_f32_16x16x32_bf16 v[78:81], v[158:161], v[216:219], v[78:81]
	s_setprio 0
	s_setprio 1
	v_mfma_f32_16x16x32_bf16 v[118:121], v[172:175], v[188:191], v[118:121]
	v_mfma_f32_16x16x32_bf16 v[114:117], v[180:183], v[188:191], v[114:117]
	v_mfma_f32_16x16x32_bf16 v[98:101], v[180:183], v[196:199], v[98:101]
	v_mfma_f32_16x16x32_bf16 v[102:105], v[172:175], v[196:199], v[102:105]
	v_mfma_f32_16x16x32_bf16 v[86:89], v[172:175], v[204:207], v[86:89]
	v_mfma_f32_16x16x32_bf16 v[82:85], v[180:183], v[204:207], v[82:85]
	v_mfma_f32_16x16x32_bf16 v[66:69], v[180:183], v[212:215], v[66:69]
	v_mfma_f32_16x16x32_bf16 v[70:73], v[172:175], v[212:215], v[70:73]
	v_mfma_f32_16x16x32_bf16 v[118:121], v[176:179], v[192:195], v[118:121]
	v_mfma_f32_16x16x32_bf16 v[114:117], v[184:187], v[192:195], v[114:117]
	v_mfma_f32_16x16x32_bf16 v[98:101], v[184:187], v[200:203], v[98:101]
	v_mfma_f32_16x16x32_bf16 v[102:105], v[176:179], v[200:203], v[102:105]
	v_mfma_f32_16x16x32_bf16 v[86:89], v[176:179], v[208:211], v[86:89]
	v_mfma_f32_16x16x32_bf16 v[82:85], v[184:187], v[208:211], v[82:85]
	v_mfma_f32_16x16x32_bf16 v[66:69], v[184:187], v[216:219], v[66:69]
	v_mfma_f32_16x16x32_bf16 v[70:73], v[176:179], v[216:219], v[70:73]
	s_setprio 0
	s_barrier
	s_add_i32 s38, s54, s44
	v_lshl_add_u64 v[146:147], v[146:147], 0, s[10:11]
	s_mov_b32 m0, s38
	ds_read_b128 v[188:191], v153 offset:49152
	ds_read_b128 v[192:195], v153 offset:50176
	ds_read_b128 v[196:199], v153 offset:51200
	ds_read_b128 v[200:203], v153 offset:52224
	ds_read_b128 v[204:207], v153 offset:53248
	ds_read_b128 v[208:211], v153 offset:54272
	ds_read_b128 v[212:215], v153 offset:55296
	ds_read_b128 v[216:219], v153 offset:56320
	global_load_lds_dwordx4 v[146:147], off
	s_add_i32 m0, s38, 0x2000
	s_add_u32 s36, s36, 0x80080
	v_lshl_add_u64 v[146:147], v[220:221], 0, s[10:11]
	s_addc_u32 s37, s37, 0
	s_add_i32 s38, s55, s44
	global_load_lds_dwordx4 v[146:147], off
	v_lshl_add_u64 v[146:147], s[36:37], 0, v[134:135]
	s_mov_b32 m0, s38
	s_nop 0
	global_load_lds_dwordx4 v[146:147], off
	v_lshl_add_u64 v[146:147], s[36:37], 0, v[130:131]
	s_add_i32 m0, s38, 0x2000
	s_nop 0
	global_load_lds_dwordx4 v[146:147], off
	v_lshl_add_u64 v[146:147], v[222:223], 0, s[10:11]
	s_mov_b32 m0, s20
	s_nop 0
	global_load_lds_dwordx4 v[146:147], off
	v_lshl_add_u64 v[146:147], v[224:225], 0, s[10:11]
	s_mov_b32 m0, s21
	s_nop 0
	global_load_lds_dwordx4 v[146:147], off
	s_waitcnt vmcnt(8)
	s_waitcnt lgkmcnt(0)
	s_barrier
	s_setprio 1
	s_waitcnt lgkmcnt(0)
	v_mfma_f32_16x16x32_bf16 v[62:65], v[154:157], v[188:191], v[62:65]
	v_mfma_f32_16x16x32_bf16 v[58:61], v[164:167], v[188:191], v[58:61]
	v_mfma_f32_16x16x32_bf16 v[42:45], v[164:167], v[196:199], v[42:45]
	v_mfma_f32_16x16x32_bf16 v[46:49], v[154:157], v[196:199], v[46:49]
	v_mfma_f32_16x16x32_bf16 v[30:33], v[154:157], v[204:207], v[30:33]
	v_mfma_f32_16x16x32_bf16 v[26:29], v[164:167], v[204:207], v[26:29]
	v_mfma_f32_16x16x32_bf16 v[10:13], v[164:167], v[212:215], v[10:13]
	v_mfma_f32_16x16x32_bf16 v[14:17], v[154:157], v[212:215], v[14:17]
	v_mfma_f32_16x16x32_bf16 v[62:65], v[158:161], v[192:195], v[62:65]
	v_mfma_f32_16x16x32_bf16 v[58:61], v[168:171], v[192:195], v[58:61]
	v_mfma_f32_16x16x32_bf16 v[42:45], v[168:171], v[200:203], v[42:45]
	v_mfma_f32_16x16x32_bf16 v[46:49], v[158:161], v[200:203], v[46:49]
	v_mfma_f32_16x16x32_bf16 v[30:33], v[158:161], v[208:211], v[30:33]
	v_mfma_f32_16x16x32_bf16 v[26:29], v[168:171], v[208:211], v[26:29]
	v_mfma_f32_16x16x32_bf16 v[10:13], v[168:171], v[216:219], v[10:13]
	v_mfma_f32_16x16x32_bf16 v[14:17], v[158:161], v[216:219], v[14:17]
	s_setprio 0
	s_setprio 1
	v_mfma_f32_16x16x32_bf16 v[54:57], v[172:175], v[188:191], v[54:57]
	v_mfma_f32_16x16x32_bf16 v[50:53], v[180:183], v[188:191], v[50:53]
	v_mfma_f32_16x16x32_bf16 v[34:37], v[180:183], v[196:199], v[34:37]
	v_mfma_f32_16x16x32_bf16 v[38:41], v[172:175], v[196:199], v[38:41]
	v_mfma_f32_16x16x32_bf16 v[22:25], v[172:175], v[204:207], v[22:25]
	v_mfma_f32_16x16x32_bf16 v[18:21], v[180:183], v[204:207], v[18:21]
	v_mfma_f32_16x16x32_bf16 v[2:5], v[180:183], v[212:215], v[2:5]
	v_mfma_f32_16x16x32_bf16 v[6:9], v[172:175], v[212:215], v[6:9]
	v_mfma_f32_16x16x32_bf16 v[54:57], v[176:179], v[192:195], v[54:57]
	v_mfma_f32_16x16x32_bf16 v[50:53], v[184:187], v[192:195], v[50:53]
	v_mfma_f32_16x16x32_bf16 v[34:37], v[184:187], v[200:203], v[34:37]
	v_mfma_f32_16x16x32_bf16 v[38:41], v[176:179], v[200:203], v[38:41]
	v_mfma_f32_16x16x32_bf16 v[22:25], v[176:179], v[208:211], v[22:25]
	v_mfma_f32_16x16x32_bf16 v[18:21], v[184:187], v[208:211], v[18:21]
	v_mfma_f32_16x16x32_bf16 v[2:5], v[184:187], v[216:219], v[2:5]
	v_mfma_f32_16x16x32_bf16 v[6:9], v[176:179], v[216:219], v[6:9]
	s_setprio 0
	s_barrier
	s_add_i32 s53, s53, 2
	s_add_u32 s34, s34, 0x100
	s_addc_u32 s35, s35, 0
	s_add_u32 s23, s23, 0x100
	s_addc_u32 s25, s25, 0
	s_cmp_gt_u32 s53, 29
	s_cbranch_scc0 .LBB0_285
	s_and_b64 vcc, exec, s[12:13]
	s_cbranch_vccz .LBB0_288
	s_barrier

.LBB0_356:
	ds_read_b128 v[134:137], v213
	ds_read_b128 v[138:141], v213 offset:1024
	ds_read_b128 v[142:145], v213 offset:2048
	ds_read_b128 v[178:181], v213 offset:3072
	ds_read_b128 v[182:185], v214
	ds_read_b128 v[186:189], v214 offset:1024
	ds_read_b128 v[190:193], v214 offset:2048
	ds_read_b128 v[194:197], v214 offset:3072
	s_add_u32 s36, s34, 0x100
	s_addc_u32 s37, s35, 0
	s_add_u32 s16, s3, s34
	s_addc_u32 s17, s14, s35
	s_cmpk_eq_i32 s15, 0x54
	s_cselect_b32 s41, s27, s17
	s_cselect_b32 s17, 0, s36
	s_cselect_b32 s40, s26, s16
	s_cselect_b32 s16, 0, s37
	s_add_u32 s38, s8, s17
	s_addc_u32 s39, s9, s16
	s_mov_b32 m0, s63
	v_lshl_add_u64 v[244:245], v[130:131], 0, s[34:35]
	ds_read_b128 v[198:201], v215
	ds_read_b128 v[202:205], v215 offset:1024
	ds_read_b128 v[206:209], v215 offset:2048
	ds_read_b128 v[224:227], v215 offset:3072
	ds_read_b128 v[228:231], v215 offset:4096
	ds_read_b128 v[232:235], v215 offset:5120
	ds_read_b128 v[236:239], v215 offset:6144
	ds_read_b128 v[240:243], v215 offset:7168
	global_load_lds_dwordx4 v[244:245], off
	v_lshl_add_u64 v[244:245], v[132:133], 0, s[34:35]
	s_mov_b32 m0, s64
	s_nop 0
	global_load_lds_dwordx4 v[244:245], off
	s_waitcnt vmcnt(8)
	s_waitcnt lgkmcnt(0)
	s_barrier
	s_setprio 1
	s_waitcnt lgkmcnt(0)
	v_mfma_f32_16x16x32_bf16 v[86:89], v[134:137], v[198:201], v[86:89]
	v_mfma_f32_16x16x32_bf16 v[82:85], v[142:145], v[198:201], v[82:85]
	v_mfma_f32_16x16x32_bf16 v[106:109], v[142:145], v[206:209], v[106:109]
	v_mfma_f32_16x16x32_bf16 v[110:113], v[134:137], v[206:209], v[110:113]
	v_mfma_f32_16x16x32_bf16 v[118:121], v[134:137], v[228:231], v[118:121]
	v_mfma_f32_16x16x32_bf16 v[114:117], v[142:145], v[228:231], v[114:117]
	v_mfma_f32_16x16x32_bf16 v[122:125], v[142:145], v[236:239], v[122:125]
	v_mfma_f32_16x16x32_bf16 v[126:129], v[134:137], v[236:239], v[126:129]
	v_mfma_f32_16x16x32_bf16 v[86:89], v[138:141], v[202:205], v[86:89]
	v_mfma_f32_16x16x32_bf16 v[82:85], v[178:181], v[202:205], v[82:85]
	v_mfma_f32_16x16x32_bf16 v[106:109], v[178:181], v[224:227], v[106:109]
	v_mfma_f32_16x16x32_bf16 v[110:113], v[138:141], v[224:227], v[110:113]
	v_mfma_f32_16x16x32_bf16 v[118:121], v[138:141], v[232:235], v[118:121]
	v_mfma_f32_16x16x32_bf16 v[114:117], v[178:181], v[232:235], v[114:117]
	v_mfma_f32_16x16x32_bf16 v[122:125], v[178:181], v[240:243], v[122:125]
	v_mfma_f32_16x16x32_bf16 v[126:129], v[138:141], v[240:243], v[126:129]
	s_setprio 0
	s_setprio 1
	v_mfma_f32_16x16x32_bf16 v[26:29], v[182:185], v[198:201], v[26:29]
	v_mfma_f32_16x16x32_bf16 v[30:33], v[190:193], v[198:201], v[30:33]
	v_mfma_f32_16x16x32_bf16 v[50:53], v[190:193], v[206:209], v[50:53]
	v_mfma_f32_16x16x32_bf16 v[42:45], v[182:185], v[206:209], v[42:45]
	v_mfma_f32_16x16x32_bf16 v[66:69], v[182:185], v[228:231], v[66:69]
	v_mfma_f32_16x16x32_bf16 v[70:73], v[190:193], v[228:231], v[70:73]
	v_mfma_f32_16x16x32_bf16 v[94:97], v[190:193], v[236:239], v[94:97]
	v_mfma_f32_16x16x32_bf16 v[90:93], v[182:185], v[236:239], v[90:93]
	v_mfma_f32_16x16x32_bf16 v[26:29], v[186:189], v[202:205], v[26:29]
	v_mfma_f32_16x16x32_bf16 v[30:33], v[194:197], v[202:205], v[30:33]
	v_mfma_f32_16x16x32_bf16 v[50:53], v[194:197], v[224:227], v[50:53]
	v_mfma_f32_16x16x32_bf16 v[42:45], v[186:189], v[224:227], v[42:45]
	v_mfma_f32_16x16x32_bf16 v[66:69], v[186:189], v[232:235], v[66:69]
	v_mfma_f32_16x16x32_bf16 v[70:73], v[194:197], v[232:235], v[70:73]
	v_mfma_f32_16x16x32_bf16 v[94:97], v[194:197], v[240:243], v[94:97]
	v_mfma_f32_16x16x32_bf16 v[90:93], v[186:189], v[240:243], v[90:93]
	s_setprio 0
	s_barrier
	s_mov_b32 m0, s65
	v_lshl_add_u64 v[244:245], s[38:39], 0, v[150:151]
	s_add_u32 s16, s38, 0x160000
	ds_read_b128 v[198:201], v215 offset:16384
	ds_read_b128 v[202:205], v215 offset:17408
	ds_read_b128 v[206:209], v215 offset:18432
	ds_read_b128 v[224:227], v215 offset:19456
	ds_read_b128 v[228:231], v215 offset:20480
	ds_read_b128 v[232:235], v215 offset:21504
	ds_read_b128 v[236:239], v215 offset:22528
	ds_read_b128 v[240:243], v215 offset:23552
	global_load_lds_dwordx4 v[244:245], off
	v_lshl_add_u64 v[246:247], s[38:39], 0, v[146:147]
	s_mov_b32 m0, s66
	s_addc_u32 s17, s39, 0
	global_load_lds_dwordx4 v[246:247], off
	v_lshl_add_u64 v[248:249], s[16:17], 0, v[150:151]
	s_mov_b32 m0, s67
	v_lshl_add_u64 v[250:251], s[40:41], 0, v[148:149]
	global_load_lds_dwordx4 v[248:249], off
	v_lshl_add_u64 v[248:249], s[16:17], 0, v[146:147]
	s_mov_b32 m0, s68
	s_nop 0
	global_load_lds_dwordx4 v[248:249], off
	v_lshl_add_u64 v[248:249], s[40:41], 0, v[152:153]
	s_mov_b32 m0, s51
	s_nop 0
	global_load_lds_dwordx4 v[248:249], off
	s_mov_b32 m0, s52
	s_nop 0
	global_load_lds_dwordx4 v[250:251], off
	s_waitcnt vmcnt(8)
	s_waitcnt lgkmcnt(0)
	s_barrier
	s_setprio 1
	s_waitcnt lgkmcnt(0)
	v_mfma_f32_16x16x32_bf16 v[102:105], v[134:137], v[198:201], v[102:105]
	v_mfma_f32_16x16x32_bf16 v[98:101], v[142:145], v[198:201], v[98:101]
	v_mfma_f32_16x16x32_bf16 v[58:61], v[142:145], v[206:209], v[58:61]
	v_mfma_f32_16x16x32_bf16 v[62:65], v[134:137], v[206:209], v[62:65]
	v_mfma_f32_16x16x32_bf16 v[38:41], v[134:137], v[228:231], v[38:41]
	v_mfma_f32_16x16x32_bf16 v[34:37], v[142:145], v[228:231], v[34:37]
	v_mfma_f32_16x16x32_bf16 v[10:13], v[142:145], v[236:239], v[10:13]
	v_mfma_f32_16x16x32_bf16 v[14:17], v[134:137], v[236:239], v[14:17]
	v_mfma_f32_16x16x32_bf16 v[102:105], v[138:141], v[202:205], v[102:105]
	v_mfma_f32_16x16x32_bf16 v[98:101], v[178:181], v[202:205], v[98:101]
	v_mfma_f32_16x16x32_bf16 v[58:61], v[178:181], v[224:227], v[58:61]
	v_mfma_f32_16x16x32_bf16 v[62:65], v[138:141], v[224:227], v[62:65]
	v_mfma_f32_16x16x32_bf16 v[38:41], v[138:141], v[232:235], v[38:41]
	v_mfma_f32_16x16x32_bf16 v[34:37], v[178:181], v[232:235], v[34:37]
	v_mfma_f32_16x16x32_bf16 v[10:13], v[178:181], v[240:243], v[10:13]
	v_mfma_f32_16x16x32_bf16 v[14:17], v[138:141], v[240:243], v[14:17]
	s_setprio 0
	s_setprio 1
	v_mfma_f32_16x16x32_bf16 v[78:81], v[182:185], v[198:201], v[78:81]
	v_mfma_f32_16x16x32_bf16 v[74:77], v[190:193], v[198:201], v[74:77]
	v_mfma_f32_16x16x32_bf16 v[46:49], v[190:193], v[206:209], v[46:49]
	v_mfma_f32_16x16x32_bf16 v[54:57], v[182:185], v[206:209], v[54:57]
	v_mfma_f32_16x16x32_bf16 v[22:25], v[182:185], v[228:231], v[22:25]
	v_mfma_f32_16x16x32_bf16 v[18:21], v[190:193], v[228:231], v[18:21]
	v_mfma_f32_16x16x32_bf16 v[2:5], v[190:193], v[236:239], v[2:5]
	v_mfma_f32_16x16x32_bf16 v[6:9], v[182:185], v[236:239], v[6:9]
	v_mfma_f32_16x16x32_bf16 v[78:81], v[186:189], v[202:205], v[78:81]
	v_mfma_f32_16x16x32_bf16 v[74:77], v[194:197], v[202:205], v[74:77]
	v_mfma_f32_16x16x32_bf16 v[46:49], v[194:197], v[224:227], v[46:49]
	v_mfma_f32_16x16x32_bf16 v[54:57], v[186:189], v[224:227], v[54:57]
	v_mfma_f32_16x16x32_bf16 v[22:25], v[186:189], v[232:235], v[22:25]
	v_mfma_f32_16x16x32_bf16 v[18:21], v[194:197], v[232:235], v[18:21]
	v_mfma_f32_16x16x32_bf16 v[2:5], v[194:197], v[240:243], v[2:5]
	v_mfma_f32_16x16x32_bf16 v[6:9], v[186:189], v[240:243], v[6:9]
	s_setprio 0
	s_barrier
	ds_read_b128 v[134:137], v219
	ds_read_b128 v[138:141], v219 offset:1024
	ds_read_b128 v[142:145], v219 offset:2048
	ds_read_b128 v[178:181], v219 offset:3072
	ds_read_b128 v[182:185], v220
	ds_read_b128 v[186:189], v220 offset:1024
	ds_read_b128 v[190:193], v220 offset:2048
	ds_read_b128 v[194:197], v220 offset:3072
	s_add_u32 s16, s40, 0x160000
	s_addc_u32 s17, s41, 0
	s_mov_b32 m0, s53
	v_lshl_add_u64 v[252:253], s[16:17], 0, v[152:153]
	ds_read_b128 v[198:201], v215 offset:32768
	ds_read_b128 v[202:205], v215 offset:33792
	ds_read_b128 v[206:209], v215 offset:34816
	ds_read_b128 v[224:227], v215 offset:35840
	ds_read_b128 v[228:231], v215 offset:36864
	ds_read_b128 v[232:235], v215 offset:37888
	ds_read_b128 v[236:239], v215 offset:38912
	ds_read_b128 v[240:243], v215 offset:39936
	global_load_lds_dwordx4 v[252:253], off
	v_lshl_add_u64 v[252:253], s[16:17], 0, v[148:149]
	s_mov_b32 m0, s54
	s_nop 0
	global_load_lds_dwordx4 v[252:253], off
	s_waitcnt vmcnt(8)
	s_waitcnt lgkmcnt(0)
	s_barrier
	s_setprio 1
	s_waitcnt lgkmcnt(0)
	v_mfma_f32_16x16x32_bf16 v[86:89], v[134:137], v[198:201], v[86:89]
	v_mfma_f32_16x16x32_bf16 v[82:85], v[142:145], v[198:201], v[82:85]
	v_mfma_f32_16x16x32_bf16 v[106:109], v[142:145], v[206:209], v[106:109]
	v_mfma_f32_16x16x32_bf16 v[110:113], v[134:137], v[206:209], v[110:113]
	v_mfma_f32_16x16x32_bf16 v[118:121], v[134:137], v[228:231], v[118:121]
	v_mfma_f32_16x16x32_bf16 v[114:117], v[142:145], v[228:231], v[114:117]
	v_mfma_f32_16x16x32_bf16 v[122:125], v[142:145], v[236:239], v[122:125]
	v_mfma_f32_16x16x32_bf16 v[126:129], v[134:137], v[236:239], v[126:129]
	v_mfma_f32_16x16x32_bf16 v[86:89], v[138:141], v[202:205], v[86:89]
	v_mfma_f32_16x16x32_bf16 v[82:85], v[178:181], v[202:205], v[82:85]
	v_mfma_f32_16x16x32_bf16 v[106:109], v[178:181], v[224:227], v[106:109]
	v_mfma_f32_16x16x32_bf16 v[110:113], v[138:141], v[224:227], v[110:113]
	v_mfma_f32_16x16x32_bf16 v[118:121], v[138:141], v[232:235], v[118:121]
	v_mfma_f32_16x16x32_bf16 v[114:117], v[178:181], v[232:235], v[114:117]
	v_mfma_f32_16x16x32_bf16 v[122:125], v[178:181], v[240:243], v[122:125]
	v_mfma_f32_16x16x32_bf16 v[126:129], v[138:141], v[240:243], v[126:129]
	s_setprio 0
	s_setprio 1
	v_mfma_f32_16x16x32_bf16 v[26:29], v[182:185], v[198:201], v[26:29]
	v_mfma_f32_16x16x32_bf16 v[30:33], v[190:193], v[198:201], v[30:33]
	v_mfma_f32_16x16x32_bf16 v[50:53], v[190:193], v[206:209], v[50:53]
	v_mfma_f32_16x16x32_bf16 v[42:45], v[182:185], v[206:209], v[42:45]
	v_mfma_f32_16x16x32_bf16 v[66:69], v[182:185], v[228:231], v[66:69]
	v_mfma_f32_16x16x32_bf16 v[70:73], v[190:193], v[228:231], v[70:73]
	v_mfma_f32_16x16x32_bf16 v[94:97], v[190:193], v[236:239], v[94:97]
	v_mfma_f32_16x16x32_bf16 v[90:93], v[182:185], v[236:239], v[90:93]
	v_mfma_f32_16x16x32_bf16 v[26:29], v[186:189], v[202:205], v[26:29]
	v_mfma_f32_16x16x32_bf16 v[30:33], v[194:197], v[202:205], v[30:33]
	v_mfma_f32_16x16x32_bf16 v[50:53], v[194:197], v[224:227], v[50:53]
	v_mfma_f32_16x16x32_bf16 v[42:45], v[186:189], v[224:227], v[42:45]
	v_mfma_f32_16x16x32_bf16 v[66:69], v[186:189], v[232:235], v[66:69]
	v_mfma_f32_16x16x32_bf16 v[70:73], v[194:197], v[232:235], v[70:73]
	v_mfma_f32_16x16x32_bf16 v[94:97], v[194:197], v[240:243], v[94:97]
	v_mfma_f32_16x16x32_bf16 v[90:93], v[186:189], v[240:243], v[90:93]
	s_setprio 0
	s_barrier
	s_mov_b32 m0, s69
	v_lshl_add_u64 v[244:245], v[244:245], 0, s[22:23]
	s_add_u32 s16, s38, 0x160080
	ds_read_b128 v[198:201], v215 offset:49152
	ds_read_b128 v[202:205], v215 offset:50176
	ds_read_b128 v[206:209], v215 offset:51200
	ds_read_b128 v[224:227], v215 offset:52224
	ds_read_b128 v[228:231], v215 offset:53248
	ds_read_b128 v[232:235], v215 offset:54272
	ds_read_b128 v[236:239], v215 offset:55296
	ds_read_b128 v[240:243], v215 offset:56320
	global_load_lds_dwordx4 v[244:245], off
	v_lshl_add_u64 v[244:245], v[246:247], 0, s[22:23]
	s_mov_b32 m0, s73
	s_addc_u32 s17, s39, 0
	global_load_lds_dwordx4 v[244:245], off
	v_lshl_add_u64 v[244:245], s[16:17], 0, v[150:151]
	s_mov_b32 m0, s74
	s_nop 0
	global_load_lds_dwordx4 v[244:245], off
	v_lshl_add_u64 v[244:245], s[16:17], 0, v[146:147]
	s_mov_b32 m0, s75
	s_nop 0
	global_load_lds_dwordx4 v[244:245], off
	v_lshl_add_u64 v[244:245], v[248:249], 0, s[22:23]
	s_mov_b32 m0, s60
	s_nop 0
	global_load_lds_dwordx4 v[244:245], off
	v_lshl_add_u64 v[244:245], v[250:251], 0, s[22:23]
	s_mov_b32 m0, s61
	s_nop 0
	global_load_lds_dwordx4 v[244:245], off
	s_waitcnt vmcnt(8)
	s_waitcnt lgkmcnt(0)
	s_barrier
	s_setprio 1
	s_waitcnt lgkmcnt(0)
	v_mfma_f32_16x16x32_bf16 v[102:105], v[134:137], v[198:201], v[102:105]
	v_mfma_f32_16x16x32_bf16 v[98:101], v[142:145], v[198:201], v[98:101]
	v_mfma_f32_16x16x32_bf16 v[58:61], v[142:145], v[206:209], v[58:61]
	v_mfma_f32_16x16x32_bf16 v[62:65], v[134:137], v[206:209], v[62:65]
	v_mfma_f32_16x16x32_bf16 v[38:41], v[134:137], v[228:231], v[38:41]
	v_mfma_f32_16x16x32_bf16 v[34:37], v[142:145], v[228:231], v[34:37]
	v_mfma_f32_16x16x32_bf16 v[10:13], v[142:145], v[236:239], v[10:13]
	v_mfma_f32_16x16x32_bf16 v[14:17], v[134:137], v[236:239], v[14:17]
	v_mfma_f32_16x16x32_bf16 v[102:105], v[138:141], v[202:205], v[102:105]
	v_mfma_f32_16x16x32_bf16 v[98:101], v[178:181], v[202:205], v[98:101]
	v_mfma_f32_16x16x32_bf16 v[58:61], v[178:181], v[224:227], v[58:61]
	v_mfma_f32_16x16x32_bf16 v[62:65], v[138:141], v[224:227], v[62:65]
	v_mfma_f32_16x16x32_bf16 v[38:41], v[138:141], v[232:235], v[38:41]
	v_mfma_f32_16x16x32_bf16 v[34:37], v[178:181], v[232:235], v[34:37]
	v_mfma_f32_16x16x32_bf16 v[10:13], v[178:181], v[240:243], v[10:13]
	v_mfma_f32_16x16x32_bf16 v[14:17], v[138:141], v[240:243], v[14:17]
	s_setprio 0
	s_setprio 1
	v_mfma_f32_16x16x32_bf16 v[78:81], v[182:185], v[198:201], v[78:81]
	v_mfma_f32_16x16x32_bf16 v[74:77], v[190:193], v[198:201], v[74:77]
	v_mfma_f32_16x16x32_bf16 v[46:49], v[190:193], v[206:209], v[46:49]
	v_mfma_f32_16x16x32_bf16 v[54:57], v[182:185], v[206:209], v[54:57]
	v_mfma_f32_16x16x32_bf16 v[22:25], v[182:185], v[228:231], v[22:25]
	v_mfma_f32_16x16x32_bf16 v[18:21], v[190:193], v[228:231], v[18:21]
	v_mfma_f32_16x16x32_bf16 v[2:5], v[190:193], v[236:239], v[2:5]
	v_mfma_f32_16x16x32_bf16 v[6:9], v[182:185], v[236:239], v[6:9]
	v_mfma_f32_16x16x32_bf16 v[78:81], v[186:189], v[202:205], v[78:81]
	v_mfma_f32_16x16x32_bf16 v[74:77], v[194:197], v[202:205], v[74:77]
	v_mfma_f32_16x16x32_bf16 v[46:49], v[194:197], v[224:227], v[46:49]
	v_mfma_f32_16x16x32_bf16 v[54:57], v[186:189], v[224:227], v[54:57]
	v_mfma_f32_16x16x32_bf16 v[22:25], v[186:189], v[232:235], v[22:25]
	v_mfma_f32_16x16x32_bf16 v[18:21], v[194:197], v[232:235], v[18:21]
	v_mfma_f32_16x16x32_bf16 v[2:5], v[194:197], v[240:243], v[2:5]
	v_mfma_f32_16x16x32_bf16 v[6:9], v[186:189], v[240:243], v[6:9]
	s_setprio 0
	s_barrier
	s_add_i32 s15, s15, 2
	s_cmpk_gt_u32 s15, 0x55
	s_mov_b64 s[34:35], s[36:37]
	s_cbranch_scc0 .LBB0_356
	s_and_b64 vcc, exec, s[24:25]
	s_cbranch_vccz .LBB0_359
	s_barrier

.LBB0_466:
	ds_read_b128 v[130:133], v170
	ds_read_b128 v[134:137], v170 offset:1024
	ds_read_b128 v[164:167], v170 offset:2048
	ds_read_b128 v[174:177], v170 offset:3072
	ds_read_b128 v[178:181], v171
	ds_read_b128 v[182:185], v171 offset:1024
	ds_read_b128 v[186:189], v171 offset:2048
	ds_read_b128 v[190:193], v171 offset:3072
	s_add_u32 s19, s42, 0xfff80080
	s_addc_u32 s20, s43, -1
	s_cmp_eq_u32 s18, 28
	s_cselect_b32 s47, s3, s20
	s_cselect_b32 s46, s7, s19
	s_cselect_b32 s45, s14, s17
	s_cselect_b32 s44, s15, s16
	v_lshl_add_u64 v[168:169], s[42:43], 0, v[154:155]
	s_add_i32 m0, s41, 0xc000
	ds_read_b128 v[194:197], v172
	ds_read_b128 v[198:201], v172 offset:1024
	ds_read_b128 v[202:205], v172 offset:2048
	ds_read_b128 v[206:209], v172 offset:3072
	ds_read_b128 v[210:213], v172 offset:4096
	ds_read_b128 v[214:217], v172 offset:5120
	ds_read_b128 v[218:221], v172 offset:6144
	ds_read_b128 v[222:225], v172 offset:7168
	global_load_lds_dwordx4 v[168:169], off
	v_lshl_add_u64 v[168:169], s[42:43], 0, v[156:157]
	s_add_i32 m0, s41, 0xe000
	s_nop 0
	global_load_lds_dwordx4 v[168:169], off
	s_waitcnt vmcnt(8)
	s_waitcnt lgkmcnt(0)
	s_barrier
	s_setprio 1
	s_waitcnt lgkmcnt(0)
	v_mfma_f32_16x16x32_bf16 v[126:129], v[130:133], v[194:197], v[126:129]
	v_mfma_f32_16x16x32_bf16 v[122:125], v[164:167], v[194:197], v[122:125]
	v_mfma_f32_16x16x32_bf16 v[106:109], v[164:167], v[202:205], v[106:109]
	v_mfma_f32_16x16x32_bf16 v[110:113], v[130:133], v[202:205], v[110:113]
	v_mfma_f32_16x16x32_bf16 v[94:97], v[130:133], v[210:213], v[94:97]
	v_mfma_f32_16x16x32_bf16 v[90:93], v[164:167], v[210:213], v[90:93]
	v_mfma_f32_16x16x32_bf16 v[74:77], v[164:167], v[218:221], v[74:77]
	v_mfma_f32_16x16x32_bf16 v[78:81], v[130:133], v[218:221], v[78:81]
	v_mfma_f32_16x16x32_bf16 v[126:129], v[134:137], v[198:201], v[126:129]
	v_mfma_f32_16x16x32_bf16 v[122:125], v[174:177], v[198:201], v[122:125]
	v_mfma_f32_16x16x32_bf16 v[106:109], v[174:177], v[206:209], v[106:109]
	v_mfma_f32_16x16x32_bf16 v[110:113], v[134:137], v[206:209], v[110:113]
	v_mfma_f32_16x16x32_bf16 v[94:97], v[134:137], v[214:217], v[94:97]
	v_mfma_f32_16x16x32_bf16 v[90:93], v[174:177], v[214:217], v[90:93]
	v_mfma_f32_16x16x32_bf16 v[74:77], v[174:177], v[222:225], v[74:77]
	v_mfma_f32_16x16x32_bf16 v[78:81], v[134:137], v[222:225], v[78:81]
	s_setprio 0
	s_setprio 1
	v_mfma_f32_16x16x32_bf16 v[118:121], v[178:181], v[194:197], v[118:121]
	v_mfma_f32_16x16x32_bf16 v[114:117], v[186:189], v[194:197], v[114:117]
	v_mfma_f32_16x16x32_bf16 v[98:101], v[186:189], v[202:205], v[98:101]
	v_mfma_f32_16x16x32_bf16 v[102:105], v[178:181], v[202:205], v[102:105]
	v_mfma_f32_16x16x32_bf16 v[86:89], v[178:181], v[210:213], v[86:89]
	v_mfma_f32_16x16x32_bf16 v[82:85], v[186:189], v[210:213], v[82:85]
	v_mfma_f32_16x16x32_bf16 v[66:69], v[186:189], v[218:221], v[66:69]
	v_mfma_f32_16x16x32_bf16 v[70:73], v[178:181], v[218:221], v[70:73]
	v_mfma_f32_16x16x32_bf16 v[118:121], v[182:185], v[198:201], v[118:121]
	v_mfma_f32_16x16x32_bf16 v[114:117], v[190:193], v[198:201], v[114:117]
	v_mfma_f32_16x16x32_bf16 v[98:101], v[190:193], v[206:209], v[98:101]
	v_mfma_f32_16x16x32_bf16 v[102:105], v[182:185], v[206:209], v[102:105]
	v_mfma_f32_16x16x32_bf16 v[86:89], v[182:185], v[214:217], v[86:89]
	v_mfma_f32_16x16x32_bf16 v[82:85], v[190:193], v[214:217], v[82:85]
	v_mfma_f32_16x16x32_bf16 v[66:69], v[190:193], v[222:225], v[66:69]
	v_mfma_f32_16x16x32_bf16 v[70:73], v[182:185], v[222:225], v[70:73]
	s_setprio 0
	s_barrier
	s_add_i32 s19, s75, s52
	v_lshl_add_u64 v[168:169], s[44:45], 0, v[140:141]
	s_mov_b32 m0, s19
	ds_read_b128 v[194:197], v172 offset:16384
	ds_read_b128 v[198:201], v172 offset:17408
	ds_read_b128 v[202:205], v172 offset:18432
	ds_read_b128 v[206:209], v172 offset:19456
	ds_read_b128 v[210:213], v172 offset:20480
	ds_read_b128 v[214:217], v172 offset:21504
	ds_read_b128 v[218:221], v172 offset:22528
	ds_read_b128 v[222:225], v172 offset:23552
	global_load_lds_dwordx4 v[168:169], off
	s_add_i32 m0, s19, 0x2000
	s_add_u32 s20, s44, 0x80000
	v_lshl_add_u64 v[226:227], s[44:45], 0, v[144:145]
	s_addc_u32 s21, s45, 0
	s_add_i32 s19, s76, s52
	global_load_lds_dwordx4 v[226:227], off
	v_lshl_add_u64 v[228:229], s[20:21], 0, v[140:141]
	s_mov_b32 m0, s19
	v_lshl_add_u64 v[230:231], s[46:47], 0, v[142:143]
	global_load_lds_dwordx4 v[228:229], off
	v_lshl_add_u64 v[228:229], s[20:21], 0, v[144:145]
	s_add_i32 m0, s19, 0x2000
	s_nop 0
	global_load_lds_dwordx4 v[228:229], off
	v_lshl_add_u64 v[228:229], s[46:47], 0, v[138:139]
	s_mov_b32 m0, s41
	s_nop 0
	global_load_lds_dwordx4 v[228:229], off
	s_mov_b32 m0, s53
	s_nop 0
	global_load_lds_dwordx4 v[230:231], off
	s_waitcnt vmcnt(8)
	s_waitcnt lgkmcnt(0)
	s_barrier
	s_setprio 1
	s_waitcnt lgkmcnt(0)
	v_mfma_f32_16x16x32_bf16 v[62:65], v[130:133], v[194:197], v[62:65]
	v_mfma_f32_16x16x32_bf16 v[58:61], v[164:167], v[194:197], v[58:61]
	v_mfma_f32_16x16x32_bf16 v[42:45], v[164:167], v[202:205], v[42:45]
	v_mfma_f32_16x16x32_bf16 v[46:49], v[130:133], v[202:205], v[46:49]
	v_mfma_f32_16x16x32_bf16 v[30:33], v[130:133], v[210:213], v[30:33]
	v_mfma_f32_16x16x32_bf16 v[26:29], v[164:167], v[210:213], v[26:29]
	v_mfma_f32_16x16x32_bf16 v[10:13], v[164:167], v[218:221], v[10:13]
	v_mfma_f32_16x16x32_bf16 v[14:17], v[130:133], v[218:221], v[14:17]
	v_mfma_f32_16x16x32_bf16 v[62:65], v[134:137], v[198:201], v[62:65]
	v_mfma_f32_16x16x32_bf16 v[58:61], v[174:177], v[198:201], v[58:61]
	v_mfma_f32_16x16x32_bf16 v[42:45], v[174:177], v[206:209], v[42:45]
	v_mfma_f32_16x16x32_bf16 v[46:49], v[134:137], v[206:209], v[46:49]
	v_mfma_f32_16x16x32_bf16 v[30:33], v[134:137], v[214:217], v[30:33]
	v_mfma_f32_16x16x32_bf16 v[26:29], v[174:177], v[214:217], v[26:29]
	v_mfma_f32_16x16x32_bf16 v[10:13], v[174:177], v[222:225], v[10:13]
	v_mfma_f32_16x16x32_bf16 v[14:17], v[134:137], v[222:225], v[14:17]
	s_setprio 0
	s_setprio 1
	v_mfma_f32_16x16x32_bf16 v[54:57], v[178:181], v[194:197], v[54:57]
	v_mfma_f32_16x16x32_bf16 v[50:53], v[186:189], v[194:197], v[50:53]
	v_mfma_f32_16x16x32_bf16 v[34:37], v[186:189], v[202:205], v[34:37]
	v_mfma_f32_16x16x32_bf16 v[38:41], v[178:181], v[202:205], v[38:41]
	v_mfma_f32_16x16x32_bf16 v[22:25], v[178:181], v[210:213], v[22:25]
	v_mfma_f32_16x16x32_bf16 v[18:21], v[186:189], v[210:213], v[18:21]
	v_mfma_f32_16x16x32_bf16 v[2:5], v[186:189], v[218:221], v[2:5]
	v_mfma_f32_16x16x32_bf16 v[6:9], v[178:181], v[218:221], v[6:9]
	v_mfma_f32_16x16x32_bf16 v[54:57], v[182:185], v[198:201], v[54:57]
	v_mfma_f32_16x16x32_bf16 v[50:53], v[190:193], v[198:201], v[50:53]
	v_mfma_f32_16x16x32_bf16 v[34:37], v[190:193], v[206:209], v[34:37]
	v_mfma_f32_16x16x32_bf16 v[38:41], v[182:185], v[206:209], v[38:41]
	v_mfma_f32_16x16x32_bf16 v[22:25], v[182:185], v[214:217], v[22:25]
	v_mfma_f32_16x16x32_bf16 v[18:21], v[190:193], v[214:217], v[18:21]
	v_mfma_f32_16x16x32_bf16 v[2:5], v[190:193], v[222:225], v[2:5]
	v_mfma_f32_16x16x32_bf16 v[6:9], v[182:185], v[222:225], v[6:9]
	s_setprio 0
	s_barrier
	s_add_i32 s19, 0, 0x18000
	v_add_u32_e32 v146, s19, v163
	s_add_i32 s31, 0, 0x1c000
	ds_read_b128 v[130:133], v146
	ds_read_b128 v[134:137], v146 offset:1024
	ds_read_b128 v[164:167], v146 offset:2048
	ds_read_b128 v[174:177], v146 offset:3072
	v_add_u32_e32 v146, s31, v163
	ds_read_b128 v[178:181], v146
	ds_read_b128 v[182:185], v146 offset:1024
	ds_read_b128 v[186:189], v146 offset:2048
	ds_read_b128 v[190:193], v146 offset:3072
	s_add_u32 s20, s46, 0x80000
	s_addc_u32 s21, s47, 0
	s_mov_b32 m0, s54
	v_lshl_add_u64 v[232:233], s[20:21], 0, v[138:139]
	ds_read_b128 v[194:197], v172 offset:32768
	ds_read_b128 v[198:201], v172 offset:33792
	ds_read_b128 v[202:205], v172 offset:34816
	ds_read_b128 v[206:209], v172 offset:35840
	ds_read_b128 v[210:213], v172 offset:36864
	ds_read_b128 v[214:217], v172 offset:37888
	ds_read_b128 v[218:221], v172 offset:38912
	ds_read_b128 v[222:225], v172 offset:39936
	global_load_lds_dwordx4 v[232:233], off
	v_lshl_add_u64 v[232:233], s[20:21], 0, v[142:143]
	s_mov_b32 m0, s55
	s_nop 0
	global_load_lds_dwordx4 v[232:233], off
	s_waitcnt vmcnt(8)
	s_waitcnt lgkmcnt(0)
	s_barrier
	s_setprio 1
	s_waitcnt lgkmcnt(0)
	v_mfma_f32_16x16x32_bf16 v[126:129], v[130:133], v[194:197], v[126:129]
	v_mfma_f32_16x16x32_bf16 v[122:125], v[164:167], v[194:197], v[122:125]
	v_mfma_f32_16x16x32_bf16 v[106:109], v[164:167], v[202:205], v[106:109]
	v_mfma_f32_16x16x32_bf16 v[110:113], v[130:133], v[202:205], v[110:113]
	v_mfma_f32_16x16x32_bf16 v[94:97], v[130:133], v[210:213], v[94:97]
	v_mfma_f32_16x16x32_bf16 v[90:93], v[164:167], v[210:213], v[90:93]
	v_mfma_f32_16x16x32_bf16 v[74:77], v[164:167], v[218:221], v[74:77]
	v_mfma_f32_16x16x32_bf16 v[78:81], v[130:133], v[218:221], v[78:81]
	v_mfma_f32_16x16x32_bf16 v[126:129], v[134:137], v[198:201], v[126:129]
	v_mfma_f32_16x16x32_bf16 v[122:125], v[174:177], v[198:201], v[122:125]
	v_mfma_f32_16x16x32_bf16 v[106:109], v[174:177], v[206:209], v[106:109]
	v_mfma_f32_16x16x32_bf16 v[110:113], v[134:137], v[206:209], v[110:113]
	v_mfma_f32_16x16x32_bf16 v[94:97], v[134:137], v[214:217], v[94:97]
	v_mfma_f32_16x16x32_bf16 v[90:93], v[174:177], v[214:217], v[90:93]
	v_mfma_f32_16x16x32_bf16 v[74:77], v[174:177], v[222:225], v[74:77]
	v_mfma_f32_16x16x32_bf16 v[78:81], v[134:137], v[222:225], v[78:81]
	s_setprio 0
	s_setprio 1
	v_mfma_f32_16x16x32_bf16 v[118:121], v[178:181], v[194:197], v[118:121]
	v_mfma_f32_16x16x32_bf16 v[114:117], v[186:189], v[194:197], v[114:117]
	v_mfma_f32_16x16x32_bf16 v[98:101], v[186:189], v[202:205], v[98:101]
	v_mfma_f32_16x16x32_bf16 v[102:105], v[178:181], v[202:205], v[102:105]
	v_mfma_f32_16x16x32_bf16 v[86:89], v[178:181], v[210:213], v[86:89]
	v_mfma_f32_16x16x32_bf16 v[82:85], v[186:189], v[210:213], v[82:85]
	v_mfma_f32_16x16x32_bf16 v[66:69], v[186:189], v[218:221], v[66:69]
	v_mfma_f32_16x16x32_bf16 v[70:73], v[178:181], v[218:221], v[70:73]
	v_mfma_f32_16x16x32_bf16 v[118:121], v[182:185], v[198:201], v[118:121]
	v_mfma_f32_16x16x32_bf16 v[114:117], v[190:193], v[198:201], v[114:117]
	v_mfma_f32_16x16x32_bf16 v[98:101], v[190:193], v[206:209], v[98:101]
	v_mfma_f32_16x16x32_bf16 v[102:105], v[182:185], v[206:209], v[102:105]
	v_mfma_f32_16x16x32_bf16 v[86:89], v[182:185], v[214:217], v[86:89]
	v_mfma_f32_16x16x32_bf16 v[82:85], v[190:193], v[214:217], v[82:85]
	v_mfma_f32_16x16x32_bf16 v[66:69], v[190:193], v[222:225], v[66:69]
	v_mfma_f32_16x16x32_bf16 v[70:73], v[182:185], v[222:225], v[70:73]
	s_setprio 0
	s_barrier
	s_add_i32 s19, s19, s52
	v_lshl_add_u64 v[168:169], v[168:169], 0, s[10:11]
	s_mov_b32 m0, s19
	ds_read_b128 v[194:197], v172 offset:49152
	ds_read_b128 v[198:201], v172 offset:50176
	ds_read_b128 v[202:205], v172 offset:51200
	ds_read_b128 v[206:209], v172 offset:52224
	ds_read_b128 v[210:213], v172 offset:53248
	ds_read_b128 v[214:217], v172 offset:54272
	ds_read_b128 v[218:221], v172 offset:55296
	ds_read_b128 v[222:225], v172 offset:56320
	global_load_lds_dwordx4 v[168:169], off
	s_add_i32 m0, s19, 0x2000
	s_add_u32 s20, s44, 0x80080
	v_lshl_add_u64 v[168:169], v[226:227], 0, s[10:11]
	s_addc_u32 s21, s45, 0
	s_add_i32 s19, s31, s52
	global_load_lds_dwordx4 v[168:169], off
	v_lshl_add_u64 v[168:169], s[20:21], 0, v[140:141]
	s_mov_b32 m0, s19
	s_nop 0
	global_load_lds_dwordx4 v[168:169], off
	v_lshl_add_u64 v[168:169], s[20:21], 0, v[144:145]
	s_add_i32 m0, s19, 0x2000
	s_nop 0
	global_load_lds_dwordx4 v[168:169], off
	v_lshl_add_u64 v[168:169], v[228:229], 0, s[10:11]
	s_mov_b32 m0, s67
	s_nop 0
	global_load_lds_dwordx4 v[168:169], off
	v_lshl_add_u64 v[168:169], v[230:231], 0, s[10:11]
	s_mov_b32 m0, s68
	s_nop 0
	global_load_lds_dwordx4 v[168:169], off
	s_waitcnt vmcnt(8)
	s_waitcnt lgkmcnt(0)
	s_barrier
	s_setprio 1
	s_waitcnt lgkmcnt(0)
	v_mfma_f32_16x16x32_bf16 v[62:65], v[130:133], v[194:197], v[62:65]
	v_mfma_f32_16x16x32_bf16 v[58:61], v[164:167], v[194:197], v[58:61]
	v_mfma_f32_16x16x32_bf16 v[42:45], v[164:167], v[202:205], v[42:45]
	v_mfma_f32_16x16x32_bf16 v[46:49], v[130:133], v[202:205], v[46:49]
	v_mfma_f32_16x16x32_bf16 v[30:33], v[130:133], v[210:213], v[30:33]
	v_mfma_f32_16x16x32_bf16 v[26:29], v[164:167], v[210:213], v[26:29]
	v_mfma_f32_16x16x32_bf16 v[10:13], v[164:167], v[218:221], v[10:13]
	v_mfma_f32_16x16x32_bf16 v[14:17], v[130:133], v[218:221], v[14:17]
	v_mfma_f32_16x16x32_bf16 v[62:65], v[134:137], v[198:201], v[62:65]
	v_mfma_f32_16x16x32_bf16 v[58:61], v[174:177], v[198:201], v[58:61]
	v_mfma_f32_16x16x32_bf16 v[42:45], v[174:177], v[206:209], v[42:45]
	v_mfma_f32_16x16x32_bf16 v[46:49], v[134:137], v[206:209], v[46:49]
	v_mfma_f32_16x16x32_bf16 v[30:33], v[134:137], v[214:217], v[30:33]
	v_mfma_f32_16x16x32_bf16 v[26:29], v[174:177], v[214:217], v[26:29]
	v_mfma_f32_16x16x32_bf16 v[10:13], v[174:177], v[222:225], v[10:13]
	v_mfma_f32_16x16x32_bf16 v[14:17], v[134:137], v[222:225], v[14:17]
	s_setprio 0
	s_setprio 1
	v_mfma_f32_16x16x32_bf16 v[54:57], v[178:181], v[194:197], v[54:57]
	v_mfma_f32_16x16x32_bf16 v[50:53], v[186:189], v[194:197], v[50:53]
	v_mfma_f32_16x16x32_bf16 v[34:37], v[186:189], v[202:205], v[34:37]
	v_mfma_f32_16x16x32_bf16 v[38:41], v[178:181], v[202:205], v[38:41]
	v_mfma_f32_16x16x32_bf16 v[22:25], v[178:181], v[210:213], v[22:25]
	v_mfma_f32_16x16x32_bf16 v[18:21], v[186:189], v[210:213], v[18:21]
	v_mfma_f32_16x16x32_bf16 v[2:5], v[186:189], v[218:221], v[2:5]
	v_mfma_f32_16x16x32_bf16 v[6:9], v[178:181], v[218:221], v[6:9]
	v_mfma_f32_16x16x32_bf16 v[54:57], v[182:185], v[198:201], v[54:57]
	v_mfma_f32_16x16x32_bf16 v[50:53], v[190:193], v[198:201], v[50:53]
	v_mfma_f32_16x16x32_bf16 v[34:37], v[190:193], v[206:209], v[34:37]
	v_mfma_f32_16x16x32_bf16 v[38:41], v[182:185], v[206:209], v[38:41]
	v_mfma_f32_16x16x32_bf16 v[22:25], v[182:185], v[214:217], v[22:25]
	v_mfma_f32_16x16x32_bf16 v[18:21], v[190:193], v[214:217], v[18:21]
	v_mfma_f32_16x16x32_bf16 v[2:5], v[190:193], v[222:225], v[2:5]
	v_mfma_f32_16x16x32_bf16 v[6:9], v[182:185], v[222:225], v[6:9]
	s_setprio 0
	s_barrier
	s_add_i32 s18, s18, 2
	s_add_u32 s42, s42, 0x100
	s_addc_u32 s43, s43, 0
	s_add_u32 s16, s16, 0x100
	s_addc_u32 s17, s17, 0
	s_cmp_gt_u32 s18, 29
	s_cbranch_scc0 .LBB0_466
	s_and_b64 vcc, exec, s[12:13]
	s_cbranch_vccz .LBB0_469
	s_barrier

.LBB0_699:
	ds_read_b128 v[134:137], v214
	ds_read_b128 v[138:141], v214 offset:1024
	ds_read_b128 v[142:145], v214 offset:2048
	ds_read_b128 v[178:181], v214 offset:3072
	ds_read_b128 v[182:185], v215
	ds_read_b128 v[186:189], v215 offset:1024
	ds_read_b128 v[190:193], v215 offset:2048
	ds_read_b128 v[194:197], v215 offset:3072
	s_add_u32 s40, s38, 0x100
	s_addc_u32 s41, s39, 0
	s_add_u32 s18, s15, s38
	s_addc_u32 s19, s16, s39
	s_cmp_eq_u32 s17, 60
	s_cselect_b32 s45, s3, s19
	s_cselect_b32 s19, 0, s40
	s_cselect_b32 s44, s14, s18
	s_cselect_b32 s18, 0, s41
	s_add_u32 s42, s10, s19
	s_addc_u32 s43, s11, s18
	s_mov_b32 m0, s66
	v_lshl_add_u64 v[244:245], v[130:131], 0, s[38:39]
	ds_read_b128 v[198:201], v216
	ds_read_b128 v[202:205], v216 offset:1024
	ds_read_b128 v[206:209], v216 offset:2048
	ds_read_b128 v[224:227], v216 offset:3072
	ds_read_b128 v[228:231], v216 offset:4096
	ds_read_b128 v[232:235], v216 offset:5120
	ds_read_b128 v[236:239], v216 offset:6144
	ds_read_b128 v[240:243], v216 offset:7168
	global_load_lds_dwordx4 v[244:245], off
	v_lshl_add_u64 v[244:245], v[132:133], 0, s[38:39]
	s_mov_b32 m0, s67
	s_nop 0
	global_load_lds_dwordx4 v[244:245], off
	s_waitcnt vmcnt(8)
	s_waitcnt lgkmcnt(0)
	s_barrier
	s_setprio 1
	s_waitcnt lgkmcnt(0)
	v_mfma_f32_16x16x32_bf16 v[82:85], v[134:137], v[198:201], v[82:85]
	v_mfma_f32_16x16x32_bf16 v[78:81], v[142:145], v[198:201], v[78:81]
	v_mfma_f32_16x16x32_bf16 v[106:109], v[142:145], v[206:209], v[106:109]
	v_mfma_f32_16x16x32_bf16 v[110:113], v[134:137], v[206:209], v[110:113]
	v_mfma_f32_16x16x32_bf16 v[118:121], v[134:137], v[228:231], v[118:121]
	v_mfma_f32_16x16x32_bf16 v[114:117], v[142:145], v[228:231], v[114:117]
	v_mfma_f32_16x16x32_bf16 v[122:125], v[142:145], v[236:239], v[122:125]
	v_mfma_f32_16x16x32_bf16 v[126:129], v[134:137], v[236:239], v[126:129]
	v_mfma_f32_16x16x32_bf16 v[82:85], v[138:141], v[202:205], v[82:85]
	v_mfma_f32_16x16x32_bf16 v[78:81], v[178:181], v[202:205], v[78:81]
	v_mfma_f32_16x16x32_bf16 v[106:109], v[178:181], v[224:227], v[106:109]
	v_mfma_f32_16x16x32_bf16 v[110:113], v[138:141], v[224:227], v[110:113]
	v_mfma_f32_16x16x32_bf16 v[118:121], v[138:141], v[232:235], v[118:121]
	v_mfma_f32_16x16x32_bf16 v[114:117], v[178:181], v[232:235], v[114:117]
	v_mfma_f32_16x16x32_bf16 v[122:125], v[178:181], v[240:243], v[122:125]
	v_mfma_f32_16x16x32_bf16 v[126:129], v[138:141], v[240:243], v[126:129]
	s_setprio 0
	s_setprio 1
	v_mfma_f32_16x16x32_bf16 v[22:25], v[182:185], v[198:201], v[22:25]
	v_mfma_f32_16x16x32_bf16 v[26:29], v[190:193], v[198:201], v[26:29]
	v_mfma_f32_16x16x32_bf16 v[46:49], v[190:193], v[206:209], v[46:49]
	v_mfma_f32_16x16x32_bf16 v[42:45], v[182:185], v[206:209], v[42:45]
	v_mfma_f32_16x16x32_bf16 v[62:65], v[182:185], v[228:231], v[62:65]
	v_mfma_f32_16x16x32_bf16 v[70:73], v[190:193], v[228:231], v[70:73]
	v_mfma_f32_16x16x32_bf16 v[94:97], v[190:193], v[236:239], v[94:97]
	v_mfma_f32_16x16x32_bf16 v[90:93], v[182:185], v[236:239], v[90:93]
	v_mfma_f32_16x16x32_bf16 v[22:25], v[186:189], v[202:205], v[22:25]
	v_mfma_f32_16x16x32_bf16 v[26:29], v[194:197], v[202:205], v[26:29]
	v_mfma_f32_16x16x32_bf16 v[46:49], v[194:197], v[224:227], v[46:49]
	v_mfma_f32_16x16x32_bf16 v[42:45], v[186:189], v[224:227], v[42:45]
	v_mfma_f32_16x16x32_bf16 v[62:65], v[186:189], v[232:235], v[62:65]
	v_mfma_f32_16x16x32_bf16 v[70:73], v[194:197], v[232:235], v[70:73]
	v_mfma_f32_16x16x32_bf16 v[94:97], v[194:197], v[240:243], v[94:97]
	v_mfma_f32_16x16x32_bf16 v[90:93], v[186:189], v[240:243], v[90:93]
	s_setprio 0
	s_barrier
	s_mov_b32 m0, s68
	v_lshl_add_u64 v[244:245], s[42:43], 0, v[150:151]
	s_add_u32 s18, s42, 0x100000
	ds_read_b128 v[198:201], v216 offset:16384
	ds_read_b128 v[202:205], v216 offset:17408
	ds_read_b128 v[206:209], v216 offset:18432
	ds_read_b128 v[224:227], v216 offset:19456
	ds_read_b128 v[228:231], v216 offset:20480
	ds_read_b128 v[232:235], v216 offset:21504
	ds_read_b128 v[236:239], v216 offset:22528
	ds_read_b128 v[240:243], v216 offset:23552
	global_load_lds_dwordx4 v[244:245], off
	v_lshl_add_u64 v[246:247], s[42:43], 0, v[146:147]
	s_mov_b32 m0, s69
	s_addc_u32 s19, s43, 0
	global_load_lds_dwordx4 v[246:247], off
	v_lshl_add_u64 v[248:249], s[18:19], 0, v[150:151]
	s_mov_b32 m0, s73
	v_lshl_add_u64 v[250:251], s[44:45], 0, v[148:149]
	global_load_lds_dwordx4 v[248:249], off
	v_lshl_add_u64 v[248:249], s[18:19], 0, v[146:147]
	s_mov_b32 m0, s74
	s_nop 0
	global_load_lds_dwordx4 v[248:249], off
	v_lshl_add_u64 v[248:249], s[44:45], 0, v[152:153]
	s_mov_b32 m0, s9
	s_nop 0
	global_load_lds_dwordx4 v[248:249], off
	s_mov_b32 m0, s55
	s_nop 0
	global_load_lds_dwordx4 v[250:251], off
	s_waitcnt vmcnt(8)
	s_waitcnt lgkmcnt(0)
	s_barrier
	s_setprio 1
	s_waitcnt lgkmcnt(0)
	v_mfma_f32_16x16x32_bf16 v[102:105], v[134:137], v[198:201], v[102:105]
	v_mfma_f32_16x16x32_bf16 v[98:101], v[142:145], v[198:201], v[98:101]
	v_mfma_f32_16x16x32_bf16 v[58:61], v[142:145], v[206:209], v[58:61]
	v_mfma_f32_16x16x32_bf16 v[66:69], v[134:137], v[206:209], v[66:69]
	v_mfma_f32_16x16x32_bf16 v[38:41], v[134:137], v[228:231], v[38:41]
	v_mfma_f32_16x16x32_bf16 v[34:37], v[142:145], v[228:231], v[34:37]
	v_mfma_f32_16x16x32_bf16 v[10:13], v[142:145], v[236:239], v[10:13]
	v_mfma_f32_16x16x32_bf16 v[14:17], v[134:137], v[236:239], v[14:17]
	v_mfma_f32_16x16x32_bf16 v[102:105], v[138:141], v[202:205], v[102:105]
	v_mfma_f32_16x16x32_bf16 v[98:101], v[178:181], v[202:205], v[98:101]
	v_mfma_f32_16x16x32_bf16 v[58:61], v[178:181], v[224:227], v[58:61]
	v_mfma_f32_16x16x32_bf16 v[66:69], v[138:141], v[224:227], v[66:69]
	v_mfma_f32_16x16x32_bf16 v[38:41], v[138:141], v[232:235], v[38:41]
	v_mfma_f32_16x16x32_bf16 v[34:37], v[178:181], v[232:235], v[34:37]
	v_mfma_f32_16x16x32_bf16 v[10:13], v[178:181], v[240:243], v[10:13]
	v_mfma_f32_16x16x32_bf16 v[14:17], v[138:141], v[240:243], v[14:17]
	s_setprio 0
	s_setprio 1
	v_mfma_f32_16x16x32_bf16 v[86:89], v[182:185], v[198:201], v[86:89]
	v_mfma_f32_16x16x32_bf16 v[74:77], v[190:193], v[198:201], v[74:77]
	v_mfma_f32_16x16x32_bf16 v[50:53], v[190:193], v[206:209], v[50:53]
	v_mfma_f32_16x16x32_bf16 v[54:57], v[182:185], v[206:209], v[54:57]
	v_mfma_f32_16x16x32_bf16 v[30:33], v[182:185], v[228:231], v[30:33]
	v_mfma_f32_16x16x32_bf16 v[18:21], v[190:193], v[228:231], v[18:21]
	v_mfma_f32_16x16x32_bf16 v[2:5], v[190:193], v[236:239], v[2:5]
	v_mfma_f32_16x16x32_bf16 v[6:9], v[182:185], v[236:239], v[6:9]
	v_mfma_f32_16x16x32_bf16 v[86:89], v[186:189], v[202:205], v[86:89]
	v_mfma_f32_16x16x32_bf16 v[74:77], v[194:197], v[202:205], v[74:77]
	v_mfma_f32_16x16x32_bf16 v[50:53], v[194:197], v[224:227], v[50:53]
	v_mfma_f32_16x16x32_bf16 v[54:57], v[186:189], v[224:227], v[54:57]
	v_mfma_f32_16x16x32_bf16 v[30:33], v[186:189], v[232:235], v[30:33]
	v_mfma_f32_16x16x32_bf16 v[18:21], v[194:197], v[232:235], v[18:21]
	v_mfma_f32_16x16x32_bf16 v[2:5], v[194:197], v[240:243], v[2:5]
	v_mfma_f32_16x16x32_bf16 v[6:9], v[186:189], v[240:243], v[6:9]
	s_setprio 0
	s_barrier
	s_add_i32 s20, 0, 0x1c000
	v_add_u32_e32 v194, s20, v212
	ds_read_b128 v[134:137], v220
	ds_read_b128 v[138:141], v220 offset:1024
	ds_read_b128 v[142:145], v220 offset:2048
	ds_read_b128 v[178:181], v220 offset:3072
	ds_read_b128 v[182:185], v194
	ds_read_b128 v[186:189], v194 offset:1024
	ds_read_b128 v[190:193], v194 offset:2048
	ds_read_b128 v[194:197], v194 offset:3072
	s_add_u32 s18, s44, 0x100000
	s_addc_u32 s19, s45, 0
	s_mov_b32 m0, s56
	v_lshl_add_u64 v[252:253], s[18:19], 0, v[152:153]
	ds_read_b128 v[198:201], v216 offset:32768
	ds_read_b128 v[202:205], v216 offset:33792
	ds_read_b128 v[206:209], v216 offset:34816
	ds_read_b128 v[224:227], v216 offset:35840
	ds_read_b128 v[228:231], v216 offset:36864
	ds_read_b128 v[232:235], v216 offset:37888
	ds_read_b128 v[236:239], v216 offset:38912
	ds_read_b128 v[240:243], v216 offset:39936
	global_load_lds_dwordx4 v[252:253], off
	v_lshl_add_u64 v[252:253], s[18:19], 0, v[148:149]
	s_mov_b32 m0, s57
	s_nop 0
	global_load_lds_dwordx4 v[252:253], off
	s_waitcnt vmcnt(8)
	s_waitcnt lgkmcnt(0)
	s_barrier
	s_setprio 1
	s_waitcnt lgkmcnt(0)
	v_mfma_f32_16x16x32_bf16 v[82:85], v[134:137], v[198:201], v[82:85]
	v_mfma_f32_16x16x32_bf16 v[78:81], v[142:145], v[198:201], v[78:81]
	v_mfma_f32_16x16x32_bf16 v[106:109], v[142:145], v[206:209], v[106:109]
	v_mfma_f32_16x16x32_bf16 v[110:113], v[134:137], v[206:209], v[110:113]
	v_mfma_f32_16x16x32_bf16 v[118:121], v[134:137], v[228:231], v[118:121]
	v_mfma_f32_16x16x32_bf16 v[114:117], v[142:145], v[228:231], v[114:117]
	v_mfma_f32_16x16x32_bf16 v[122:125], v[142:145], v[236:239], v[122:125]
	v_mfma_f32_16x16x32_bf16 v[126:129], v[134:137], v[236:239], v[126:129]
	v_mfma_f32_16x16x32_bf16 v[82:85], v[138:141], v[202:205], v[82:85]
	v_mfma_f32_16x16x32_bf16 v[78:81], v[178:181], v[202:205], v[78:81]
	v_mfma_f32_16x16x32_bf16 v[106:109], v[178:181], v[224:227], v[106:109]
	v_mfma_f32_16x16x32_bf16 v[110:113], v[138:141], v[224:227], v[110:113]
	v_mfma_f32_16x16x32_bf16 v[118:121], v[138:141], v[232:235], v[118:121]
	v_mfma_f32_16x16x32_bf16 v[114:117], v[178:181], v[232:235], v[114:117]
	v_mfma_f32_16x16x32_bf16 v[122:125], v[178:181], v[240:243], v[122:125]
	v_mfma_f32_16x16x32_bf16 v[126:129], v[138:141], v[240:243], v[126:129]
	s_setprio 0
	s_setprio 1
	v_mfma_f32_16x16x32_bf16 v[22:25], v[182:185], v[198:201], v[22:25]
	v_mfma_f32_16x16x32_bf16 v[26:29], v[190:193], v[198:201], v[26:29]
	v_mfma_f32_16x16x32_bf16 v[46:49], v[190:193], v[206:209], v[46:49]
	v_mfma_f32_16x16x32_bf16 v[42:45], v[182:185], v[206:209], v[42:45]
	v_mfma_f32_16x16x32_bf16 v[62:65], v[182:185], v[228:231], v[62:65]
	v_mfma_f32_16x16x32_bf16 v[70:73], v[190:193], v[228:231], v[70:73]
	v_mfma_f32_16x16x32_bf16 v[94:97], v[190:193], v[236:239], v[94:97]
	v_mfma_f32_16x16x32_bf16 v[90:93], v[182:185], v[236:239], v[90:93]
	v_mfma_f32_16x16x32_bf16 v[22:25], v[186:189], v[202:205], v[22:25]
	v_mfma_f32_16x16x32_bf16 v[26:29], v[194:197], v[202:205], v[26:29]
	v_mfma_f32_16x16x32_bf16 v[46:49], v[194:197], v[224:227], v[46:49]
	v_mfma_f32_16x16x32_bf16 v[42:45], v[186:189], v[224:227], v[42:45]
	v_mfma_f32_16x16x32_bf16 v[62:65], v[186:189], v[232:235], v[62:65]
	v_mfma_f32_16x16x32_bf16 v[70:73], v[194:197], v[232:235], v[70:73]
	v_mfma_f32_16x16x32_bf16 v[94:97], v[194:197], v[240:243], v[94:97]
	v_mfma_f32_16x16x32_bf16 v[90:93], v[186:189], v[240:243], v[90:93]
	s_setprio 0
	s_barrier
	s_add_i32 s18, s75, s54
	v_lshl_add_u64 v[244:245], v[244:245], 0, s[26:27]
	s_mov_b32 m0, s18
	ds_read_b128 v[198:201], v216 offset:49152
	ds_read_b128 v[202:205], v216 offset:50176
	ds_read_b128 v[206:209], v216 offset:51200
	ds_read_b128 v[224:227], v216 offset:52224
	ds_read_b128 v[228:231], v216 offset:53248
	ds_read_b128 v[232:235], v216 offset:54272
	ds_read_b128 v[236:239], v216 offset:55296
	ds_read_b128 v[240:243], v216 offset:56320
	global_load_lds_dwordx4 v[244:245], off
	s_add_i32 m0, s18, 0x2000
	s_add_u32 s18, s42, 0x100080
	v_lshl_add_u64 v[244:245], v[246:247], 0, s[26:27]
	s_addc_u32 s19, s43, 0
	s_add_i32 s20, s20, s54
	global_load_lds_dwordx4 v[244:245], off
	v_lshl_add_u64 v[244:245], s[18:19], 0, v[150:151]
	s_mov_b32 m0, s20
	s_nop 0
	global_load_lds_dwordx4 v[244:245], off
	v_lshl_add_u64 v[244:245], s[18:19], 0, v[146:147]
	s_add_i32 m0, s20, 0x2000
	s_nop 0
	global_load_lds_dwordx4 v[244:245], off
	v_lshl_add_u64 v[244:245], v[248:249], 0, s[26:27]
	s_mov_b32 m0, s63
	s_nop 0
	global_load_lds_dwordx4 v[244:245], off
	v_lshl_add_u64 v[244:245], v[250:251], 0, s[26:27]
	s_mov_b32 m0, s64
	s_nop 0
	global_load_lds_dwordx4 v[244:245], off
	s_waitcnt vmcnt(8)
	s_waitcnt lgkmcnt(0)
	s_barrier
	s_setprio 1
	s_waitcnt lgkmcnt(0)
	v_mfma_f32_16x16x32_bf16 v[102:105], v[134:137], v[198:201], v[102:105]
	v_mfma_f32_16x16x32_bf16 v[98:101], v[142:145], v[198:201], v[98:101]
	v_mfma_f32_16x16x32_bf16 v[58:61], v[142:145], v[206:209], v[58:61]
	v_mfma_f32_16x16x32_bf16 v[66:69], v[134:137], v[206:209], v[66:69]
	v_mfma_f32_16x16x32_bf16 v[38:41], v[134:137], v[228:231], v[38:41]
	v_mfma_f32_16x16x32_bf16 v[34:37], v[142:145], v[228:231], v[34:37]
	v_mfma_f32_16x16x32_bf16 v[10:13], v[142:145], v[236:239], v[10:13]
	v_mfma_f32_16x16x32_bf16 v[14:17], v[134:137], v[236:239], v[14:17]
	v_mfma_f32_16x16x32_bf16 v[102:105], v[138:141], v[202:205], v[102:105]
	v_mfma_f32_16x16x32_bf16 v[98:101], v[178:181], v[202:205], v[98:101]
	v_mfma_f32_16x16x32_bf16 v[58:61], v[178:181], v[224:227], v[58:61]
	v_mfma_f32_16x16x32_bf16 v[66:69], v[138:141], v[224:227], v[66:69]
	v_mfma_f32_16x16x32_bf16 v[38:41], v[138:141], v[232:235], v[38:41]
	v_mfma_f32_16x16x32_bf16 v[34:37], v[178:181], v[232:235], v[34:37]
	v_mfma_f32_16x16x32_bf16 v[10:13], v[178:181], v[240:243], v[10:13]
	v_mfma_f32_16x16x32_bf16 v[14:17], v[138:141], v[240:243], v[14:17]
	s_setprio 0
	s_setprio 1
	v_mfma_f32_16x16x32_bf16 v[86:89], v[182:185], v[198:201], v[86:89]
	v_mfma_f32_16x16x32_bf16 v[74:77], v[190:193], v[198:201], v[74:77]
	v_mfma_f32_16x16x32_bf16 v[50:53], v[190:193], v[206:209], v[50:53]
	v_mfma_f32_16x16x32_bf16 v[54:57], v[182:185], v[206:209], v[54:57]
	v_mfma_f32_16x16x32_bf16 v[30:33], v[182:185], v[228:231], v[30:33]
	v_mfma_f32_16x16x32_bf16 v[18:21], v[190:193], v[228:231], v[18:21]
	v_mfma_f32_16x16x32_bf16 v[2:5], v[190:193], v[236:239], v[2:5]
	v_mfma_f32_16x16x32_bf16 v[6:9], v[182:185], v[236:239], v[6:9]
	v_mfma_f32_16x16x32_bf16 v[86:89], v[186:189], v[202:205], v[86:89]
	v_mfma_f32_16x16x32_bf16 v[74:77], v[194:197], v[202:205], v[74:77]
	v_mfma_f32_16x16x32_bf16 v[50:53], v[194:197], v[224:227], v[50:53]
	v_mfma_f32_16x16x32_bf16 v[54:57], v[186:189], v[224:227], v[54:57]
	v_mfma_f32_16x16x32_bf16 v[30:33], v[186:189], v[232:235], v[30:33]
	v_mfma_f32_16x16x32_bf16 v[18:21], v[194:197], v[232:235], v[18:21]
	v_mfma_f32_16x16x32_bf16 v[2:5], v[194:197], v[240:243], v[2:5]
	v_mfma_f32_16x16x32_bf16 v[6:9], v[186:189], v[240:243], v[6:9]
	s_setprio 0
	s_barrier
	s_add_i32 s17, s17, 2
	s_cmp_gt_u32 s17, 61
	s_mov_b64 s[38:39], s[40:41]
	s_cbranch_scc0 .LBB0_699
	s_and_b64 vcc, exec, s[28:29]
	s_cbranch_vccz .LBB0_702
	s_barrier

.LBB0_877:
	ds_read_b128 v[130:133], v220
	ds_read_b128 v[134:137], v220 offset:1024
	ds_read_b128 v[138:141], v220 offset:2048
	ds_read_b128 v[142:145], v220 offset:3072
	ds_read_b128 v[184:187], v224
	ds_read_b128 v[188:191], v224 offset:1024
	ds_read_b128 v[192:195], v224 offset:2048
	ds_read_b128 v[196:199], v224 offset:3072
	s_add_u32 s14, s36, 0xffea0080
	s_addc_u32 s15, s37, -1
	s_cmpk_eq_i32 s3, 0x54
	s_cselect_b32 s43, s29, s15
	s_cselect_b32 s42, s28, s14
	s_cselect_b32 s41, s9, s39
	s_cselect_b32 s40, s8, s38
	s_mov_b32 m0, s50
	v_lshl_add_u64 v[244:245], s[36:37], 0, v[178:179]
	ds_read_b128 v[200:203], v221
	ds_read_b128 v[204:207], v221 offset:1024
	ds_read_b128 v[208:211], v221 offset:2048
	ds_read_b128 v[212:215], v221 offset:3072
	ds_read_b128 v[228:231], v221 offset:4096
	ds_read_b128 v[232:235], v221 offset:5120
	ds_read_b128 v[236:239], v221 offset:6144
	ds_read_b128 v[240:243], v221 offset:7168
	global_load_lds_dwordx4 v[244:245], off
	v_lshl_add_u64 v[244:245], s[36:37], 0, v[180:181]
	s_mov_b32 m0, s51
	s_nop 0
	global_load_lds_dwordx4 v[244:245], off
	s_waitcnt vmcnt(8)
	s_waitcnt lgkmcnt(0)
	s_barrier
	s_setprio 1
	s_waitcnt lgkmcnt(0)
	v_mfma_f32_16x16x32_bf16 v[30:33], v[130:133], v[200:203], v[30:33]
	v_mfma_f32_16x16x32_bf16 v[26:29], v[138:141], v[200:203], v[26:29]
	v_mfma_f32_16x16x32_bf16 v[42:45], v[138:141], v[208:211], v[42:45]
	v_mfma_f32_16x16x32_bf16 v[46:49], v[130:133], v[208:211], v[46:49]
	v_mfma_f32_16x16x32_bf16 v[62:65], v[130:133], v[228:231], v[62:65]
	v_mfma_f32_16x16x32_bf16 v[58:61], v[138:141], v[228:231], v[58:61]
	v_mfma_f32_16x16x32_bf16 v[90:93], v[138:141], v[236:239], v[90:93]
	v_mfma_f32_16x16x32_bf16 v[94:97], v[130:133], v[236:239], v[94:97]
	v_mfma_f32_16x16x32_bf16 v[30:33], v[134:137], v[204:207], v[30:33]
	v_mfma_f32_16x16x32_bf16 v[26:29], v[142:145], v[204:207], v[26:29]
	v_mfma_f32_16x16x32_bf16 v[42:45], v[142:145], v[212:215], v[42:45]
	v_mfma_f32_16x16x32_bf16 v[46:49], v[134:137], v[212:215], v[46:49]
	v_mfma_f32_16x16x32_bf16 v[62:65], v[134:137], v[232:235], v[62:65]
	v_mfma_f32_16x16x32_bf16 v[58:61], v[142:145], v[232:235], v[58:61]
	v_mfma_f32_16x16x32_bf16 v[90:93], v[142:145], v[240:243], v[90:93]
	v_mfma_f32_16x16x32_bf16 v[94:97], v[134:137], v[240:243], v[94:97]
	s_setprio 0
	s_setprio 1
	v_mfma_f32_16x16x32_bf16 v[2:5], v[184:187], v[200:203], v[2:5]
	v_mfma_f32_16x16x32_bf16 v[6:9], v[192:195], v[200:203], v[6:9]
	v_mfma_f32_16x16x32_bf16 v[14:17], v[192:195], v[208:211], v[14:17]
	v_mfma_f32_16x16x32_bf16 v[10:13], v[184:187], v[208:211], v[10:13]
	v_mfma_f32_16x16x32_bf16 v[18:21], v[184:187], v[228:231], v[18:21]
	v_mfma_f32_16x16x32_bf16 v[22:25], v[192:195], v[228:231], v[22:25]
	v_mfma_f32_16x16x32_bf16 v[38:41], v[192:195], v[236:239], v[38:41]
	v_mfma_f32_16x16x32_bf16 v[34:37], v[184:187], v[236:239], v[34:37]
	v_mfma_f32_16x16x32_bf16 v[2:5], v[188:191], v[204:207], v[2:5]
	v_mfma_f32_16x16x32_bf16 v[6:9], v[196:199], v[204:207], v[6:9]
	v_mfma_f32_16x16x32_bf16 v[14:17], v[196:199], v[212:215], v[14:17]
	v_mfma_f32_16x16x32_bf16 v[10:13], v[188:191], v[212:215], v[10:13]
	v_mfma_f32_16x16x32_bf16 v[18:21], v[188:191], v[232:235], v[18:21]
	v_mfma_f32_16x16x32_bf16 v[22:25], v[196:199], v[232:235], v[22:25]
	v_mfma_f32_16x16x32_bf16 v[38:41], v[196:199], v[240:243], v[38:41]
	v_mfma_f32_16x16x32_bf16 v[34:37], v[188:191], v[240:243], v[34:37]
	s_setprio 0
	s_barrier
	s_mov_b32 m0, s52
	v_lshl_add_u64 v[244:245], s[40:41], 0, v[150:151]
	s_add_u32 s14, s40, 0x160000
	ds_read_b128 v[200:203], v221 offset:16384
	ds_read_b128 v[204:207], v221 offset:17408
	ds_read_b128 v[208:211], v221 offset:18432
	ds_read_b128 v[212:215], v221 offset:19456
	ds_read_b128 v[228:231], v221 offset:20480
	ds_read_b128 v[232:235], v221 offset:21504
	ds_read_b128 v[236:239], v221 offset:22528
	ds_read_b128 v[240:243], v221 offset:23552
	global_load_lds_dwordx4 v[244:245], off
	v_lshl_add_u64 v[246:247], s[40:41], 0, v[146:147]
	s_mov_b32 m0, s53
	s_addc_u32 s15, s41, 0
	global_load_lds_dwordx4 v[246:247], off
	v_lshl_add_u64 v[248:249], s[14:15], 0, v[150:151]
	s_mov_b32 m0, s54
	v_lshl_add_u64 v[250:251], s[42:43], 0, v[148:149]
	global_load_lds_dwordx4 v[248:249], off
	v_lshl_add_u64 v[248:249], s[14:15], 0, v[146:147]
	s_mov_b32 m0, s55
	s_nop 0
	global_load_lds_dwordx4 v[248:249], off
	v_lshl_add_u64 v[248:249], s[42:43], 0, v[152:153]
	s_mov_b32 m0, s61
	s_nop 0
	global_load_lds_dwordx4 v[248:249], off
	s_mov_b32 m0, s62
	s_nop 0
	global_load_lds_dwordx4 v[250:251], off
	s_waitcnt vmcnt(8)
	s_waitcnt lgkmcnt(0)
	s_barrier
	s_setprio 1
	s_waitcnt lgkmcnt(0)
	v_mfma_f32_16x16x32_bf16 v[114:117], v[130:133], v[200:203], v[114:117]
	v_mfma_f32_16x16x32_bf16 v[110:113], v[138:141], v[200:203], v[110:113]
	v_mfma_f32_16x16x32_bf16 v[122:125], v[138:141], v[208:211], v[122:125]
	v_mfma_f32_16x16x32_bf16 v[126:129], v[130:133], v[208:211], v[126:129]
	v_mfma_f32_16x16x32_bf16 v[118:121], v[130:133], v[228:231], v[118:121]
	v_mfma_f32_16x16x32_bf16 v[106:109], v[138:141], v[228:231], v[106:109]
	v_mfma_f32_16x16x32_bf16 v[74:77], v[138:141], v[236:239], v[74:77]
	v_mfma_f32_16x16x32_bf16 v[78:81], v[130:133], v[236:239], v[78:81]
	v_mfma_f32_16x16x32_bf16 v[114:117], v[134:137], v[204:207], v[114:117]
	v_mfma_f32_16x16x32_bf16 v[110:113], v[142:145], v[204:207], v[110:113]
	v_mfma_f32_16x16x32_bf16 v[122:125], v[142:145], v[212:215], v[122:125]
	v_mfma_f32_16x16x32_bf16 v[126:129], v[134:137], v[212:215], v[126:129]
	v_mfma_f32_16x16x32_bf16 v[118:121], v[134:137], v[232:235], v[118:121]
	v_mfma_f32_16x16x32_bf16 v[106:109], v[142:145], v[232:235], v[106:109]
	v_mfma_f32_16x16x32_bf16 v[74:77], v[142:145], v[240:243], v[74:77]
	v_mfma_f32_16x16x32_bf16 v[78:81], v[134:137], v[240:243], v[78:81]
	s_setprio 0
	s_setprio 1
	v_mfma_f32_16x16x32_bf16 v[50:53], v[184:187], v[200:203], v[50:53]
	v_mfma_f32_16x16x32_bf16 v[54:57], v[192:195], v[200:203], v[54:57]
	v_mfma_f32_16x16x32_bf16 v[86:89], v[192:195], v[208:211], v[86:89]
	v_mfma_f32_16x16x32_bf16 v[82:85], v[184:187], v[208:211], v[82:85]
	v_mfma_f32_16x16x32_bf16 v[102:105], v[184:187], v[228:231], v[102:105]
	v_mfma_f32_16x16x32_bf16 v[98:101], v[192:195], v[228:231], v[98:101]
	v_mfma_f32_16x16x32_bf16 v[66:69], v[192:195], v[236:239], v[66:69]
	v_mfma_f32_16x16x32_bf16 v[70:73], v[184:187], v[236:239], v[70:73]
	v_mfma_f32_16x16x32_bf16 v[50:53], v[188:191], v[204:207], v[50:53]
	v_mfma_f32_16x16x32_bf16 v[54:57], v[196:199], v[204:207], v[54:57]
	v_mfma_f32_16x16x32_bf16 v[86:89], v[196:199], v[212:215], v[86:89]
	v_mfma_f32_16x16x32_bf16 v[82:85], v[188:191], v[212:215], v[82:85]
	v_mfma_f32_16x16x32_bf16 v[102:105], v[188:191], v[232:235], v[102:105]
	v_mfma_f32_16x16x32_bf16 v[98:101], v[196:199], v[232:235], v[98:101]
	v_mfma_f32_16x16x32_bf16 v[66:69], v[196:199], v[240:243], v[66:69]
	v_mfma_f32_16x16x32_bf16 v[70:73], v[188:191], v[240:243], v[70:73]
	s_setprio 0
	s_barrier
	v_add_u32_e32 v196, s74, v218
	ds_read_b128 v[130:133], v225
	ds_read_b128 v[134:137], v225 offset:1024
	ds_read_b128 v[138:141], v225 offset:2048
	ds_read_b128 v[142:145], v225 offset:3072
	ds_read_b128 v[184:187], v196
	ds_read_b128 v[188:191], v196 offset:1024
	ds_read_b128 v[192:195], v196 offset:2048
	ds_read_b128 v[196:199], v196 offset:3072
	s_add_u32 s14, s42, 0x160000
	s_addc_u32 s15, s43, 0
	s_mov_b32 m0, s63
	v_lshl_add_u64 v[252:253], s[14:15], 0, v[152:153]
	ds_read_b128 v[200:203], v221 offset:32768
	ds_read_b128 v[204:207], v221 offset:33792
	ds_read_b128 v[208:211], v221 offset:34816
	ds_read_b128 v[212:215], v221 offset:35840
	ds_read_b128 v[228:231], v221 offset:36864
	ds_read_b128 v[232:235], v221 offset:37888
	ds_read_b128 v[236:239], v221 offset:38912
	ds_read_b128 v[240:243], v221 offset:39936
	global_load_lds_dwordx4 v[252:253], off
	v_lshl_add_u64 v[252:253], s[14:15], 0, v[148:149]
	s_mov_b32 m0, s64
	s_nop 0
	global_load_lds_dwordx4 v[252:253], off
	s_waitcnt vmcnt(8)
	s_waitcnt lgkmcnt(0)
	s_barrier
	s_setprio 1
	s_waitcnt lgkmcnt(0)
	v_mfma_f32_16x16x32_bf16 v[30:33], v[130:133], v[200:203], v[30:33]
	v_mfma_f32_16x16x32_bf16 v[26:29], v[138:141], v[200:203], v[26:29]
	v_mfma_f32_16x16x32_bf16 v[42:45], v[138:141], v[208:211], v[42:45]
	v_mfma_f32_16x16x32_bf16 v[46:49], v[130:133], v[208:211], v[46:49]
	v_mfma_f32_16x16x32_bf16 v[62:65], v[130:133], v[228:231], v[62:65]
	v_mfma_f32_16x16x32_bf16 v[58:61], v[138:141], v[228:231], v[58:61]
	v_mfma_f32_16x16x32_bf16 v[90:93], v[138:141], v[236:239], v[90:93]
	v_mfma_f32_16x16x32_bf16 v[94:97], v[130:133], v[236:239], v[94:97]
	v_mfma_f32_16x16x32_bf16 v[30:33], v[134:137], v[204:207], v[30:33]
	v_mfma_f32_16x16x32_bf16 v[26:29], v[142:145], v[204:207], v[26:29]
	v_mfma_f32_16x16x32_bf16 v[42:45], v[142:145], v[212:215], v[42:45]
	v_mfma_f32_16x16x32_bf16 v[46:49], v[134:137], v[212:215], v[46:49]
	v_mfma_f32_16x16x32_bf16 v[62:65], v[134:137], v[232:235], v[62:65]
	v_mfma_f32_16x16x32_bf16 v[58:61], v[142:145], v[232:235], v[58:61]
	v_mfma_f32_16x16x32_bf16 v[90:93], v[142:145], v[240:243], v[90:93]
	v_mfma_f32_16x16x32_bf16 v[94:97], v[134:137], v[240:243], v[94:97]
	s_setprio 0
	s_setprio 1
	v_mfma_f32_16x16x32_bf16 v[2:5], v[184:187], v[200:203], v[2:5]
	v_mfma_f32_16x16x32_bf16 v[6:9], v[192:195], v[200:203], v[6:9]
	v_mfma_f32_16x16x32_bf16 v[14:17], v[192:195], v[208:211], v[14:17]
	v_mfma_f32_16x16x32_bf16 v[10:13], v[184:187], v[208:211], v[10:13]
	v_mfma_f32_16x16x32_bf16 v[18:21], v[184:187], v[228:231], v[18:21]
	v_mfma_f32_16x16x32_bf16 v[22:25], v[192:195], v[228:231], v[22:25]
	v_mfma_f32_16x16x32_bf16 v[38:41], v[192:195], v[236:239], v[38:41]
	v_mfma_f32_16x16x32_bf16 v[34:37], v[184:187], v[236:239], v[34:37]
	v_mfma_f32_16x16x32_bf16 v[2:5], v[188:191], v[204:207], v[2:5]
	v_mfma_f32_16x16x32_bf16 v[6:9], v[196:199], v[204:207], v[6:9]
	v_mfma_f32_16x16x32_bf16 v[14:17], v[196:199], v[212:215], v[14:17]
	v_mfma_f32_16x16x32_bf16 v[10:13], v[188:191], v[212:215], v[10:13]
	v_mfma_f32_16x16x32_bf16 v[18:21], v[188:191], v[232:235], v[18:21]
	v_mfma_f32_16x16x32_bf16 v[22:25], v[196:199], v[232:235], v[22:25]
	v_mfma_f32_16x16x32_bf16 v[38:41], v[196:199], v[240:243], v[38:41]
	v_mfma_f32_16x16x32_bf16 v[34:37], v[188:191], v[240:243], v[34:37]
	s_setprio 0
	s_barrier
	s_mov_b32 m0, s75
	v_lshl_add_u64 v[244:245], v[244:245], 0, s[22:23]
	s_add_u32 s14, s40, 0x160080
	ds_read_b128 v[200:203], v221 offset:49152
	ds_read_b128 v[204:207], v221 offset:50176
	ds_read_b128 v[208:211], v221 offset:51200
	ds_read_b128 v[212:215], v221 offset:52224
	ds_read_b128 v[228:231], v221 offset:53248
	ds_read_b128 v[232:235], v221 offset:54272
	ds_read_b128 v[236:239], v221 offset:55296
	ds_read_b128 v[240:243], v221 offset:56320
	global_load_lds_dwordx4 v[244:245], off
	v_lshl_add_u64 v[244:245], v[246:247], 0, s[22:23]
	s_mov_b32 m0, s76
	s_addc_u32 s15, s41, 0
	global_load_lds_dwordx4 v[244:245], off
	v_lshl_add_u64 v[244:245], s[14:15], 0, v[150:151]
	s_mov_b32 m0, s77
	s_nop 0
	global_load_lds_dwordx4 v[244:245], off
	v_lshl_add_u64 v[244:245], s[14:15], 0, v[146:147]
	s_mov_b32 m0, s78
	s_nop 0
	global_load_lds_dwordx4 v[244:245], off
	v_lshl_add_u64 v[244:245], v[248:249], 0, s[22:23]
	s_mov_b32 m0, s68
	s_nop 0
	global_load_lds_dwordx4 v[244:245], off
	v_lshl_add_u64 v[244:245], v[250:251], 0, s[22:23]
	s_mov_b32 m0, s69
	s_nop 0
	global_load_lds_dwordx4 v[244:245], off
	s_waitcnt vmcnt(8)
	s_waitcnt lgkmcnt(0)
	s_barrier
	s_setprio 1
	s_waitcnt lgkmcnt(0)
	v_mfma_f32_16x16x32_bf16 v[114:117], v[130:133], v[200:203], v[114:117]
	v_mfma_f32_16x16x32_bf16 v[110:113], v[138:141], v[200:203], v[110:113]
	v_mfma_f32_16x16x32_bf16 v[122:125], v[138:141], v[208:211], v[122:125]
	v_mfma_f32_16x16x32_bf16 v[126:129], v[130:133], v[208:211], v[126:129]
	v_mfma_f32_16x16x32_bf16 v[118:121], v[130:133], v[228:231], v[118:121]
	v_mfma_f32_16x16x32_bf16 v[106:109], v[138:141], v[228:231], v[106:109]
	v_mfma_f32_16x16x32_bf16 v[74:77], v[138:141], v[236:239], v[74:77]
	v_mfma_f32_16x16x32_bf16 v[78:81], v[130:133], v[236:239], v[78:81]
	v_mfma_f32_16x16x32_bf16 v[114:117], v[134:137], v[204:207], v[114:117]
	v_mfma_f32_16x16x32_bf16 v[110:113], v[142:145], v[204:207], v[110:113]
	v_mfma_f32_16x16x32_bf16 v[122:125], v[142:145], v[212:215], v[122:125]
	v_mfma_f32_16x16x32_bf16 v[126:129], v[134:137], v[212:215], v[126:129]
	v_mfma_f32_16x16x32_bf16 v[118:121], v[134:137], v[232:235], v[118:121]
	v_mfma_f32_16x16x32_bf16 v[106:109], v[142:145], v[232:235], v[106:109]
	v_mfma_f32_16x16x32_bf16 v[74:77], v[142:145], v[240:243], v[74:77]
	v_mfma_f32_16x16x32_bf16 v[78:81], v[134:137], v[240:243], v[78:81]
	s_setprio 0
	s_setprio 1
	v_mfma_f32_16x16x32_bf16 v[50:53], v[184:187], v[200:203], v[50:53]
	v_mfma_f32_16x16x32_bf16 v[54:57], v[192:195], v[200:203], v[54:57]
	v_mfma_f32_16x16x32_bf16 v[86:89], v[192:195], v[208:211], v[86:89]
	v_mfma_f32_16x16x32_bf16 v[82:85], v[184:187], v[208:211], v[82:85]
	v_mfma_f32_16x16x32_bf16 v[102:105], v[184:187], v[228:231], v[102:105]
	v_mfma_f32_16x16x32_bf16 v[98:101], v[192:195], v[228:231], v[98:101]
	v_mfma_f32_16x16x32_bf16 v[66:69], v[192:195], v[236:239], v[66:69]
	v_mfma_f32_16x16x32_bf16 v[70:73], v[184:187], v[236:239], v[70:73]
	v_mfma_f32_16x16x32_bf16 v[50:53], v[188:191], v[204:207], v[50:53]
	v_mfma_f32_16x16x32_bf16 v[54:57], v[196:199], v[204:207], v[54:57]
	v_mfma_f32_16x16x32_bf16 v[86:89], v[196:199], v[212:215], v[86:89]
	v_mfma_f32_16x16x32_bf16 v[82:85], v[188:191], v[212:215], v[82:85]
	v_mfma_f32_16x16x32_bf16 v[102:105], v[188:191], v[232:235], v[102:105]
	v_mfma_f32_16x16x32_bf16 v[98:101], v[196:199], v[232:235], v[98:101]
	v_mfma_f32_16x16x32_bf16 v[66:69], v[196:199], v[240:243], v[66:69]
	v_mfma_f32_16x16x32_bf16 v[70:73], v[188:191], v[240:243], v[70:73]
	s_setprio 0
	s_barrier
	s_add_i32 s3, s3, 2
	s_add_u32 s36, s36, 0x100
	s_addc_u32 s37, s37, 0
	s_add_u32 s38, s38, 0x100
	s_addc_u32 s39, s39, 0
	s_cmpk_gt_u32 s3, 0x55
	s_cbranch_scc0 .LBB0_877
	s_and_b64 vcc, exec, s[24:25]
	s_cbranch_vccz .LBB0_880
	s_barrier

.LBB0_986:
	ds_read_b128 v[130:133], v172
	ds_read_b128 v[134:137], v172 offset:1024
	ds_read_b128 v[138:141], v172 offset:2048
	ds_read_b128 v[142:145], v172 offset:3072
	ds_read_b128 v[166:169], v173
	ds_read_b128 v[176:179], v173 offset:1024
	ds_read_b128 v[180:183], v173 offset:2048
	ds_read_b128 v[184:187], v173 offset:3072
	s_add_u32 s20, s52, 0xfff80080
	s_addc_u32 s21, s53, -1
	s_cmp_eq_u32 s19, 28
	s_cselect_b32 s57, s3, s21
	s_cselect_b32 s56, s14, s20
	s_cselect_b32 s55, s15, s18
	s_cselect_b32 s54, s16, s17
	v_lshl_add_u64 v[220:221], s[52:53], 0, v[156:157]
	s_add_i32 m0, s65, 0xc000
	ds_read_b128 v[188:191], v174
	ds_read_b128 v[192:195], v174 offset:1024
	ds_read_b128 v[196:199], v174 offset:2048
	ds_read_b128 v[200:203], v174 offset:3072
	ds_read_b128 v[204:207], v174 offset:4096
	ds_read_b128 v[208:211], v174 offset:5120
	ds_read_b128 v[212:215], v174 offset:6144
	ds_read_b128 v[216:219], v174 offset:7168
	global_load_lds_dwordx4 v[220:221], off
	v_lshl_add_u64 v[220:221], s[52:53], 0, v[158:159]
	s_add_i32 m0, s65, 0xe000
	s_nop 0
	global_load_lds_dwordx4 v[220:221], off
	s_waitcnt vmcnt(8)
	s_waitcnt lgkmcnt(0)
	s_barrier
	s_setprio 1
	s_waitcnt lgkmcnt(0)
	v_mfma_f32_16x16x32_bf16 v[126:129], v[130:133], v[188:191], v[126:129]
	v_mfma_f32_16x16x32_bf16 v[122:125], v[138:141], v[188:191], v[122:125]
	v_mfma_f32_16x16x32_bf16 v[106:109], v[138:141], v[196:199], v[106:109]
	v_mfma_f32_16x16x32_bf16 v[110:113], v[130:133], v[196:199], v[110:113]
	v_mfma_f32_16x16x32_bf16 v[94:97], v[130:133], v[204:207], v[94:97]
	v_mfma_f32_16x16x32_bf16 v[90:93], v[138:141], v[204:207], v[90:93]
	v_mfma_f32_16x16x32_bf16 v[74:77], v[138:141], v[212:215], v[74:77]
	v_mfma_f32_16x16x32_bf16 v[78:81], v[130:133], v[212:215], v[78:81]
	v_mfma_f32_16x16x32_bf16 v[126:129], v[134:137], v[192:195], v[126:129]
	v_mfma_f32_16x16x32_bf16 v[122:125], v[142:145], v[192:195], v[122:125]
	v_mfma_f32_16x16x32_bf16 v[106:109], v[142:145], v[200:203], v[106:109]
	v_mfma_f32_16x16x32_bf16 v[110:113], v[134:137], v[200:203], v[110:113]
	v_mfma_f32_16x16x32_bf16 v[94:97], v[134:137], v[208:211], v[94:97]
	v_mfma_f32_16x16x32_bf16 v[90:93], v[142:145], v[208:211], v[90:93]
	v_mfma_f32_16x16x32_bf16 v[74:77], v[142:145], v[216:219], v[74:77]
	v_mfma_f32_16x16x32_bf16 v[78:81], v[134:137], v[216:219], v[78:81]
	s_setprio 0
	s_setprio 1
	v_mfma_f32_16x16x32_bf16 v[118:121], v[166:169], v[188:191], v[118:121]
	v_mfma_f32_16x16x32_bf16 v[114:117], v[180:183], v[188:191], v[114:117]
	v_mfma_f32_16x16x32_bf16 v[98:101], v[180:183], v[196:199], v[98:101]
	v_mfma_f32_16x16x32_bf16 v[102:105], v[166:169], v[196:199], v[102:105]
	v_mfma_f32_16x16x32_bf16 v[86:89], v[166:169], v[204:207], v[86:89]
	v_mfma_f32_16x16x32_bf16 v[82:85], v[180:183], v[204:207], v[82:85]
	v_mfma_f32_16x16x32_bf16 v[66:69], v[180:183], v[212:215], v[66:69]
	v_mfma_f32_16x16x32_bf16 v[70:73], v[166:169], v[212:215], v[70:73]
	v_mfma_f32_16x16x32_bf16 v[118:121], v[176:179], v[192:195], v[118:121]
	v_mfma_f32_16x16x32_bf16 v[114:117], v[184:187], v[192:195], v[114:117]
	v_mfma_f32_16x16x32_bf16 v[98:101], v[184:187], v[200:203], v[98:101]
	v_mfma_f32_16x16x32_bf16 v[102:105], v[176:179], v[200:203], v[102:105]
	v_mfma_f32_16x16x32_bf16 v[86:89], v[176:179], v[208:211], v[86:89]
	v_mfma_f32_16x16x32_bf16 v[82:85], v[184:187], v[208:211], v[82:85]
	v_mfma_f32_16x16x32_bf16 v[66:69], v[184:187], v[216:219], v[66:69]
	v_mfma_f32_16x16x32_bf16 v[70:73], v[176:179], v[216:219], v[70:73]
	s_setprio 0
	s_barrier
	s_add_i32 s20, s77, s64
	v_lshl_add_u64 v[220:221], s[54:55], 0, v[146:147]
	s_mov_b32 m0, s20
	ds_read_b128 v[188:191], v174 offset:16384
	ds_read_b128 v[192:195], v174 offset:17408
	ds_read_b128 v[196:199], v174 offset:18432
	ds_read_b128 v[200:203], v174 offset:19456
	ds_read_b128 v[204:207], v174 offset:20480
	ds_read_b128 v[208:211], v174 offset:21504
	ds_read_b128 v[212:215], v174 offset:22528
	ds_read_b128 v[216:219], v174 offset:23552
	global_load_lds_dwordx4 v[220:221], off
	s_add_i32 m0, s20, 0x2000
	s_add_u32 s20, s54, 0x80000
	v_lshl_add_u64 v[222:223], s[54:55], 0, v[148:149]
	s_addc_u32 s21, s55, 0
	s_add_i32 s43, s78, s64
	global_load_lds_dwordx4 v[222:223], off
	v_lshl_add_u64 v[224:225], s[20:21], 0, v[146:147]
	s_mov_b32 m0, s43
	v_lshl_add_u64 v[226:227], s[56:57], 0, v[148:149]
	global_load_lds_dwordx4 v[224:225], off
	v_lshl_add_u64 v[224:225], s[20:21], 0, v[148:149]
	s_add_i32 m0, s43, 0x2000
	s_nop 0
	global_load_lds_dwordx4 v[224:225], off
	v_lshl_add_u64 v[224:225], s[56:57], 0, v[146:147]
	s_mov_b32 m0, s65
	s_nop 0
	global_load_lds_dwordx4 v[224:225], off
	s_mov_b32 m0, s66
	s_nop 0
	global_load_lds_dwordx4 v[226:227], off
	s_waitcnt vmcnt(8)
	s_waitcnt lgkmcnt(0)
	s_barrier
	s_setprio 1
	s_waitcnt lgkmcnt(0)
	v_mfma_f32_16x16x32_bf16 v[62:65], v[130:133], v[188:191], v[62:65]
	v_mfma_f32_16x16x32_bf16 v[58:61], v[138:141], v[188:191], v[58:61]
	v_mfma_f32_16x16x32_bf16 v[42:45], v[138:141], v[196:199], v[42:45]
	v_mfma_f32_16x16x32_bf16 v[46:49], v[130:133], v[196:199], v[46:49]
	v_mfma_f32_16x16x32_bf16 v[30:33], v[130:133], v[204:207], v[30:33]
	v_mfma_f32_16x16x32_bf16 v[26:29], v[138:141], v[204:207], v[26:29]
	v_mfma_f32_16x16x32_bf16 v[10:13], v[138:141], v[212:215], v[10:13]
	v_mfma_f32_16x16x32_bf16 v[14:17], v[130:133], v[212:215], v[14:17]
	v_mfma_f32_16x16x32_bf16 v[62:65], v[134:137], v[192:195], v[62:65]
	v_mfma_f32_16x16x32_bf16 v[58:61], v[142:145], v[192:195], v[58:61]
	v_mfma_f32_16x16x32_bf16 v[42:45], v[142:145], v[200:203], v[42:45]
	v_mfma_f32_16x16x32_bf16 v[46:49], v[134:137], v[200:203], v[46:49]
	v_mfma_f32_16x16x32_bf16 v[30:33], v[134:137], v[208:211], v[30:33]
	v_mfma_f32_16x16x32_bf16 v[26:29], v[142:145], v[208:211], v[26:29]
	v_mfma_f32_16x16x32_bf16 v[10:13], v[142:145], v[216:219], v[10:13]
	v_mfma_f32_16x16x32_bf16 v[14:17], v[134:137], v[216:219], v[14:17]
	s_setprio 0
	s_setprio 1
	v_mfma_f32_16x16x32_bf16 v[54:57], v[166:169], v[188:191], v[54:57]
	v_mfma_f32_16x16x32_bf16 v[50:53], v[180:183], v[188:191], v[50:53]
	v_mfma_f32_16x16x32_bf16 v[34:37], v[180:183], v[196:199], v[34:37]
	v_mfma_f32_16x16x32_bf16 v[38:41], v[166:169], v[196:199], v[38:41]
	v_mfma_f32_16x16x32_bf16 v[22:25], v[166:169], v[204:207], v[22:25]
	v_mfma_f32_16x16x32_bf16 v[18:21], v[180:183], v[204:207], v[18:21]
	v_mfma_f32_16x16x32_bf16 v[2:5], v[180:183], v[212:215], v[2:5]
	v_mfma_f32_16x16x32_bf16 v[6:9], v[166:169], v[212:215], v[6:9]
	v_mfma_f32_16x16x32_bf16 v[54:57], v[176:179], v[192:195], v[54:57]
	v_mfma_f32_16x16x32_bf16 v[50:53], v[184:187], v[192:195], v[50:53]
	v_mfma_f32_16x16x32_bf16 v[34:37], v[184:187], v[200:203], v[34:37]
	v_mfma_f32_16x16x32_bf16 v[38:41], v[176:179], v[200:203], v[38:41]
	v_mfma_f32_16x16x32_bf16 v[22:25], v[176:179], v[208:211], v[22:25]
	v_mfma_f32_16x16x32_bf16 v[18:21], v[184:187], v[208:211], v[18:21]
	v_mfma_f32_16x16x32_bf16 v[2:5], v[184:187], v[216:219], v[2:5]
	v_mfma_f32_16x16x32_bf16 v[6:9], v[176:179], v[216:219], v[6:9]
	s_setprio 0
	s_barrier
	s_add_i32 s43, 0, 0x18000
	s_add_i32 s45, 0, 0x1c000
	v_add_u32_e32 v142, s43, v170
	v_add_u32_e32 v184, s45, v170
	ds_read_b128 v[130:133], v142
	ds_read_b128 v[134:137], v142 offset:1024
	ds_read_b128 v[138:141], v142 offset:2048
	ds_read_b128 v[142:145], v142 offset:3072
	ds_read_b128 v[166:169], v184
	ds_read_b128 v[176:179], v184 offset:1024
	ds_read_b128 v[180:183], v184 offset:2048
	ds_read_b128 v[184:187], v184 offset:3072
	s_add_u32 s20, s56, 0x80000
	s_addc_u32 s21, s57, 0
	s_mov_b32 m0, s67
	v_lshl_add_u64 v[228:229], s[20:21], 0, v[146:147]
	ds_read_b128 v[188:191], v174 offset:32768
	ds_read_b128 v[192:195], v174 offset:33792
	ds_read_b128 v[196:199], v174 offset:34816
	ds_read_b128 v[200:203], v174 offset:35840
	ds_read_b128 v[204:207], v174 offset:36864
	ds_read_b128 v[208:211], v174 offset:37888
	ds_read_b128 v[212:215], v174 offset:38912
	ds_read_b128 v[216:219], v174 offset:39936
	global_load_lds_dwordx4 v[228:229], off
	v_lshl_add_u64 v[228:229], s[20:21], 0, v[148:149]
	s_mov_b32 m0, s68
	s_nop 0
	global_load_lds_dwordx4 v[228:229], off
	s_waitcnt vmcnt(8)
	s_waitcnt lgkmcnt(0)
	s_barrier
	s_setprio 1
	s_waitcnt lgkmcnt(0)
	v_mfma_f32_16x16x32_bf16 v[126:129], v[130:133], v[188:191], v[126:129]
	v_mfma_f32_16x16x32_bf16 v[122:125], v[138:141], v[188:191], v[122:125]
	v_mfma_f32_16x16x32_bf16 v[106:109], v[138:141], v[196:199], v[106:109]
	v_mfma_f32_16x16x32_bf16 v[110:113], v[130:133], v[196:199], v[110:113]
	v_mfma_f32_16x16x32_bf16 v[94:97], v[130:133], v[204:207], v[94:97]
	v_mfma_f32_16x16x32_bf16 v[90:93], v[138:141], v[204:207], v[90:93]
	v_mfma_f32_16x16x32_bf16 v[74:77], v[138:141], v[212:215], v[74:77]
	v_mfma_f32_16x16x32_bf16 v[78:81], v[130:133], v[212:215], v[78:81]
	v_mfma_f32_16x16x32_bf16 v[126:129], v[134:137], v[192:195], v[126:129]
	v_mfma_f32_16x16x32_bf16 v[122:125], v[142:145], v[192:195], v[122:125]
	v_mfma_f32_16x16x32_bf16 v[106:109], v[142:145], v[200:203], v[106:109]
	v_mfma_f32_16x16x32_bf16 v[110:113], v[134:137], v[200:203], v[110:113]
	v_mfma_f32_16x16x32_bf16 v[94:97], v[134:137], v[208:211], v[94:97]
	v_mfma_f32_16x16x32_bf16 v[90:93], v[142:145], v[208:211], v[90:93]
	v_mfma_f32_16x16x32_bf16 v[74:77], v[142:145], v[216:219], v[74:77]
	v_mfma_f32_16x16x32_bf16 v[78:81], v[134:137], v[216:219], v[78:81]
	s_setprio 0
	s_setprio 1
	v_mfma_f32_16x16x32_bf16 v[118:121], v[166:169], v[188:191], v[118:121]
	v_mfma_f32_16x16x32_bf16 v[114:117], v[180:183], v[188:191], v[114:117]
	v_mfma_f32_16x16x32_bf16 v[98:101], v[180:183], v[196:199], v[98:101]
	v_mfma_f32_16x16x32_bf16 v[102:105], v[166:169], v[196:199], v[102:105]
	v_mfma_f32_16x16x32_bf16 v[86:89], v[166:169], v[204:207], v[86:89]
	v_mfma_f32_16x16x32_bf16 v[82:85], v[180:183], v[204:207], v[82:85]
	v_mfma_f32_16x16x32_bf16 v[66:69], v[180:183], v[212:215], v[66:69]
	v_mfma_f32_16x16x32_bf16 v[70:73], v[166:169], v[212:215], v[70:73]
	v_mfma_f32_16x16x32_bf16 v[118:121], v[176:179], v[192:195], v[118:121]
	v_mfma_f32_16x16x32_bf16 v[114:117], v[184:187], v[192:195], v[114:117]
	v_mfma_f32_16x16x32_bf16 v[98:101], v[184:187], v[200:203], v[98:101]
	v_mfma_f32_16x16x32_bf16 v[102:105], v[176:179], v[200:203], v[102:105]
	v_mfma_f32_16x16x32_bf16 v[86:89], v[176:179], v[208:211], v[86:89]
	v_mfma_f32_16x16x32_bf16 v[82:85], v[184:187], v[208:211], v[82:85]
	v_mfma_f32_16x16x32_bf16 v[66:69], v[184:187], v[216:219], v[66:69]
	v_mfma_f32_16x16x32_bf16 v[70:73], v[176:179], v[216:219], v[70:73]
	s_setprio 0
	s_barrier
	s_add_i32 s20, s43, s64
	v_lshl_add_u64 v[220:221], v[220:221], 0, s[26:27]
	s_mov_b32 m0, s20
	ds_read_b128 v[188:191], v174 offset:49152
	ds_read_b128 v[192:195], v174 offset:50176
	ds_read_b128 v[196:199], v174 offset:51200
	ds_read_b128 v[200:203], v174 offset:52224
	ds_read_b128 v[204:207], v174 offset:53248
	ds_read_b128 v[208:211], v174 offset:54272
	ds_read_b128 v[212:215], v174 offset:55296
	ds_read_b128 v[216:219], v174 offset:56320
	global_load_lds_dwordx4 v[220:221], off
	s_add_i32 m0, s20, 0x2000
	s_add_u32 s20, s54, 0x80080
	v_lshl_add_u64 v[220:221], v[222:223], 0, s[26:27]
	s_addc_u32 s21, s55, 0
	s_add_i32 s43, s45, s64
	global_load_lds_dwordx4 v[220:221], off
	v_lshl_add_u64 v[220:221], s[20:21], 0, v[146:147]
	s_mov_b32 m0, s43
	s_nop 0
	global_load_lds_dwordx4 v[220:221], off
	v_lshl_add_u64 v[220:221], s[20:21], 0, v[148:149]
	s_add_i32 m0, s43, 0x2000
	s_nop 0
	global_load_lds_dwordx4 v[220:221], off
	v_lshl_add_u64 v[220:221], v[224:225], 0, s[26:27]
	s_mov_b32 m0, s73
	s_nop 0
	global_load_lds_dwordx4 v[220:221], off
	v_lshl_add_u64 v[220:221], v[226:227], 0, s[26:27]
	s_mov_b32 m0, s74
	s_nop 0
	global_load_lds_dwordx4 v[220:221], off
	s_waitcnt vmcnt(8)
	s_waitcnt lgkmcnt(0)
	s_barrier
	s_setprio 1
	s_waitcnt lgkmcnt(0)
	v_mfma_f32_16x16x32_bf16 v[62:65], v[130:133], v[188:191], v[62:65]
	v_mfma_f32_16x16x32_bf16 v[58:61], v[138:141], v[188:191], v[58:61]
	v_mfma_f32_16x16x32_bf16 v[42:45], v[138:141], v[196:199], v[42:45]
	v_mfma_f32_16x16x32_bf16 v[46:49], v[130:133], v[196:199], v[46:49]
	v_mfma_f32_16x16x32_bf16 v[30:33], v[130:133], v[204:207], v[30:33]
	v_mfma_f32_16x16x32_bf16 v[26:29], v[138:141], v[204:207], v[26:29]
	v_mfma_f32_16x16x32_bf16 v[10:13], v[138:141], v[212:215], v[10:13]
	v_mfma_f32_16x16x32_bf16 v[14:17], v[130:133], v[212:215], v[14:17]
	v_mfma_f32_16x16x32_bf16 v[62:65], v[134:137], v[192:195], v[62:65]
	v_mfma_f32_16x16x32_bf16 v[58:61], v[142:145], v[192:195], v[58:61]
	v_mfma_f32_16x16x32_bf16 v[42:45], v[142:145], v[200:203], v[42:45]
	v_mfma_f32_16x16x32_bf16 v[46:49], v[134:137], v[200:203], v[46:49]
	v_mfma_f32_16x16x32_bf16 v[30:33], v[134:137], v[208:211], v[30:33]
	v_mfma_f32_16x16x32_bf16 v[26:29], v[142:145], v[208:211], v[26:29]
	v_mfma_f32_16x16x32_bf16 v[10:13], v[142:145], v[216:219], v[10:13]
	v_mfma_f32_16x16x32_bf16 v[14:17], v[134:137], v[216:219], v[14:17]
	s_setprio 0
	s_setprio 1
	v_mfma_f32_16x16x32_bf16 v[54:57], v[166:169], v[188:191], v[54:57]
	v_mfma_f32_16x16x32_bf16 v[50:53], v[180:183], v[188:191], v[50:53]
	v_mfma_f32_16x16x32_bf16 v[34:37], v[180:183], v[196:199], v[34:37]
	v_mfma_f32_16x16x32_bf16 v[38:41], v[166:169], v[196:199], v[38:41]
	v_mfma_f32_16x16x32_bf16 v[22:25], v[166:169], v[204:207], v[22:25]
	v_mfma_f32_16x16x32_bf16 v[18:21], v[180:183], v[204:207], v[18:21]
	v_mfma_f32_16x16x32_bf16 v[2:5], v[180:183], v[212:215], v[2:5]
	v_mfma_f32_16x16x32_bf16 v[6:9], v[166:169], v[212:215], v[6:9]
	v_mfma_f32_16x16x32_bf16 v[54:57], v[176:179], v[192:195], v[54:57]
	v_mfma_f32_16x16x32_bf16 v[50:53], v[184:187], v[192:195], v[50:53]
	v_mfma_f32_16x16x32_bf16 v[34:37], v[184:187], v[200:203], v[34:37]
	v_mfma_f32_16x16x32_bf16 v[38:41], v[176:179], v[200:203], v[38:41]
	v_mfma_f32_16x16x32_bf16 v[22:25], v[176:179], v[208:211], v[22:25]
	v_mfma_f32_16x16x32_bf16 v[18:21], v[184:187], v[208:211], v[18:21]
	v_mfma_f32_16x16x32_bf16 v[2:5], v[184:187], v[216:219], v[2:5]
	v_mfma_f32_16x16x32_bf16 v[6:9], v[176:179], v[216:219], v[6:9]
	s_setprio 0
	s_barrier
	s_add_i32 s19, s19, 2
	s_add_u32 s52, s52, 0x100
	s_addc_u32 s53, s53, 0
	s_add_u32 s17, s17, 0x100
	s_addc_u32 s18, s18, 0
	s_cmp_gt_u32 s19, 29
	s_cbranch_scc0 .LBB0_986
	s_and_b64 vcc, exec, s[28:29]
	s_cbranch_vccnz .LBB0_991
	v_lshl_add_u32 v166, s50, 8, v163
	s_cmp_gt_i32 s10, 1
	s_mov_b64 s[50:51], -1
	s_cbranch_scc1 .LBB0_992

.LBB0_1213:
	ds_read_b128 v[130:133], v189
	ds_read_b128 v[134:137], v189 offset:1024
	ds_read_b128 v[138:141], v189 offset:2048
	ds_read_b128 v[142:145], v189 offset:3072
	ds_read_b128 v[164:167], v190
	ds_read_b128 v[168:171], v190 offset:1024
	ds_read_b128 v[172:175], v190 offset:2048
	ds_read_b128 v[194:197], v190 offset:3072
	s_add_u32 s20, s52, 0xfff80080
	s_addc_u32 s21, s53, -1
	s_cmp_eq_u32 s19, 28
	s_cselect_b32 s57, s3, s21
	s_cselect_b32 s56, s14, s20
	s_cselect_b32 s55, s15, s18
	s_cselect_b32 s54, s16, s17
	v_lshl_add_u64 v[230:231], s[52:53], 0, v[154:155]
	s_add_i32 m0, s65, 0xc000
	ds_read_b128 v[198:201], v191
	ds_read_b128 v[202:205], v191 offset:1024
	ds_read_b128 v[206:209], v191 offset:2048
	ds_read_b128 v[210:213], v191 offset:3072
	ds_read_b128 v[214:217], v191 offset:4096
	ds_read_b128 v[218:221], v191 offset:5120
	ds_read_b128 v[222:225], v191 offset:6144
	ds_read_b128 v[226:229], v191 offset:7168
	global_load_lds_dwordx4 v[230:231], off
	v_lshl_add_u64 v[230:231], s[52:53], 0, v[156:157]
	s_add_i32 m0, s65, 0xe000
	s_nop 0
	global_load_lds_dwordx4 v[230:231], off
	s_waitcnt vmcnt(8)
	s_waitcnt lgkmcnt(0)
	s_barrier
	s_setprio 1
	s_waitcnt lgkmcnt(0)
	v_mfma_f32_16x16x32_bf16 v[126:129], v[130:133], v[198:201], v[126:129]
	v_mfma_f32_16x16x32_bf16 v[122:125], v[138:141], v[198:201], v[122:125]
	v_mfma_f32_16x16x32_bf16 v[106:109], v[138:141], v[206:209], v[106:109]
	v_mfma_f32_16x16x32_bf16 v[110:113], v[130:133], v[206:209], v[110:113]
	v_mfma_f32_16x16x32_bf16 v[94:97], v[130:133], v[214:217], v[94:97]
	v_mfma_f32_16x16x32_bf16 v[90:93], v[138:141], v[214:217], v[90:93]
	v_mfma_f32_16x16x32_bf16 v[74:77], v[138:141], v[222:225], v[74:77]
	v_mfma_f32_16x16x32_bf16 v[78:81], v[130:133], v[222:225], v[78:81]
	v_mfma_f32_16x16x32_bf16 v[126:129], v[134:137], v[202:205], v[126:129]
	v_mfma_f32_16x16x32_bf16 v[122:125], v[142:145], v[202:205], v[122:125]
	v_mfma_f32_16x16x32_bf16 v[106:109], v[142:145], v[210:213], v[106:109]
	v_mfma_f32_16x16x32_bf16 v[110:113], v[134:137], v[210:213], v[110:113]
	v_mfma_f32_16x16x32_bf16 v[94:97], v[134:137], v[218:221], v[94:97]
	v_mfma_f32_16x16x32_bf16 v[90:93], v[142:145], v[218:221], v[90:93]
	v_mfma_f32_16x16x32_bf16 v[74:77], v[142:145], v[226:229], v[74:77]
	v_mfma_f32_16x16x32_bf16 v[78:81], v[134:137], v[226:229], v[78:81]
	s_setprio 0
	s_setprio 1
	v_mfma_f32_16x16x32_bf16 v[118:121], v[164:167], v[198:201], v[118:121]
	v_mfma_f32_16x16x32_bf16 v[114:117], v[172:175], v[198:201], v[114:117]
	v_mfma_f32_16x16x32_bf16 v[98:101], v[172:175], v[206:209], v[98:101]
	v_mfma_f32_16x16x32_bf16 v[102:105], v[164:167], v[206:209], v[102:105]
	v_mfma_f32_16x16x32_bf16 v[86:89], v[164:167], v[214:217], v[86:89]
	v_mfma_f32_16x16x32_bf16 v[82:85], v[172:175], v[214:217], v[82:85]
	v_mfma_f32_16x16x32_bf16 v[66:69], v[172:175], v[222:225], v[66:69]
	v_mfma_f32_16x16x32_bf16 v[70:73], v[164:167], v[222:225], v[70:73]
	v_mfma_f32_16x16x32_bf16 v[118:121], v[168:171], v[202:205], v[118:121]
	v_mfma_f32_16x16x32_bf16 v[114:117], v[194:197], v[202:205], v[114:117]
	v_mfma_f32_16x16x32_bf16 v[98:101], v[194:197], v[210:213], v[98:101]
	v_mfma_f32_16x16x32_bf16 v[102:105], v[168:171], v[210:213], v[102:105]
	v_mfma_f32_16x16x32_bf16 v[86:89], v[168:171], v[218:221], v[86:89]
	v_mfma_f32_16x16x32_bf16 v[82:85], v[194:197], v[218:221], v[82:85]
	v_mfma_f32_16x16x32_bf16 v[66:69], v[194:197], v[226:229], v[66:69]
	v_mfma_f32_16x16x32_bf16 v[70:73], v[168:171], v[226:229], v[70:73]
	s_setprio 0
	s_barrier
	s_add_i32 s20, s77, s64
	v_lshl_add_u64 v[230:231], s[54:55], 0, v[146:147]
	s_mov_b32 m0, s20
	ds_read_b128 v[198:201], v191 offset:16384
	ds_read_b128 v[202:205], v191 offset:17408
	ds_read_b128 v[206:209], v191 offset:18432
	ds_read_b128 v[210:213], v191 offset:19456
	ds_read_b128 v[214:217], v191 offset:20480
	ds_read_b128 v[218:221], v191 offset:21504
	ds_read_b128 v[222:225], v191 offset:22528
	ds_read_b128 v[226:229], v191 offset:23552
	global_load_lds_dwordx4 v[230:231], off
	s_add_i32 m0, s20, 0x2000
	s_add_u32 s20, s54, 0x80000
	v_lshl_add_u64 v[232:233], s[54:55], 0, v[148:149]
	s_addc_u32 s21, s55, 0
	s_add_i32 s43, s78, s64
	global_load_lds_dwordx4 v[232:233], off
	v_lshl_add_u64 v[234:235], s[20:21], 0, v[146:147]
	s_mov_b32 m0, s43
	v_lshl_add_u64 v[236:237], s[56:57], 0, v[148:149]
	global_load_lds_dwordx4 v[234:235], off
	v_lshl_add_u64 v[234:235], s[20:21], 0, v[148:149]
	s_add_i32 m0, s43, 0x2000
	s_nop 0
	global_load_lds_dwordx4 v[234:235], off
	v_lshl_add_u64 v[234:235], s[56:57], 0, v[146:147]
	s_mov_b32 m0, s65
	s_nop 0
	global_load_lds_dwordx4 v[234:235], off
	s_mov_b32 m0, s66
	s_nop 0
	global_load_lds_dwordx4 v[236:237], off
	s_waitcnt vmcnt(8)
	s_waitcnt lgkmcnt(0)
	s_barrier
	s_setprio 1
	s_waitcnt lgkmcnt(0)
	v_mfma_f32_16x16x32_bf16 v[62:65], v[130:133], v[198:201], v[62:65]
	v_mfma_f32_16x16x32_bf16 v[58:61], v[138:141], v[198:201], v[58:61]
	v_mfma_f32_16x16x32_bf16 v[42:45], v[138:141], v[206:209], v[42:45]
	v_mfma_f32_16x16x32_bf16 v[46:49], v[130:133], v[206:209], v[46:49]
	v_mfma_f32_16x16x32_bf16 v[30:33], v[130:133], v[214:217], v[30:33]
	v_mfma_f32_16x16x32_bf16 v[26:29], v[138:141], v[214:217], v[26:29]
	v_mfma_f32_16x16x32_bf16 v[10:13], v[138:141], v[222:225], v[10:13]
	v_mfma_f32_16x16x32_bf16 v[14:17], v[130:133], v[222:225], v[14:17]
	v_mfma_f32_16x16x32_bf16 v[62:65], v[134:137], v[202:205], v[62:65]
	v_mfma_f32_16x16x32_bf16 v[58:61], v[142:145], v[202:205], v[58:61]
	v_mfma_f32_16x16x32_bf16 v[42:45], v[142:145], v[210:213], v[42:45]
	v_mfma_f32_16x16x32_bf16 v[46:49], v[134:137], v[210:213], v[46:49]
	v_mfma_f32_16x16x32_bf16 v[30:33], v[134:137], v[218:221], v[30:33]
	v_mfma_f32_16x16x32_bf16 v[26:29], v[142:145], v[218:221], v[26:29]
	v_mfma_f32_16x16x32_bf16 v[10:13], v[142:145], v[226:229], v[10:13]
	v_mfma_f32_16x16x32_bf16 v[14:17], v[134:137], v[226:229], v[14:17]
	s_setprio 0
	s_setprio 1
	v_mfma_f32_16x16x32_bf16 v[54:57], v[164:167], v[198:201], v[54:57]
	v_mfma_f32_16x16x32_bf16 v[50:53], v[172:175], v[198:201], v[50:53]
	v_mfma_f32_16x16x32_bf16 v[34:37], v[172:175], v[206:209], v[34:37]
	v_mfma_f32_16x16x32_bf16 v[38:41], v[164:167], v[206:209], v[38:41]
	v_mfma_f32_16x16x32_bf16 v[22:25], v[164:167], v[214:217], v[22:25]
	v_mfma_f32_16x16x32_bf16 v[18:21], v[172:175], v[214:217], v[18:21]
	v_mfma_f32_16x16x32_bf16 v[2:5], v[172:175], v[222:225], v[2:5]
	v_mfma_f32_16x16x32_bf16 v[6:9], v[164:167], v[222:225], v[6:9]
	v_mfma_f32_16x16x32_bf16 v[54:57], v[168:171], v[202:205], v[54:57]
	v_mfma_f32_16x16x32_bf16 v[50:53], v[194:197], v[202:205], v[50:53]
	v_mfma_f32_16x16x32_bf16 v[34:37], v[194:197], v[210:213], v[34:37]
	v_mfma_f32_16x16x32_bf16 v[38:41], v[168:171], v[210:213], v[38:41]
	v_mfma_f32_16x16x32_bf16 v[22:25], v[168:171], v[218:221], v[22:25]
	v_mfma_f32_16x16x32_bf16 v[18:21], v[194:197], v[218:221], v[18:21]
	v_mfma_f32_16x16x32_bf16 v[2:5], v[194:197], v[226:229], v[2:5]
	v_mfma_f32_16x16x32_bf16 v[6:9], v[168:171], v[226:229], v[6:9]
	s_setprio 0
	s_barrier
	s_add_i32 s43, 0, 0x18000
	s_add_i32 s45, 0, 0x1c000
	v_add_u32_e32 v142, s43, v187
	v_add_u32_e32 v193, s45, v187
	ds_read_b128 v[130:133], v142
	ds_read_b128 v[134:137], v142 offset:1024
	ds_read_b128 v[138:141], v142 offset:2048
	ds_read_b128 v[142:145], v142 offset:3072
	ds_read_b128 v[164:167], v193
	ds_read_b128 v[168:171], v193 offset:1024
	ds_read_b128 v[172:175], v193 offset:2048
	ds_read_b128 v[194:197], v193 offset:3072
	s_add_u32 s20, s56, 0x80000
	s_addc_u32 s21, s57, 0
	s_mov_b32 m0, s67
	v_lshl_add_u64 v[238:239], s[20:21], 0, v[146:147]
	ds_read_b128 v[198:201], v191 offset:32768
	ds_read_b128 v[202:205], v191 offset:33792
	ds_read_b128 v[206:209], v191 offset:34816
	ds_read_b128 v[210:213], v191 offset:35840
	ds_read_b128 v[214:217], v191 offset:36864
	ds_read_b128 v[218:221], v191 offset:37888
	ds_read_b128 v[222:225], v191 offset:38912
	ds_read_b128 v[226:229], v191 offset:39936
	global_load_lds_dwordx4 v[238:239], off
	v_lshl_add_u64 v[238:239], s[20:21], 0, v[148:149]
	s_mov_b32 m0, s68
	s_nop 0
	global_load_lds_dwordx4 v[238:239], off
	s_waitcnt vmcnt(8)
	s_waitcnt lgkmcnt(0)
	s_barrier
	s_setprio 1
	s_waitcnt lgkmcnt(0)
	v_mfma_f32_16x16x32_bf16 v[126:129], v[130:133], v[198:201], v[126:129]
	v_mfma_f32_16x16x32_bf16 v[122:125], v[138:141], v[198:201], v[122:125]
	v_mfma_f32_16x16x32_bf16 v[106:109], v[138:141], v[206:209], v[106:109]
	v_mfma_f32_16x16x32_bf16 v[110:113], v[130:133], v[206:209], v[110:113]
	v_mfma_f32_16x16x32_bf16 v[94:97], v[130:133], v[214:217], v[94:97]
	v_mfma_f32_16x16x32_bf16 v[90:93], v[138:141], v[214:217], v[90:93]
	v_mfma_f32_16x16x32_bf16 v[74:77], v[138:141], v[222:225], v[74:77]
	v_mfma_f32_16x16x32_bf16 v[78:81], v[130:133], v[222:225], v[78:81]
	v_mfma_f32_16x16x32_bf16 v[126:129], v[134:137], v[202:205], v[126:129]
	v_mfma_f32_16x16x32_bf16 v[122:125], v[142:145], v[202:205], v[122:125]
	v_mfma_f32_16x16x32_bf16 v[106:109], v[142:145], v[210:213], v[106:109]
	v_mfma_f32_16x16x32_bf16 v[110:113], v[134:137], v[210:213], v[110:113]
	v_mfma_f32_16x16x32_bf16 v[94:97], v[134:137], v[218:221], v[94:97]
	v_mfma_f32_16x16x32_bf16 v[90:93], v[142:145], v[218:221], v[90:93]
	v_mfma_f32_16x16x32_bf16 v[74:77], v[142:145], v[226:229], v[74:77]
	v_mfma_f32_16x16x32_bf16 v[78:81], v[134:137], v[226:229], v[78:81]
	s_setprio 0
	s_setprio 1
	v_mfma_f32_16x16x32_bf16 v[118:121], v[164:167], v[198:201], v[118:121]
	v_mfma_f32_16x16x32_bf16 v[114:117], v[172:175], v[198:201], v[114:117]
	v_mfma_f32_16x16x32_bf16 v[98:101], v[172:175], v[206:209], v[98:101]
	v_mfma_f32_16x16x32_bf16 v[102:105], v[164:167], v[206:209], v[102:105]
	v_mfma_f32_16x16x32_bf16 v[86:89], v[164:167], v[214:217], v[86:89]
	v_mfma_f32_16x16x32_bf16 v[82:85], v[172:175], v[214:217], v[82:85]
	v_mfma_f32_16x16x32_bf16 v[66:69], v[172:175], v[222:225], v[66:69]
	v_mfma_f32_16x16x32_bf16 v[70:73], v[164:167], v[222:225], v[70:73]
	v_mfma_f32_16x16x32_bf16 v[118:121], v[168:171], v[202:205], v[118:121]
	v_mfma_f32_16x16x32_bf16 v[114:117], v[194:197], v[202:205], v[114:117]
	v_mfma_f32_16x16x32_bf16 v[98:101], v[194:197], v[210:213], v[98:101]
	v_mfma_f32_16x16x32_bf16 v[102:105], v[168:171], v[210:213], v[102:105]
	v_mfma_f32_16x16x32_bf16 v[86:89], v[168:171], v[218:221], v[86:89]
	v_mfma_f32_16x16x32_bf16 v[82:85], v[194:197], v[218:221], v[82:85]
	v_mfma_f32_16x16x32_bf16 v[66:69], v[194:197], v[226:229], v[66:69]
	v_mfma_f32_16x16x32_bf16 v[70:73], v[168:171], v[226:229], v[70:73]
	s_setprio 0
	s_barrier
	s_add_i32 s20, s43, s64
	v_lshl_add_u64 v[230:231], v[230:231], 0, s[26:27]
	s_mov_b32 m0, s20
	ds_read_b128 v[198:201], v191 offset:49152
	ds_read_b128 v[202:205], v191 offset:50176
	ds_read_b128 v[206:209], v191 offset:51200
	ds_read_b128 v[210:213], v191 offset:52224
	ds_read_b128 v[214:217], v191 offset:53248
	ds_read_b128 v[218:221], v191 offset:54272
	ds_read_b128 v[222:225], v191 offset:55296
	ds_read_b128 v[226:229], v191 offset:56320
	global_load_lds_dwordx4 v[230:231], off
	s_add_i32 m0, s20, 0x2000
	s_add_u32 s20, s54, 0x80080
	v_lshl_add_u64 v[230:231], v[232:233], 0, s[26:27]
	s_addc_u32 s21, s55, 0
	s_add_i32 s43, s45, s64
	global_load_lds_dwordx4 v[230:231], off
	v_lshl_add_u64 v[230:231], s[20:21], 0, v[146:147]
	s_mov_b32 m0, s43
	s_nop 0
	global_load_lds_dwordx4 v[230:231], off
	v_lshl_add_u64 v[230:231], s[20:21], 0, v[148:149]
	s_add_i32 m0, s43, 0x2000
	s_nop 0
	global_load_lds_dwordx4 v[230:231], off
	v_lshl_add_u64 v[230:231], v[234:235], 0, s[26:27]
	s_mov_b32 m0, s73
	s_nop 0
	global_load_lds_dwordx4 v[230:231], off
	v_lshl_add_u64 v[230:231], v[236:237], 0, s[26:27]
	s_mov_b32 m0, s74
	s_nop 0
	global_load_lds_dwordx4 v[230:231], off
	s_waitcnt vmcnt(8)
	s_waitcnt lgkmcnt(0)
	s_barrier
	s_setprio 1
	s_waitcnt lgkmcnt(0)
	v_mfma_f32_16x16x32_bf16 v[62:65], v[130:133], v[198:201], v[62:65]
	v_mfma_f32_16x16x32_bf16 v[58:61], v[138:141], v[198:201], v[58:61]
	v_mfma_f32_16x16x32_bf16 v[42:45], v[138:141], v[206:209], v[42:45]
	v_mfma_f32_16x16x32_bf16 v[46:49], v[130:133], v[206:209], v[46:49]
	v_mfma_f32_16x16x32_bf16 v[30:33], v[130:133], v[214:217], v[30:33]
	v_mfma_f32_16x16x32_bf16 v[26:29], v[138:141], v[214:217], v[26:29]
	v_mfma_f32_16x16x32_bf16 v[10:13], v[138:141], v[222:225], v[10:13]
	v_mfma_f32_16x16x32_bf16 v[14:17], v[130:133], v[222:225], v[14:17]
	v_mfma_f32_16x16x32_bf16 v[62:65], v[134:137], v[202:205], v[62:65]
	v_mfma_f32_16x16x32_bf16 v[58:61], v[142:145], v[202:205], v[58:61]
	v_mfma_f32_16x16x32_bf16 v[42:45], v[142:145], v[210:213], v[42:45]
	v_mfma_f32_16x16x32_bf16 v[46:49], v[134:137], v[210:213], v[46:49]
	v_mfma_f32_16x16x32_bf16 v[30:33], v[134:137], v[218:221], v[30:33]
	v_mfma_f32_16x16x32_bf16 v[26:29], v[142:145], v[218:221], v[26:29]
	v_mfma_f32_16x16x32_bf16 v[10:13], v[142:145], v[226:229], v[10:13]
	v_mfma_f32_16x16x32_bf16 v[14:17], v[134:137], v[226:229], v[14:17]
	s_setprio 0
	s_setprio 1
	v_mfma_f32_16x16x32_bf16 v[54:57], v[164:167], v[198:201], v[54:57]
	v_mfma_f32_16x16x32_bf16 v[50:53], v[172:175], v[198:201], v[50:53]
	v_mfma_f32_16x16x32_bf16 v[34:37], v[172:175], v[206:209], v[34:37]
	v_mfma_f32_16x16x32_bf16 v[38:41], v[164:167], v[206:209], v[38:41]
	v_mfma_f32_16x16x32_bf16 v[22:25], v[164:167], v[214:217], v[22:25]
	v_mfma_f32_16x16x32_bf16 v[18:21], v[172:175], v[214:217], v[18:21]
	v_mfma_f32_16x16x32_bf16 v[2:5], v[172:175], v[222:225], v[2:5]
	v_mfma_f32_16x16x32_bf16 v[6:9], v[164:167], v[222:225], v[6:9]
	v_mfma_f32_16x16x32_bf16 v[54:57], v[168:171], v[202:205], v[54:57]
	v_mfma_f32_16x16x32_bf16 v[50:53], v[194:197], v[202:205], v[50:53]
	v_mfma_f32_16x16x32_bf16 v[34:37], v[194:197], v[210:213], v[34:37]
	v_mfma_f32_16x16x32_bf16 v[38:41], v[168:171], v[210:213], v[38:41]
	v_mfma_f32_16x16x32_bf16 v[22:25], v[168:171], v[218:221], v[22:25]
	v_mfma_f32_16x16x32_bf16 v[18:21], v[194:197], v[218:221], v[18:21]
	v_mfma_f32_16x16x32_bf16 v[2:5], v[194:197], v[226:229], v[2:5]
	v_mfma_f32_16x16x32_bf16 v[6:9], v[168:171], v[226:229], v[6:9]
	s_setprio 0
	s_barrier
	s_add_i32 s19, s19, 2
	s_add_u32 s52, s52, 0x100
	s_addc_u32 s53, s53, 0
	s_add_u32 s17, s17, 0x100
	s_addc_u32 s18, s18, 0
	s_cmp_gt_u32 s19, 29
	s_cbranch_scc0 .LBB0_1213
	s_and_b64 vcc, exec, s[28:29]
	s_cbranch_vccnz .LBB0_1218
	v_lshl_add_u32 v164, s50, 8, v186
	s_cmp_gt_i32 s10, 1
	s_mov_b64 s[50:51], -1
	s_cbranch_scc1 .LBB0_1219

.LBB0_1264:
	ds_read_b128 v[142:145], v163
	ds_read_b128 v[146:149], v163 offset:1024
	ds_read_b128 v[150:153], v163 offset:2048
	ds_read_b128 v[154:157], v163 offset:3072
	ds_read_b128 v[170:173], v166
	ds_read_b128 v[174:177], v166 offset:1024
	ds_read_b128 v[178:181], v166 offset:2048
	ds_read_b128 v[182:185], v166 offset:3072
	s_add_u32 s44, s42, 0xfffe0080
	s_addc_u32 s45, s43, -1
	s_cmp_eq_u32 s29, 4
	s_cselect_b32 s47, s3, s45
	s_cselect_b32 s46, s16, s44
	s_cselect_b32 s45, s17, s27
	s_cselect_b32 s44, s18, s19
	v_lshl_add_u64 v[218:219], s[42:43], 0, v[138:139]
	s_add_i32 m0, s39, 0xc000
	ds_read_b128 v[186:189], v167
	ds_read_b128 v[190:193], v167 offset:1024
	ds_read_b128 v[194:197], v167 offset:2048
	ds_read_b128 v[198:201], v167 offset:3072
	ds_read_b128 v[202:205], v167 offset:4096
	ds_read_b128 v[206:209], v167 offset:5120
	ds_read_b128 v[210:213], v167 offset:6144
	ds_read_b128 v[214:217], v167 offset:7168
	global_load_lds_dwordx4 v[218:219], off
	v_lshl_add_u64 v[218:219], s[42:43], 0, v[140:141]
	s_add_i32 m0, s39, 0xe000
	s_nop 0
	global_load_lds_dwordx4 v[218:219], off
	s_waitcnt vmcnt(8)
	s_waitcnt lgkmcnt(0)
	s_barrier
	s_setprio 1
	s_waitcnt lgkmcnt(0)
	v_mfma_f32_16x16x32_bf16 v[126:129], v[142:145], v[186:189], v[126:129]
	v_mfma_f32_16x16x32_bf16 v[122:125], v[150:153], v[186:189], v[122:125]
	v_mfma_f32_16x16x32_bf16 v[110:113], v[150:153], v[194:197], v[110:113]
	v_mfma_f32_16x16x32_bf16 v[118:121], v[142:145], v[194:197], v[118:121]
	v_mfma_f32_16x16x32_bf16 v[102:105], v[142:145], v[202:205], v[102:105]
	v_mfma_f32_16x16x32_bf16 v[94:97], v[150:153], v[202:205], v[94:97]
	v_mfma_f32_16x16x32_bf16 v[78:81], v[150:153], v[210:213], v[78:81]
	v_mfma_f32_16x16x32_bf16 v[86:89], v[142:145], v[210:213], v[86:89]
	v_mfma_f32_16x16x32_bf16 v[126:129], v[146:149], v[190:193], v[126:129]
	v_mfma_f32_16x16x32_bf16 v[122:125], v[154:157], v[190:193], v[122:125]
	v_mfma_f32_16x16x32_bf16 v[110:113], v[154:157], v[198:201], v[110:113]
	v_mfma_f32_16x16x32_bf16 v[118:121], v[146:149], v[198:201], v[118:121]
	v_mfma_f32_16x16x32_bf16 v[102:105], v[146:149], v[206:209], v[102:105]
	v_mfma_f32_16x16x32_bf16 v[94:97], v[154:157], v[206:209], v[94:97]
	v_mfma_f32_16x16x32_bf16 v[78:81], v[154:157], v[214:217], v[78:81]
	v_mfma_f32_16x16x32_bf16 v[86:89], v[146:149], v[214:217], v[86:89]
	s_setprio 0
	s_setprio 1
	v_mfma_f32_16x16x32_bf16 v[114:117], v[170:173], v[186:189], v[114:117]
	v_mfma_f32_16x16x32_bf16 v[106:109], v[178:181], v[186:189], v[106:109]
	v_mfma_f32_16x16x32_bf16 v[90:93], v[178:181], v[194:197], v[90:93]
	v_mfma_f32_16x16x32_bf16 v[98:101], v[170:173], v[194:197], v[98:101]
	v_mfma_f32_16x16x32_bf16 v[82:85], v[170:173], v[202:205], v[82:85]
	v_mfma_f32_16x16x32_bf16 v[74:77], v[178:181], v[202:205], v[74:77]
	v_mfma_f32_16x16x32_bf16 v[66:69], v[178:181], v[210:213], v[66:69]
	v_mfma_f32_16x16x32_bf16 v[70:73], v[170:173], v[210:213], v[70:73]
	v_mfma_f32_16x16x32_bf16 v[114:117], v[174:177], v[190:193], v[114:117]
	v_mfma_f32_16x16x32_bf16 v[106:109], v[182:185], v[190:193], v[106:109]
	v_mfma_f32_16x16x32_bf16 v[90:93], v[182:185], v[198:201], v[90:93]
	v_mfma_f32_16x16x32_bf16 v[98:101], v[174:177], v[198:201], v[98:101]
	v_mfma_f32_16x16x32_bf16 v[82:85], v[174:177], v[206:209], v[82:85]
	v_mfma_f32_16x16x32_bf16 v[74:77], v[182:185], v[206:209], v[74:77]
	v_mfma_f32_16x16x32_bf16 v[66:69], v[182:185], v[214:217], v[66:69]
	v_mfma_f32_16x16x32_bf16 v[70:73], v[174:177], v[214:217], v[70:73]
	s_setprio 0
	s_barrier
	s_add_i32 s62, s60, s54
	v_lshl_add_u64 v[218:219], s[44:45], 0, v[132:133]
	s_mov_b32 m0, s62
	ds_read_b128 v[186:189], v167 offset:16384
	ds_read_b128 v[190:193], v167 offset:17408
	ds_read_b128 v[194:197], v167 offset:18432
	ds_read_b128 v[198:201], v167 offset:19456
	ds_read_b128 v[202:205], v167 offset:20480
	ds_read_b128 v[206:209], v167 offset:21504
	ds_read_b128 v[210:213], v167 offset:22528
	ds_read_b128 v[214:217], v167 offset:23552
	global_load_lds_dwordx4 v[218:219], off
	s_add_i32 m0, s62, 0x2000
	s_add_u32 s62, s44, 0x20000
	v_lshl_add_u64 v[220:221], s[44:45], 0, v[136:137]
	s_addc_u32 s63, s45, 0
	s_add_i32 s64, s61, s54
	global_load_lds_dwordx4 v[220:221], off
	v_lshl_add_u64 v[222:223], s[62:63], 0, v[132:133]
	s_mov_b32 m0, s64
	v_lshl_add_u64 v[224:225], s[46:47], 0, v[134:135]
	global_load_lds_dwordx4 v[222:223], off
	v_lshl_add_u64 v[222:223], s[62:63], 0, v[136:137]
	s_add_i32 m0, s64, 0x2000
	s_nop 0
	global_load_lds_dwordx4 v[222:223], off
	v_lshl_add_u64 v[222:223], s[46:47], 0, v[130:131]
	s_mov_b32 m0, s39
	s_nop 0
	global_load_lds_dwordx4 v[222:223], off
	s_mov_b32 m0, s41
	s_nop 0
	global_load_lds_dwordx4 v[224:225], off
	s_waitcnt vmcnt(8)
	s_waitcnt lgkmcnt(0)
	s_barrier
	s_setprio 1
	s_waitcnt lgkmcnt(0)
	v_mfma_f32_16x16x32_bf16 v[62:65], v[142:145], v[186:189], v[62:65]
	v_mfma_f32_16x16x32_bf16 v[58:61], v[150:153], v[186:189], v[58:61]
	v_mfma_f32_16x16x32_bf16 v[46:49], v[150:153], v[194:197], v[46:49]
	v_mfma_f32_16x16x32_bf16 v[54:57], v[142:145], v[194:197], v[54:57]
	v_mfma_f32_16x16x32_bf16 v[38:41], v[142:145], v[202:205], v[38:41]
	v_mfma_f32_16x16x32_bf16 v[30:33], v[150:153], v[202:205], v[30:33]
	v_mfma_f32_16x16x32_bf16 v[14:17], v[150:153], v[210:213], v[14:17]
	v_mfma_f32_16x16x32_bf16 v[22:25], v[142:145], v[210:213], v[22:25]
	v_mfma_f32_16x16x32_bf16 v[62:65], v[146:149], v[190:193], v[62:65]
	v_mfma_f32_16x16x32_bf16 v[58:61], v[154:157], v[190:193], v[58:61]
	v_mfma_f32_16x16x32_bf16 v[46:49], v[154:157], v[198:201], v[46:49]
	v_mfma_f32_16x16x32_bf16 v[54:57], v[146:149], v[198:201], v[54:57]
	v_mfma_f32_16x16x32_bf16 v[38:41], v[146:149], v[206:209], v[38:41]
	v_mfma_f32_16x16x32_bf16 v[30:33], v[154:157], v[206:209], v[30:33]
	v_mfma_f32_16x16x32_bf16 v[14:17], v[154:157], v[214:217], v[14:17]
	v_mfma_f32_16x16x32_bf16 v[22:25], v[146:149], v[214:217], v[22:25]
	s_setprio 0
	s_setprio 1
	v_mfma_f32_16x16x32_bf16 v[50:53], v[170:173], v[186:189], v[50:53]
	v_mfma_f32_16x16x32_bf16 v[42:45], v[178:181], v[186:189], v[42:45]
	v_mfma_f32_16x16x32_bf16 v[26:29], v[178:181], v[194:197], v[26:29]
	v_mfma_f32_16x16x32_bf16 v[34:37], v[170:173], v[194:197], v[34:37]
	v_mfma_f32_16x16x32_bf16 v[18:21], v[170:173], v[202:205], v[18:21]
	v_mfma_f32_16x16x32_bf16 v[10:13], v[178:181], v[202:205], v[10:13]
	v_mfma_f32_16x16x32_bf16 v[2:5], v[178:181], v[210:213], v[2:5]
	v_mfma_f32_16x16x32_bf16 v[6:9], v[170:173], v[210:213], v[6:9]
	v_mfma_f32_16x16x32_bf16 v[50:53], v[174:177], v[190:193], v[50:53]
	v_mfma_f32_16x16x32_bf16 v[42:45], v[182:185], v[190:193], v[42:45]
	v_mfma_f32_16x16x32_bf16 v[26:29], v[182:185], v[198:201], v[26:29]
	v_mfma_f32_16x16x32_bf16 v[34:37], v[174:177], v[198:201], v[34:37]
	v_mfma_f32_16x16x32_bf16 v[18:21], v[174:177], v[206:209], v[18:21]
	v_mfma_f32_16x16x32_bf16 v[10:13], v[182:185], v[206:209], v[10:13]
	v_mfma_f32_16x16x32_bf16 v[2:5], v[182:185], v[214:217], v[2:5]
	v_mfma_f32_16x16x32_bf16 v[6:9], v[174:177], v[214:217], v[6:9]
	s_setprio 0
	s_barrier
	s_add_i32 s62, 0, 0x18000
	s_add_i32 s63, 0, 0x1c000
	v_add_u32_e32 v154, s62, v161
	v_add_u32_e32 v158, s63, v161
	ds_read_b128 v[142:145], v154
	ds_read_b128 v[146:149], v154 offset:1024
	ds_read_b128 v[150:153], v154 offset:2048
	ds_read_b128 v[154:157], v154 offset:3072
	ds_read_b128 v[170:173], v158
	ds_read_b128 v[174:177], v158 offset:1024
	ds_read_b128 v[178:181], v158 offset:2048
	ds_read_b128 v[182:185], v158 offset:3072
	s_add_u32 s46, s46, 0x20000
	s_addc_u32 s47, s47, 0
	s_mov_b32 m0, s55
	v_lshl_add_u64 v[226:227], s[46:47], 0, v[130:131]
	ds_read_b128 v[186:189], v167 offset:32768
	ds_read_b128 v[190:193], v167 offset:33792
	ds_read_b128 v[194:197], v167 offset:34816
	ds_read_b128 v[198:201], v167 offset:35840
	ds_read_b128 v[202:205], v167 offset:36864
	ds_read_b128 v[206:209], v167 offset:37888
	ds_read_b128 v[210:213], v167 offset:38912
	ds_read_b128 v[214:217], v167 offset:39936
	global_load_lds_dwordx4 v[226:227], off
	v_lshl_add_u64 v[226:227], s[46:47], 0, v[134:135]
	s_mov_b32 m0, s56
	s_nop 0
	global_load_lds_dwordx4 v[226:227], off
	s_waitcnt vmcnt(8)
	s_waitcnt lgkmcnt(0)
	s_barrier
	s_setprio 1
	s_waitcnt lgkmcnt(0)
	v_mfma_f32_16x16x32_bf16 v[126:129], v[142:145], v[186:189], v[126:129]
	v_mfma_f32_16x16x32_bf16 v[122:125], v[150:153], v[186:189], v[122:125]
	v_mfma_f32_16x16x32_bf16 v[110:113], v[150:153], v[194:197], v[110:113]
	v_mfma_f32_16x16x32_bf16 v[118:121], v[142:145], v[194:197], v[118:121]
	v_mfma_f32_16x16x32_bf16 v[102:105], v[142:145], v[202:205], v[102:105]
	v_mfma_f32_16x16x32_bf16 v[94:97], v[150:153], v[202:205], v[94:97]
	v_mfma_f32_16x16x32_bf16 v[78:81], v[150:153], v[210:213], v[78:81]
	v_mfma_f32_16x16x32_bf16 v[86:89], v[142:145], v[210:213], v[86:89]
	v_mfma_f32_16x16x32_bf16 v[126:129], v[146:149], v[190:193], v[126:129]
	v_mfma_f32_16x16x32_bf16 v[122:125], v[154:157], v[190:193], v[122:125]
	v_mfma_f32_16x16x32_bf16 v[110:113], v[154:157], v[198:201], v[110:113]
	v_mfma_f32_16x16x32_bf16 v[118:121], v[146:149], v[198:201], v[118:121]
	v_mfma_f32_16x16x32_bf16 v[102:105], v[146:149], v[206:209], v[102:105]
	v_mfma_f32_16x16x32_bf16 v[94:97], v[154:157], v[206:209], v[94:97]
	v_mfma_f32_16x16x32_bf16 v[78:81], v[154:157], v[214:217], v[78:81]
	v_mfma_f32_16x16x32_bf16 v[86:89], v[146:149], v[214:217], v[86:89]
	s_setprio 0
	s_setprio 1
	v_mfma_f32_16x16x32_bf16 v[114:117], v[170:173], v[186:189], v[114:117]
	v_mfma_f32_16x16x32_bf16 v[106:109], v[178:181], v[186:189], v[106:109]
	v_mfma_f32_16x16x32_bf16 v[90:93], v[178:181], v[194:197], v[90:93]
	v_mfma_f32_16x16x32_bf16 v[98:101], v[170:173], v[194:197], v[98:101]
	v_mfma_f32_16x16x32_bf16 v[82:85], v[170:173], v[202:205], v[82:85]
	v_mfma_f32_16x16x32_bf16 v[74:77], v[178:181], v[202:205], v[74:77]
	v_mfma_f32_16x16x32_bf16 v[66:69], v[178:181], v[210:213], v[66:69]
	v_mfma_f32_16x16x32_bf16 v[70:73], v[170:173], v[210:213], v[70:73]
	v_mfma_f32_16x16x32_bf16 v[114:117], v[174:177], v[190:193], v[114:117]
	v_mfma_f32_16x16x32_bf16 v[106:109], v[182:185], v[190:193], v[106:109]
	v_mfma_f32_16x16x32_bf16 v[90:93], v[182:185], v[198:201], v[90:93]
	v_mfma_f32_16x16x32_bf16 v[98:101], v[174:177], v[198:201], v[98:101]
	v_mfma_f32_16x16x32_bf16 v[82:85], v[174:177], v[206:209], v[82:85]
	v_mfma_f32_16x16x32_bf16 v[74:77], v[182:185], v[206:209], v[74:77]
	v_mfma_f32_16x16x32_bf16 v[66:69], v[182:185], v[214:217], v[66:69]
	v_mfma_f32_16x16x32_bf16 v[70:73], v[174:177], v[214:217], v[70:73]
	s_setprio 0
	s_barrier
	s_add_i32 s46, s62, s54
	v_lshl_add_u64 v[218:219], v[218:219], 0, s[22:23]
	s_mov_b32 m0, s46
	ds_read_b128 v[186:189], v167 offset:49152
	ds_read_b128 v[190:193], v167 offset:50176
	ds_read_b128 v[194:197], v167 offset:51200
	ds_read_b128 v[198:201], v167 offset:52224
	ds_read_b128 v[202:205], v167 offset:53248
	ds_read_b128 v[206:209], v167 offset:54272
	ds_read_b128 v[210:213], v167 offset:55296
	ds_read_b128 v[214:217], v167 offset:56320
	global_load_lds_dwordx4 v[218:219], off
	s_add_i32 m0, s46, 0x2000
	s_add_u32 s44, s44, 0x20080
	v_lshl_add_u64 v[218:219], v[220:221], 0, s[22:23]
	s_addc_u32 s45, s45, 0
	s_add_i32 s46, s63, s54
	global_load_lds_dwordx4 v[218:219], off
	v_lshl_add_u64 v[218:219], s[44:45], 0, v[132:133]
	s_mov_b32 m0, s46
	s_nop 0
	global_load_lds_dwordx4 v[218:219], off
	v_lshl_add_u64 v[218:219], s[44:45], 0, v[136:137]
	s_add_i32 m0, s46, 0x2000
	s_nop 0
	global_load_lds_dwordx4 v[218:219], off
	v_lshl_add_u64 v[218:219], v[222:223], 0, s[22:23]
	s_mov_b32 m0, s14
	s_nop 0
	global_load_lds_dwordx4 v[218:219], off
	v_lshl_add_u64 v[218:219], v[224:225], 0, s[22:23]
	s_mov_b32 m0, s15
	s_nop 0
	global_load_lds_dwordx4 v[218:219], off
	s_waitcnt vmcnt(8)
	s_waitcnt lgkmcnt(0)
	s_barrier
	s_setprio 1
	s_waitcnt lgkmcnt(0)
	v_mfma_f32_16x16x32_bf16 v[62:65], v[142:145], v[186:189], v[62:65]
	v_mfma_f32_16x16x32_bf16 v[58:61], v[150:153], v[186:189], v[58:61]
	v_mfma_f32_16x16x32_bf16 v[46:49], v[150:153], v[194:197], v[46:49]
	v_mfma_f32_16x16x32_bf16 v[54:57], v[142:145], v[194:197], v[54:57]
	v_mfma_f32_16x16x32_bf16 v[38:41], v[142:145], v[202:205], v[38:41]
	v_mfma_f32_16x16x32_bf16 v[30:33], v[150:153], v[202:205], v[30:33]
	v_mfma_f32_16x16x32_bf16 v[14:17], v[150:153], v[210:213], v[14:17]
	v_mfma_f32_16x16x32_bf16 v[22:25], v[142:145], v[210:213], v[22:25]
	v_mfma_f32_16x16x32_bf16 v[62:65], v[146:149], v[190:193], v[62:65]
	v_mfma_f32_16x16x32_bf16 v[58:61], v[154:157], v[190:193], v[58:61]
	v_mfma_f32_16x16x32_bf16 v[46:49], v[154:157], v[198:201], v[46:49]
	v_mfma_f32_16x16x32_bf16 v[54:57], v[146:149], v[198:201], v[54:57]
	v_mfma_f32_16x16x32_bf16 v[38:41], v[146:149], v[206:209], v[38:41]
	v_mfma_f32_16x16x32_bf16 v[30:33], v[154:157], v[206:209], v[30:33]
	v_mfma_f32_16x16x32_bf16 v[14:17], v[154:157], v[214:217], v[14:17]
	v_mfma_f32_16x16x32_bf16 v[22:25], v[146:149], v[214:217], v[22:25]
	s_setprio 0
	s_setprio 1
	v_mfma_f32_16x16x32_bf16 v[50:53], v[170:173], v[186:189], v[50:53]
	v_mfma_f32_16x16x32_bf16 v[42:45], v[178:181], v[186:189], v[42:45]
	v_mfma_f32_16x16x32_bf16 v[26:29], v[178:181], v[194:197], v[26:29]
	v_mfma_f32_16x16x32_bf16 v[34:37], v[170:173], v[194:197], v[34:37]
	v_mfma_f32_16x16x32_bf16 v[18:21], v[170:173], v[202:205], v[18:21]
	v_mfma_f32_16x16x32_bf16 v[10:13], v[178:181], v[202:205], v[10:13]
	v_mfma_f32_16x16x32_bf16 v[2:5], v[178:181], v[210:213], v[2:5]
	v_mfma_f32_16x16x32_bf16 v[6:9], v[170:173], v[210:213], v[6:9]
	v_mfma_f32_16x16x32_bf16 v[50:53], v[174:177], v[190:193], v[50:53]
	v_mfma_f32_16x16x32_bf16 v[42:45], v[182:185], v[190:193], v[42:45]
	v_mfma_f32_16x16x32_bf16 v[26:29], v[182:185], v[198:201], v[26:29]
	v_mfma_f32_16x16x32_bf16 v[34:37], v[174:177], v[198:201], v[34:37]
	v_mfma_f32_16x16x32_bf16 v[18:21], v[174:177], v[206:209], v[18:21]
	v_mfma_f32_16x16x32_bf16 v[10:13], v[182:185], v[206:209], v[10:13]
	v_mfma_f32_16x16x32_bf16 v[2:5], v[182:185], v[214:217], v[2:5]
	v_mfma_f32_16x16x32_bf16 v[6:9], v[174:177], v[214:217], v[6:9]
	s_setprio 0
	s_barrier
	s_add_i32 s29, s29, 2
	s_add_u32 s42, s42, 0x100
	s_addc_u32 s43, s43, 0
	s_add_u32 s19, s19, 0x100
	s_addc_u32 s27, s27, 0
	s_cmp_gt_u32 s29, 5
	s_cbranch_scc0 .LBB0_1264
	s_and_b64 vcc, exec, s[24:25]
	s_cbranch_vccz .LBB0_1267
	s_barrier

.LBB0_1336:
	ds_read_b128 v[154:157], v175
	ds_read_b128 v[158:161], v175 offset:1024
	ds_read_b128 v[164:167], v175 offset:2048
	ds_read_b128 v[168:171], v175 offset:3072
	ds_read_b128 v[180:183], v176
	ds_read_b128 v[184:187], v176 offset:1024
	ds_read_b128 v[188:191], v176 offset:2048
	ds_read_b128 v[192:195], v176 offset:3072
	s_add_u32 s20, s36, 0xfffe0080
	s_addc_u32 s21, s37, -1
	s_cmp_eq_u32 s19, 4
	s_cselect_b32 s41, s3, s21
	s_cselect_b32 s40, s14, s20
	s_cselect_b32 s39, s15, s18
	s_cselect_b32 s38, s16, s17
	v_lshl_add_u64 v[228:229], s[36:37], 0, v[144:145]
	s_add_i32 m0, s49, 0xc000
	ds_read_b128 v[196:199], v177
	ds_read_b128 v[200:203], v177 offset:1024
	ds_read_b128 v[204:207], v177 offset:2048
	ds_read_b128 v[208:211], v177 offset:3072
	ds_read_b128 v[212:215], v177 offset:4096
	ds_read_b128 v[216:219], v177 offset:5120
	ds_read_b128 v[220:223], v177 offset:6144
	ds_read_b128 v[224:227], v177 offset:7168
	global_load_lds_dwordx4 v[228:229], off
	v_lshl_add_u64 v[228:229], s[36:37], 0, v[146:147]
	s_add_i32 m0, s49, 0xe000
	s_nop 0
	global_load_lds_dwordx4 v[228:229], off
	s_waitcnt vmcnt(8)
	s_waitcnt lgkmcnt(0)
	s_barrier
	s_setprio 1
	s_waitcnt lgkmcnt(0)
	v_mfma_f32_16x16x32_bf16 v[126:129], v[154:157], v[196:199], v[126:129]
	v_mfma_f32_16x16x32_bf16 v[122:125], v[164:167], v[196:199], v[122:125]
	v_mfma_f32_16x16x32_bf16 v[110:113], v[164:167], v[204:207], v[110:113]
	v_mfma_f32_16x16x32_bf16 v[118:121], v[154:157], v[204:207], v[118:121]
	v_mfma_f32_16x16x32_bf16 v[102:105], v[154:157], v[212:215], v[102:105]
	v_mfma_f32_16x16x32_bf16 v[94:97], v[164:167], v[212:215], v[94:97]
	v_mfma_f32_16x16x32_bf16 v[78:81], v[164:167], v[220:223], v[78:81]
	v_mfma_f32_16x16x32_bf16 v[86:89], v[154:157], v[220:223], v[86:89]
	v_mfma_f32_16x16x32_bf16 v[126:129], v[158:161], v[200:203], v[126:129]
	v_mfma_f32_16x16x32_bf16 v[122:125], v[168:171], v[200:203], v[122:125]
	v_mfma_f32_16x16x32_bf16 v[110:113], v[168:171], v[208:211], v[110:113]
	v_mfma_f32_16x16x32_bf16 v[118:121], v[158:161], v[208:211], v[118:121]
	v_mfma_f32_16x16x32_bf16 v[102:105], v[158:161], v[216:219], v[102:105]
	v_mfma_f32_16x16x32_bf16 v[94:97], v[168:171], v[216:219], v[94:97]
	v_mfma_f32_16x16x32_bf16 v[78:81], v[168:171], v[224:227], v[78:81]
	v_mfma_f32_16x16x32_bf16 v[86:89], v[158:161], v[224:227], v[86:89]
	s_setprio 0
	s_setprio 1
	v_mfma_f32_16x16x32_bf16 v[114:117], v[180:183], v[196:199], v[114:117]
	v_mfma_f32_16x16x32_bf16 v[106:109], v[188:191], v[196:199], v[106:109]
	v_mfma_f32_16x16x32_bf16 v[90:93], v[188:191], v[204:207], v[90:93]
	v_mfma_f32_16x16x32_bf16 v[98:101], v[180:183], v[204:207], v[98:101]
	v_mfma_f32_16x16x32_bf16 v[82:85], v[180:183], v[212:215], v[82:85]
	v_mfma_f32_16x16x32_bf16 v[74:77], v[188:191], v[212:215], v[74:77]
	v_mfma_f32_16x16x32_bf16 v[66:69], v[188:191], v[220:223], v[66:69]
	v_mfma_f32_16x16x32_bf16 v[70:73], v[180:183], v[220:223], v[70:73]
	v_mfma_f32_16x16x32_bf16 v[114:117], v[184:187], v[200:203], v[114:117]
	v_mfma_f32_16x16x32_bf16 v[106:109], v[192:195], v[200:203], v[106:109]
	v_mfma_f32_16x16x32_bf16 v[90:93], v[192:195], v[208:211], v[90:93]
	v_mfma_f32_16x16x32_bf16 v[98:101], v[184:187], v[208:211], v[98:101]
	v_mfma_f32_16x16x32_bf16 v[82:85], v[184:187], v[216:219], v[82:85]
	v_mfma_f32_16x16x32_bf16 v[74:77], v[192:195], v[216:219], v[74:77]
	v_mfma_f32_16x16x32_bf16 v[66:69], v[192:195], v[224:227], v[66:69]
	v_mfma_f32_16x16x32_bf16 v[70:73], v[184:187], v[224:227], v[70:73]
	s_setprio 0
	s_barrier
	s_add_i32 s20, s57, s46
	v_lshl_add_u64 v[228:229], s[38:39], 0, v[134:135]
	s_mov_b32 m0, s20
	ds_read_b128 v[196:199], v177 offset:16384
	ds_read_b128 v[200:203], v177 offset:17408
	ds_read_b128 v[204:207], v177 offset:18432
	ds_read_b128 v[208:211], v177 offset:19456
	ds_read_b128 v[212:215], v177 offset:20480
	ds_read_b128 v[216:219], v177 offset:21504
	ds_read_b128 v[220:223], v177 offset:22528
	ds_read_b128 v[224:227], v177 offset:23552
	global_load_lds_dwordx4 v[228:229], off
	s_add_i32 m0, s20, 0x2000
	s_add_u32 s20, s38, 0x20000
	v_lshl_add_u64 v[230:231], s[38:39], 0, v[130:131]
	s_addc_u32 s21, s39, 0
	s_add_i32 s27, s60, s46
	global_load_lds_dwordx4 v[230:231], off
	v_lshl_add_u64 v[232:233], s[20:21], 0, v[134:135]
	s_mov_b32 m0, s27
	v_lshl_add_u64 v[234:235], s[40:41], 0, v[132:133]
	global_load_lds_dwordx4 v[232:233], off
	v_lshl_add_u64 v[232:233], s[20:21], 0, v[130:131]
	s_add_i32 m0, s27, 0x2000
	s_nop 0
	global_load_lds_dwordx4 v[232:233], off
	v_lshl_add_u64 v[232:233], s[40:41], 0, v[136:137]
	s_mov_b32 m0, s49
	s_nop 0
	global_load_lds_dwordx4 v[232:233], off
	s_mov_b32 m0, s50
	s_nop 0
	global_load_lds_dwordx4 v[234:235], off
	s_waitcnt vmcnt(8)
	s_waitcnt lgkmcnt(0)
	s_barrier
	s_setprio 1
	s_waitcnt lgkmcnt(0)
	v_mfma_f32_16x16x32_bf16 v[62:65], v[154:157], v[196:199], v[62:65]
	v_mfma_f32_16x16x32_bf16 v[58:61], v[164:167], v[196:199], v[58:61]
	v_mfma_f32_16x16x32_bf16 v[46:49], v[164:167], v[204:207], v[46:49]
	v_mfma_f32_16x16x32_bf16 v[54:57], v[154:157], v[204:207], v[54:57]
	v_mfma_f32_16x16x32_bf16 v[38:41], v[154:157], v[212:215], v[38:41]
	v_mfma_f32_16x16x32_bf16 v[30:33], v[164:167], v[212:215], v[30:33]
	v_mfma_f32_16x16x32_bf16 v[14:17], v[164:167], v[220:223], v[14:17]
	v_mfma_f32_16x16x32_bf16 v[22:25], v[154:157], v[220:223], v[22:25]
	v_mfma_f32_16x16x32_bf16 v[62:65], v[158:161], v[200:203], v[62:65]
	v_mfma_f32_16x16x32_bf16 v[58:61], v[168:171], v[200:203], v[58:61]
	v_mfma_f32_16x16x32_bf16 v[46:49], v[168:171], v[208:211], v[46:49]
	v_mfma_f32_16x16x32_bf16 v[54:57], v[158:161], v[208:211], v[54:57]
	v_mfma_f32_16x16x32_bf16 v[38:41], v[158:161], v[216:219], v[38:41]
	v_mfma_f32_16x16x32_bf16 v[30:33], v[168:171], v[216:219], v[30:33]
	v_mfma_f32_16x16x32_bf16 v[14:17], v[168:171], v[224:227], v[14:17]
	v_mfma_f32_16x16x32_bf16 v[22:25], v[158:161], v[224:227], v[22:25]
	s_setprio 0
	s_setprio 1
	v_mfma_f32_16x16x32_bf16 v[50:53], v[180:183], v[196:199], v[50:53]
	v_mfma_f32_16x16x32_bf16 v[42:45], v[188:191], v[196:199], v[42:45]
	v_mfma_f32_16x16x32_bf16 v[26:29], v[188:191], v[204:207], v[26:29]
	v_mfma_f32_16x16x32_bf16 v[34:37], v[180:183], v[204:207], v[34:37]
	v_mfma_f32_16x16x32_bf16 v[18:21], v[180:183], v[212:215], v[18:21]
	v_mfma_f32_16x16x32_bf16 v[10:13], v[188:191], v[212:215], v[10:13]
	v_mfma_f32_16x16x32_bf16 v[2:5], v[188:191], v[220:223], v[2:5]
	v_mfma_f32_16x16x32_bf16 v[6:9], v[180:183], v[220:223], v[6:9]
	v_mfma_f32_16x16x32_bf16 v[50:53], v[184:187], v[200:203], v[50:53]
	v_mfma_f32_16x16x32_bf16 v[42:45], v[192:195], v[200:203], v[42:45]
	v_mfma_f32_16x16x32_bf16 v[26:29], v[192:195], v[208:211], v[26:29]
	v_mfma_f32_16x16x32_bf16 v[34:37], v[184:187], v[208:211], v[34:37]
	v_mfma_f32_16x16x32_bf16 v[18:21], v[184:187], v[216:219], v[18:21]
	v_mfma_f32_16x16x32_bf16 v[10:13], v[192:195], v[216:219], v[10:13]
	v_mfma_f32_16x16x32_bf16 v[2:5], v[192:195], v[224:227], v[2:5]
	v_mfma_f32_16x16x32_bf16 v[6:9], v[184:187], v[224:227], v[6:9]
	s_setprio 0
	s_barrier
	s_add_i32 s27, 0, 0x18000
	v_add_u32_e32 v153, s27, v173
	s_add_i32 s29, 0, 0x1c000
	ds_read_b128 v[154:157], v153
	ds_read_b128 v[158:161], v153 offset:1024
	ds_read_b128 v[164:167], v153 offset:2048
	ds_read_b128 v[168:171], v153 offset:3072
	v_add_u32_e32 v153, s29, v173
	ds_read_b128 v[180:183], v153
	ds_read_b128 v[184:187], v153 offset:1024
	ds_read_b128 v[188:191], v153 offset:2048
	ds_read_b128 v[192:195], v153 offset:3072
	s_add_u32 s20, s40, 0x20000
	s_addc_u32 s21, s41, 0
	s_mov_b32 m0, s51
	v_lshl_add_u64 v[236:237], s[20:21], 0, v[136:137]
	ds_read_b128 v[196:199], v177 offset:32768
	ds_read_b128 v[200:203], v177 offset:33792
	ds_read_b128 v[204:207], v177 offset:34816
	ds_read_b128 v[208:211], v177 offset:35840
	ds_read_b128 v[212:215], v177 offset:36864
	ds_read_b128 v[216:219], v177 offset:37888
	ds_read_b128 v[220:223], v177 offset:38912
	ds_read_b128 v[224:227], v177 offset:39936
	global_load_lds_dwordx4 v[236:237], off
	v_lshl_add_u64 v[236:237], s[20:21], 0, v[132:133]
	s_mov_b32 m0, s52
	s_nop 0
	global_load_lds_dwordx4 v[236:237], off
	s_waitcnt vmcnt(8)
	s_waitcnt lgkmcnt(0)
	s_barrier
	s_setprio 1
	s_waitcnt lgkmcnt(0)
	v_mfma_f32_16x16x32_bf16 v[126:129], v[154:157], v[196:199], v[126:129]
	v_mfma_f32_16x16x32_bf16 v[122:125], v[164:167], v[196:199], v[122:125]
	v_mfma_f32_16x16x32_bf16 v[110:113], v[164:167], v[204:207], v[110:113]
	v_mfma_f32_16x16x32_bf16 v[118:121], v[154:157], v[204:207], v[118:121]
	v_mfma_f32_16x16x32_bf16 v[102:105], v[154:157], v[212:215], v[102:105]
	v_mfma_f32_16x16x32_bf16 v[94:97], v[164:167], v[212:215], v[94:97]
	v_mfma_f32_16x16x32_bf16 v[78:81], v[164:167], v[220:223], v[78:81]
	v_mfma_f32_16x16x32_bf16 v[86:89], v[154:157], v[220:223], v[86:89]
	v_mfma_f32_16x16x32_bf16 v[126:129], v[158:161], v[200:203], v[126:129]
	v_mfma_f32_16x16x32_bf16 v[122:125], v[168:171], v[200:203], v[122:125]
	v_mfma_f32_16x16x32_bf16 v[110:113], v[168:171], v[208:211], v[110:113]
	v_mfma_f32_16x16x32_bf16 v[118:121], v[158:161], v[208:211], v[118:121]
	v_mfma_f32_16x16x32_bf16 v[102:105], v[158:161], v[216:219], v[102:105]
	v_mfma_f32_16x16x32_bf16 v[94:97], v[168:171], v[216:219], v[94:97]
	v_mfma_f32_16x16x32_bf16 v[78:81], v[168:171], v[224:227], v[78:81]
	v_mfma_f32_16x16x32_bf16 v[86:89], v[158:161], v[224:227], v[86:89]
	s_setprio 0
	s_setprio 1
	v_mfma_f32_16x16x32_bf16 v[114:117], v[180:183], v[196:199], v[114:117]
	v_mfma_f32_16x16x32_bf16 v[106:109], v[188:191], v[196:199], v[106:109]
	v_mfma_f32_16x16x32_bf16 v[90:93], v[188:191], v[204:207], v[90:93]
	v_mfma_f32_16x16x32_bf16 v[98:101], v[180:183], v[204:207], v[98:101]
	v_mfma_f32_16x16x32_bf16 v[82:85], v[180:183], v[212:215], v[82:85]
	v_mfma_f32_16x16x32_bf16 v[74:77], v[188:191], v[212:215], v[74:77]
	v_mfma_f32_16x16x32_bf16 v[66:69], v[188:191], v[220:223], v[66:69]
	v_mfma_f32_16x16x32_bf16 v[70:73], v[180:183], v[220:223], v[70:73]
	v_mfma_f32_16x16x32_bf16 v[114:117], v[184:187], v[200:203], v[114:117]
	v_mfma_f32_16x16x32_bf16 v[106:109], v[192:195], v[200:203], v[106:109]
	v_mfma_f32_16x16x32_bf16 v[90:93], v[192:195], v[208:211], v[90:93]
	v_mfma_f32_16x16x32_bf16 v[98:101], v[184:187], v[208:211], v[98:101]
	v_mfma_f32_16x16x32_bf16 v[82:85], v[184:187], v[216:219], v[82:85]
	v_mfma_f32_16x16x32_bf16 v[74:77], v[192:195], v[216:219], v[74:77]
	v_mfma_f32_16x16x32_bf16 v[66:69], v[192:195], v[224:227], v[66:69]
	v_mfma_f32_16x16x32_bf16 v[70:73], v[184:187], v[224:227], v[70:73]
	s_setprio 0
	s_barrier
	s_add_i32 s20, s27, s46
	v_lshl_add_u64 v[228:229], v[228:229], 0, s[22:23]
	s_mov_b32 m0, s20
	ds_read_b128 v[196:199], v177 offset:49152
	ds_read_b128 v[200:203], v177 offset:50176
	ds_read_b128 v[204:207], v177 offset:51200
	ds_read_b128 v[208:211], v177 offset:52224
	ds_read_b128 v[212:215], v177 offset:53248
	ds_read_b128 v[216:219], v177 offset:54272
	ds_read_b128 v[220:223], v177 offset:55296
	ds_read_b128 v[224:227], v177 offset:56320
	global_load_lds_dwordx4 v[228:229], off
	s_add_i32 m0, s20, 0x2000
	s_add_u32 s20, s38, 0x20080
	v_lshl_add_u64 v[228:229], v[230:231], 0, s[22:23]
	s_addc_u32 s21, s39, 0
	s_add_i32 s27, s29, s46
	global_load_lds_dwordx4 v[228:229], off
	v_lshl_add_u64 v[228:229], s[20:21], 0, v[134:135]
	s_mov_b32 m0, s27
	s_nop 0
	global_load_lds_dwordx4 v[228:229], off
	v_lshl_add_u64 v[228:229], s[20:21], 0, v[130:131]
	s_add_i32 m0, s27, 0x2000
	s_nop 0
	global_load_lds_dwordx4 v[228:229], off
	v_lshl_add_u64 v[228:229], v[232:233], 0, s[22:23]
	s_mov_b32 m0, s53
	s_nop 0
	global_load_lds_dwordx4 v[228:229], off
	v_lshl_add_u64 v[228:229], v[234:235], 0, s[22:23]
	s_mov_b32 m0, s54
	s_nop 0
	global_load_lds_dwordx4 v[228:229], off
	s_waitcnt vmcnt(8)
	s_waitcnt lgkmcnt(0)
	s_barrier
	s_setprio 1
	s_waitcnt lgkmcnt(0)
	v_mfma_f32_16x16x32_bf16 v[62:65], v[154:157], v[196:199], v[62:65]
	v_mfma_f32_16x16x32_bf16 v[58:61], v[164:167], v[196:199], v[58:61]
	v_mfma_f32_16x16x32_bf16 v[46:49], v[164:167], v[204:207], v[46:49]
	v_mfma_f32_16x16x32_bf16 v[54:57], v[154:157], v[204:207], v[54:57]
	v_mfma_f32_16x16x32_bf16 v[38:41], v[154:157], v[212:215], v[38:41]
	v_mfma_f32_16x16x32_bf16 v[30:33], v[164:167], v[212:215], v[30:33]
	v_mfma_f32_16x16x32_bf16 v[14:17], v[164:167], v[220:223], v[14:17]
	v_mfma_f32_16x16x32_bf16 v[22:25], v[154:157], v[220:223], v[22:25]
	v_mfma_f32_16x16x32_bf16 v[62:65], v[158:161], v[200:203], v[62:65]
	v_mfma_f32_16x16x32_bf16 v[58:61], v[168:171], v[200:203], v[58:61]
	v_mfma_f32_16x16x32_bf16 v[46:49], v[168:171], v[208:211], v[46:49]
	v_mfma_f32_16x16x32_bf16 v[54:57], v[158:161], v[208:211], v[54:57]
	v_mfma_f32_16x16x32_bf16 v[38:41], v[158:161], v[216:219], v[38:41]
	v_mfma_f32_16x16x32_bf16 v[30:33], v[168:171], v[216:219], v[30:33]
	v_mfma_f32_16x16x32_bf16 v[14:17], v[168:171], v[224:227], v[14:17]
	v_mfma_f32_16x16x32_bf16 v[22:25], v[158:161], v[224:227], v[22:25]
	s_setprio 0
	s_setprio 1
	v_mfma_f32_16x16x32_bf16 v[50:53], v[180:183], v[196:199], v[50:53]
	v_mfma_f32_16x16x32_bf16 v[42:45], v[188:191], v[196:199], v[42:45]
	v_mfma_f32_16x16x32_bf16 v[26:29], v[188:191], v[204:207], v[26:29]
	v_mfma_f32_16x16x32_bf16 v[34:37], v[180:183], v[204:207], v[34:37]
	v_mfma_f32_16x16x32_bf16 v[18:21], v[180:183], v[212:215], v[18:21]
	v_mfma_f32_16x16x32_bf16 v[10:13], v[188:191], v[212:215], v[10:13]
	v_mfma_f32_16x16x32_bf16 v[2:5], v[188:191], v[220:223], v[2:5]
	v_mfma_f32_16x16x32_bf16 v[6:9], v[180:183], v[220:223], v[6:9]
	v_mfma_f32_16x16x32_bf16 v[50:53], v[184:187], v[200:203], v[50:53]
	v_mfma_f32_16x16x32_bf16 v[42:45], v[192:195], v[200:203], v[42:45]
	v_mfma_f32_16x16x32_bf16 v[26:29], v[192:195], v[208:211], v[26:29]
	v_mfma_f32_16x16x32_bf16 v[34:37], v[184:187], v[208:211], v[34:37]
	v_mfma_f32_16x16x32_bf16 v[18:21], v[184:187], v[216:219], v[18:21]
	v_mfma_f32_16x16x32_bf16 v[10:13], v[192:195], v[216:219], v[10:13]
	v_mfma_f32_16x16x32_bf16 v[2:5], v[192:195], v[224:227], v[2:5]
	v_mfma_f32_16x16x32_bf16 v[6:9], v[184:187], v[224:227], v[6:9]
	s_setprio 0
	s_barrier
	s_add_i32 s19, s19, 2
	s_add_u32 s36, s36, 0x100
	s_addc_u32 s37, s37, 0
	s_add_u32 s17, s17, 0x100
	s_addc_u32 s18, s18, 0
	s_cmp_gt_u32 s19, 5
	s_cbranch_scc0 .LBB0_1336
	s_and_b64 vcc, exec, s[24:25]
	s_cbranch_vccz .LBB0_1339
	s_barrier

.LBB0_1497:
	ds_read_b128 v[134:137], v214
	ds_read_b128 v[138:141], v214 offset:1024
	ds_read_b128 v[142:145], v214 offset:2048
	ds_read_b128 v[178:181], v214 offset:3072
	ds_read_b128 v[182:185], v215
	ds_read_b128 v[186:189], v215 offset:1024
	ds_read_b128 v[190:193], v215 offset:2048
	ds_read_b128 v[194:197], v215 offset:3072
	s_add_u32 s40, s38, 0x100
	s_addc_u32 s41, s39, 0
	s_add_u32 s0, s15, s38
	s_addc_u32 s1, s16, s39
	s_cmp_eq_u32 s17, 28
	s_cselect_b32 s45, s3, s1
	s_cselect_b32 s1, 0, s40
	s_cselect_b32 s44, s14, s0
	s_cselect_b32 s0, 0, s41
	s_add_u32 s42, s10, s1
	s_addc_u32 s43, s11, s0
	s_mov_b32 m0, s64
	v_lshl_add_u64 v[244:245], v[130:131], 0, s[38:39]
	ds_read_b128 v[198:201], v216
	ds_read_b128 v[202:205], v216 offset:1024
	ds_read_b128 v[206:209], v216 offset:2048
	ds_read_b128 v[224:227], v216 offset:3072
	ds_read_b128 v[228:231], v216 offset:4096
	ds_read_b128 v[232:235], v216 offset:5120
	ds_read_b128 v[236:239], v216 offset:6144
	ds_read_b128 v[240:243], v216 offset:7168
	global_load_lds_dwordx4 v[244:245], off
	v_lshl_add_u64 v[244:245], v[132:133], 0, s[38:39]
	s_mov_b32 m0, s65
	s_nop 0
	global_load_lds_dwordx4 v[244:245], off
	s_waitcnt vmcnt(8)
	s_waitcnt lgkmcnt(0)
	s_barrier
	s_setprio 1
	s_waitcnt lgkmcnt(0)
	v_mfma_f32_16x16x32_bf16 v[82:85], v[134:137], v[198:201], v[82:85]
	v_mfma_f32_16x16x32_bf16 v[78:81], v[142:145], v[198:201], v[78:81]
	v_mfma_f32_16x16x32_bf16 v[106:109], v[142:145], v[206:209], v[106:109]
	v_mfma_f32_16x16x32_bf16 v[110:113], v[134:137], v[206:209], v[110:113]
	v_mfma_f32_16x16x32_bf16 v[118:121], v[134:137], v[228:231], v[118:121]
	v_mfma_f32_16x16x32_bf16 v[114:117], v[142:145], v[228:231], v[114:117]
	v_mfma_f32_16x16x32_bf16 v[122:125], v[142:145], v[236:239], v[122:125]
	v_mfma_f32_16x16x32_bf16 v[126:129], v[134:137], v[236:239], v[126:129]
	v_mfma_f32_16x16x32_bf16 v[82:85], v[138:141], v[202:205], v[82:85]
	v_mfma_f32_16x16x32_bf16 v[78:81], v[178:181], v[202:205], v[78:81]
	v_mfma_f32_16x16x32_bf16 v[106:109], v[178:181], v[224:227], v[106:109]
	v_mfma_f32_16x16x32_bf16 v[110:113], v[138:141], v[224:227], v[110:113]
	v_mfma_f32_16x16x32_bf16 v[118:121], v[138:141], v[232:235], v[118:121]
	v_mfma_f32_16x16x32_bf16 v[114:117], v[178:181], v[232:235], v[114:117]
	v_mfma_f32_16x16x32_bf16 v[122:125], v[178:181], v[240:243], v[122:125]
	v_mfma_f32_16x16x32_bf16 v[126:129], v[138:141], v[240:243], v[126:129]
	s_setprio 0
	s_setprio 1
	v_mfma_f32_16x16x32_bf16 v[22:25], v[182:185], v[198:201], v[22:25]
	v_mfma_f32_16x16x32_bf16 v[26:29], v[190:193], v[198:201], v[26:29]
	v_mfma_f32_16x16x32_bf16 v[46:49], v[190:193], v[206:209], v[46:49]
	v_mfma_f32_16x16x32_bf16 v[42:45], v[182:185], v[206:209], v[42:45]
	v_mfma_f32_16x16x32_bf16 v[62:65], v[182:185], v[228:231], v[62:65]
	v_mfma_f32_16x16x32_bf16 v[70:73], v[190:193], v[228:231], v[70:73]
	v_mfma_f32_16x16x32_bf16 v[94:97], v[190:193], v[236:239], v[94:97]
	v_mfma_f32_16x16x32_bf16 v[90:93], v[182:185], v[236:239], v[90:93]
	v_mfma_f32_16x16x32_bf16 v[22:25], v[186:189], v[202:205], v[22:25]
	v_mfma_f32_16x16x32_bf16 v[26:29], v[194:197], v[202:205], v[26:29]
	v_mfma_f32_16x16x32_bf16 v[46:49], v[194:197], v[224:227], v[46:49]
	v_mfma_f32_16x16x32_bf16 v[42:45], v[186:189], v[224:227], v[42:45]
	v_mfma_f32_16x16x32_bf16 v[62:65], v[186:189], v[232:235], v[62:65]
	v_mfma_f32_16x16x32_bf16 v[70:73], v[194:197], v[232:235], v[70:73]
	v_mfma_f32_16x16x32_bf16 v[94:97], v[194:197], v[240:243], v[94:97]
	v_mfma_f32_16x16x32_bf16 v[90:93], v[186:189], v[240:243], v[90:93]
	s_setprio 0
	s_barrier
	s_mov_b32 m0, s66
	v_lshl_add_u64 v[244:245], s[42:43], 0, v[150:151]
	s_add_u32 s18, s42, 0x80000
	ds_read_b128 v[198:201], v216 offset:16384
	ds_read_b128 v[202:205], v216 offset:17408
	ds_read_b128 v[206:209], v216 offset:18432
	ds_read_b128 v[224:227], v216 offset:19456
	ds_read_b128 v[228:231], v216 offset:20480
	ds_read_b128 v[232:235], v216 offset:21504
	ds_read_b128 v[236:239], v216 offset:22528
	ds_read_b128 v[240:243], v216 offset:23552
	global_load_lds_dwordx4 v[244:245], off
	v_lshl_add_u64 v[246:247], s[42:43], 0, v[146:147]
	s_mov_b32 m0, s67
	s_addc_u32 s19, s43, 0
	global_load_lds_dwordx4 v[246:247], off
	v_lshl_add_u64 v[248:249], s[18:19], 0, v[150:151]
	s_mov_b32 m0, s68
	v_lshl_add_u64 v[250:251], s[44:45], 0, v[148:149]
	global_load_lds_dwordx4 v[248:249], off
	v_lshl_add_u64 v[248:249], s[18:19], 0, v[146:147]
	s_mov_b32 m0, s69
	s_nop 0
	global_load_lds_dwordx4 v[248:249], off
	v_lshl_add_u64 v[248:249], s[44:45], 0, v[152:153]
	s_mov_b32 m0, s9
	s_nop 0
	global_load_lds_dwordx4 v[248:249], off
	s_mov_b32 m0, s55
	s_nop 0
	global_load_lds_dwordx4 v[250:251], off
	s_waitcnt vmcnt(8)
	s_waitcnt lgkmcnt(0)
	s_barrier
	s_setprio 1
	s_waitcnt lgkmcnt(0)
	v_mfma_f32_16x16x32_bf16 v[102:105], v[134:137], v[198:201], v[102:105]
	v_mfma_f32_16x16x32_bf16 v[98:101], v[142:145], v[198:201], v[98:101]
	v_mfma_f32_16x16x32_bf16 v[58:61], v[142:145], v[206:209], v[58:61]
	v_mfma_f32_16x16x32_bf16 v[66:69], v[134:137], v[206:209], v[66:69]
	v_mfma_f32_16x16x32_bf16 v[38:41], v[134:137], v[228:231], v[38:41]
	v_mfma_f32_16x16x32_bf16 v[34:37], v[142:145], v[228:231], v[34:37]
	v_mfma_f32_16x16x32_bf16 v[10:13], v[142:145], v[236:239], v[10:13]
	v_mfma_f32_16x16x32_bf16 v[14:17], v[134:137], v[236:239], v[14:17]
	v_mfma_f32_16x16x32_bf16 v[102:105], v[138:141], v[202:205], v[102:105]
	v_mfma_f32_16x16x32_bf16 v[98:101], v[178:181], v[202:205], v[98:101]
	v_mfma_f32_16x16x32_bf16 v[58:61], v[178:181], v[224:227], v[58:61]
	v_mfma_f32_16x16x32_bf16 v[66:69], v[138:141], v[224:227], v[66:69]
	v_mfma_f32_16x16x32_bf16 v[38:41], v[138:141], v[232:235], v[38:41]
	v_mfma_f32_16x16x32_bf16 v[34:37], v[178:181], v[232:235], v[34:37]
	v_mfma_f32_16x16x32_bf16 v[10:13], v[178:181], v[240:243], v[10:13]
	v_mfma_f32_16x16x32_bf16 v[14:17], v[138:141], v[240:243], v[14:17]
	s_setprio 0
	s_setprio 1
	v_mfma_f32_16x16x32_bf16 v[86:89], v[182:185], v[198:201], v[86:89]
	v_mfma_f32_16x16x32_bf16 v[74:77], v[190:193], v[198:201], v[74:77]
	v_mfma_f32_16x16x32_bf16 v[50:53], v[190:193], v[206:209], v[50:53]
	v_mfma_f32_16x16x32_bf16 v[54:57], v[182:185], v[206:209], v[54:57]
	v_mfma_f32_16x16x32_bf16 v[30:33], v[182:185], v[228:231], v[30:33]
	v_mfma_f32_16x16x32_bf16 v[18:21], v[190:193], v[228:231], v[18:21]
	v_mfma_f32_16x16x32_bf16 v[2:5], v[190:193], v[236:239], v[2:5]
	v_mfma_f32_16x16x32_bf16 v[6:9], v[182:185], v[236:239], v[6:9]
	v_mfma_f32_16x16x32_bf16 v[86:89], v[186:189], v[202:205], v[86:89]
	v_mfma_f32_16x16x32_bf16 v[74:77], v[194:197], v[202:205], v[74:77]
	v_mfma_f32_16x16x32_bf16 v[50:53], v[194:197], v[224:227], v[50:53]
	v_mfma_f32_16x16x32_bf16 v[54:57], v[186:189], v[224:227], v[54:57]
	v_mfma_f32_16x16x32_bf16 v[30:33], v[186:189], v[232:235], v[30:33]
	v_mfma_f32_16x16x32_bf16 v[18:21], v[194:197], v[232:235], v[18:21]
	v_mfma_f32_16x16x32_bf16 v[2:5], v[194:197], v[240:243], v[2:5]
	v_mfma_f32_16x16x32_bf16 v[6:9], v[186:189], v[240:243], v[6:9]
	s_setprio 0
	s_barrier
	s_add_i32 s0, 0, 0x1c000
	v_add_u32_e32 v194, s0, v212
	ds_read_b128 v[134:137], v220
	ds_read_b128 v[138:141], v220 offset:1024
	ds_read_b128 v[142:145], v220 offset:2048
	ds_read_b128 v[178:181], v220 offset:3072
	ds_read_b128 v[182:185], v194
	ds_read_b128 v[186:189], v194 offset:1024
	ds_read_b128 v[190:193], v194 offset:2048
	ds_read_b128 v[194:197], v194 offset:3072
	s_add_u32 s18, s44, 0x80000
	s_addc_u32 s19, s45, 0
	s_mov_b32 m0, s56
	v_lshl_add_u64 v[252:253], s[18:19], 0, v[152:153]
	ds_read_b128 v[198:201], v216 offset:32768
	ds_read_b128 v[202:205], v216 offset:33792
	ds_read_b128 v[206:209], v216 offset:34816
	ds_read_b128 v[224:227], v216 offset:35840
	ds_read_b128 v[228:231], v216 offset:36864
	ds_read_b128 v[232:235], v216 offset:37888
	ds_read_b128 v[236:239], v216 offset:38912
	ds_read_b128 v[240:243], v216 offset:39936
	global_load_lds_dwordx4 v[252:253], off
	v_lshl_add_u64 v[252:253], s[18:19], 0, v[148:149]
	s_mov_b32 m0, s57
	s_nop 0
	global_load_lds_dwordx4 v[252:253], off
	s_waitcnt vmcnt(8)
	s_waitcnt lgkmcnt(0)
	s_barrier
	s_setprio 1
	s_waitcnt lgkmcnt(0)
	v_mfma_f32_16x16x32_bf16 v[82:85], v[134:137], v[198:201], v[82:85]
	v_mfma_f32_16x16x32_bf16 v[78:81], v[142:145], v[198:201], v[78:81]
	v_mfma_f32_16x16x32_bf16 v[106:109], v[142:145], v[206:209], v[106:109]
	v_mfma_f32_16x16x32_bf16 v[110:113], v[134:137], v[206:209], v[110:113]
	v_mfma_f32_16x16x32_bf16 v[118:121], v[134:137], v[228:231], v[118:121]
	v_mfma_f32_16x16x32_bf16 v[114:117], v[142:145], v[228:231], v[114:117]
	v_mfma_f32_16x16x32_bf16 v[122:125], v[142:145], v[236:239], v[122:125]
	v_mfma_f32_16x16x32_bf16 v[126:129], v[134:137], v[236:239], v[126:129]
	v_mfma_f32_16x16x32_bf16 v[82:85], v[138:141], v[202:205], v[82:85]
	v_mfma_f32_16x16x32_bf16 v[78:81], v[178:181], v[202:205], v[78:81]
	v_mfma_f32_16x16x32_bf16 v[106:109], v[178:181], v[224:227], v[106:109]
	v_mfma_f32_16x16x32_bf16 v[110:113], v[138:141], v[224:227], v[110:113]
	v_mfma_f32_16x16x32_bf16 v[118:121], v[138:141], v[232:235], v[118:121]
	v_mfma_f32_16x16x32_bf16 v[114:117], v[178:181], v[232:235], v[114:117]
	v_mfma_f32_16x16x32_bf16 v[122:125], v[178:181], v[240:243], v[122:125]
	v_mfma_f32_16x16x32_bf16 v[126:129], v[138:141], v[240:243], v[126:129]
	s_setprio 0
	s_setprio 1
	v_mfma_f32_16x16x32_bf16 v[22:25], v[182:185], v[198:201], v[22:25]
	v_mfma_f32_16x16x32_bf16 v[26:29], v[190:193], v[198:201], v[26:29]
	v_mfma_f32_16x16x32_bf16 v[46:49], v[190:193], v[206:209], v[46:49]
	v_mfma_f32_16x16x32_bf16 v[42:45], v[182:185], v[206:209], v[42:45]
	v_mfma_f32_16x16x32_bf16 v[62:65], v[182:185], v[228:231], v[62:65]
	v_mfma_f32_16x16x32_bf16 v[70:73], v[190:193], v[228:231], v[70:73]
	v_mfma_f32_16x16x32_bf16 v[94:97], v[190:193], v[236:239], v[94:97]
	v_mfma_f32_16x16x32_bf16 v[90:93], v[182:185], v[236:239], v[90:93]
	v_mfma_f32_16x16x32_bf16 v[22:25], v[186:189], v[202:205], v[22:25]
	v_mfma_f32_16x16x32_bf16 v[26:29], v[194:197], v[202:205], v[26:29]
	v_mfma_f32_16x16x32_bf16 v[46:49], v[194:197], v[224:227], v[46:49]
	v_mfma_f32_16x16x32_bf16 v[42:45], v[186:189], v[224:227], v[42:45]
	v_mfma_f32_16x16x32_bf16 v[62:65], v[186:189], v[232:235], v[62:65]
	v_mfma_f32_16x16x32_bf16 v[70:73], v[194:197], v[232:235], v[70:73]
	v_mfma_f32_16x16x32_bf16 v[94:97], v[194:197], v[240:243], v[94:97]
	v_mfma_f32_16x16x32_bf16 v[90:93], v[186:189], v[240:243], v[90:93]
	s_setprio 0
	s_barrier
	s_add_i32 s1, s72, s54
	v_lshl_add_u64 v[244:245], v[244:245], 0, s[26:27]
	s_mov_b32 m0, s1
	ds_read_b128 v[198:201], v216 offset:49152
	ds_read_b128 v[202:205], v216 offset:50176
	ds_read_b128 v[206:209], v216 offset:51200
	ds_read_b128 v[224:227], v216 offset:52224
	ds_read_b128 v[228:231], v216 offset:53248
	ds_read_b128 v[232:235], v216 offset:54272
	ds_read_b128 v[236:239], v216 offset:55296
	ds_read_b128 v[240:243], v216 offset:56320
	global_load_lds_dwordx4 v[244:245], off
	s_add_i32 m0, s1, 0x2000
	s_add_u32 s18, s42, 0x80080
	v_lshl_add_u64 v[244:245], v[246:247], 0, s[26:27]
	s_addc_u32 s19, s43, 0
	s_add_i32 s0, s0, s54
	global_load_lds_dwordx4 v[244:245], off
	v_lshl_add_u64 v[244:245], s[18:19], 0, v[150:151]
	s_mov_b32 m0, s0
	s_nop 0
	global_load_lds_dwordx4 v[244:245], off
	v_lshl_add_u64 v[244:245], s[18:19], 0, v[146:147]
	s_add_i32 m0, s0, 0x2000
	s_nop 0
	global_load_lds_dwordx4 v[244:245], off
	v_lshl_add_u64 v[244:245], v[248:249], 0, s[26:27]
	s_mov_b32 m0, s61
	s_nop 0
	global_load_lds_dwordx4 v[244:245], off
	v_lshl_add_u64 v[244:245], v[250:251], 0, s[26:27]
	s_mov_b32 m0, s62
	s_nop 0
	global_load_lds_dwordx4 v[244:245], off
	s_waitcnt vmcnt(8)
	s_waitcnt lgkmcnt(0)
	s_barrier
	s_setprio 1
	s_waitcnt lgkmcnt(0)
	v_mfma_f32_16x16x32_bf16 v[102:105], v[134:137], v[198:201], v[102:105]
	v_mfma_f32_16x16x32_bf16 v[98:101], v[142:145], v[198:201], v[98:101]
	v_mfma_f32_16x16x32_bf16 v[58:61], v[142:145], v[206:209], v[58:61]
	v_mfma_f32_16x16x32_bf16 v[66:69], v[134:137], v[206:209], v[66:69]
	v_mfma_f32_16x16x32_bf16 v[38:41], v[134:137], v[228:231], v[38:41]
	v_mfma_f32_16x16x32_bf16 v[34:37], v[142:145], v[228:231], v[34:37]
	v_mfma_f32_16x16x32_bf16 v[10:13], v[142:145], v[236:239], v[10:13]
	v_mfma_f32_16x16x32_bf16 v[14:17], v[134:137], v[236:239], v[14:17]
	v_mfma_f32_16x16x32_bf16 v[102:105], v[138:141], v[202:205], v[102:105]
	v_mfma_f32_16x16x32_bf16 v[98:101], v[178:181], v[202:205], v[98:101]
	v_mfma_f32_16x16x32_bf16 v[58:61], v[178:181], v[224:227], v[58:61]
	v_mfma_f32_16x16x32_bf16 v[66:69], v[138:141], v[224:227], v[66:69]
	v_mfma_f32_16x16x32_bf16 v[38:41], v[138:141], v[232:235], v[38:41]
	v_mfma_f32_16x16x32_bf16 v[34:37], v[178:181], v[232:235], v[34:37]
	v_mfma_f32_16x16x32_bf16 v[10:13], v[178:181], v[240:243], v[10:13]
	v_mfma_f32_16x16x32_bf16 v[14:17], v[138:141], v[240:243], v[14:17]
	s_setprio 0
	s_setprio 1
	v_mfma_f32_16x16x32_bf16 v[86:89], v[182:185], v[198:201], v[86:89]
	v_mfma_f32_16x16x32_bf16 v[74:77], v[190:193], v[198:201], v[74:77]
	v_mfma_f32_16x16x32_bf16 v[50:53], v[190:193], v[206:209], v[50:53]
	v_mfma_f32_16x16x32_bf16 v[54:57], v[182:185], v[206:209], v[54:57]
	v_mfma_f32_16x16x32_bf16 v[30:33], v[182:185], v[228:231], v[30:33]
	v_mfma_f32_16x16x32_bf16 v[18:21], v[190:193], v[228:231], v[18:21]
	v_mfma_f32_16x16x32_bf16 v[2:5], v[190:193], v[236:239], v[2:5]
	v_mfma_f32_16x16x32_bf16 v[6:9], v[182:185], v[236:239], v[6:9]
	v_mfma_f32_16x16x32_bf16 v[86:89], v[186:189], v[202:205], v[86:89]
	v_mfma_f32_16x16x32_bf16 v[74:77], v[194:197], v[202:205], v[74:77]
	v_mfma_f32_16x16x32_bf16 v[50:53], v[194:197], v[224:227], v[50:53]
	v_mfma_f32_16x16x32_bf16 v[54:57], v[186:189], v[224:227], v[54:57]
	v_mfma_f32_16x16x32_bf16 v[30:33], v[186:189], v[232:235], v[30:33]
	v_mfma_f32_16x16x32_bf16 v[18:21], v[194:197], v[232:235], v[18:21]
	v_mfma_f32_16x16x32_bf16 v[2:5], v[194:197], v[240:243], v[2:5]
	v_mfma_f32_16x16x32_bf16 v[6:9], v[186:189], v[240:243], v[6:9]
	s_setprio 0
	s_barrier
	s_add_i32 s17, s17, 2
	s_cmp_gt_u32 s17, 29
	s_mov_b64 s[38:39], s[40:41]
	s_cbranch_scc0 .LBB0_1497
	s_and_b64 vcc, exec, s[28:29]
	s_cbranch_vccz .LBB0_1500
	s_barrier

.LBB0_1604:
	ds_read_b128 v[154:157], v151
	ds_read_b128 v[158:161], v151 offset:1024
	ds_read_b128 v[164:167], v151 offset:2048
	ds_read_b128 v[168:171], v151 offset:3072
	ds_read_b128 v[172:175], v152
	ds_read_b128 v[176:179], v152 offset:1024
	ds_read_b128 v[180:183], v152 offset:2048
	ds_read_b128 v[184:187], v152 offset:3072
	s_add_u32 s0, s34, 0xfff80080
	s_addc_u32 s1, s35, -1
	s_cmp_eq_u32 s53, 28
	s_cselect_b32 s39, s16, s1
	s_cselect_b32 s38, s17, s0
	s_cselect_b32 s37, s18, s25
	s_cselect_b32 s36, s19, s23
	v_lshl_add_u64 v[146:147], s[34:35], 0, v[138:139]
	s_add_i32 m0, s31, 0xc000
	ds_read_b128 v[188:191], v153
	ds_read_b128 v[192:195], v153 offset:1024
	ds_read_b128 v[196:199], v153 offset:2048
	ds_read_b128 v[200:203], v153 offset:3072
	ds_read_b128 v[204:207], v153 offset:4096
	ds_read_b128 v[208:211], v153 offset:5120
	ds_read_b128 v[212:215], v153 offset:6144
	ds_read_b128 v[216:219], v153 offset:7168
	global_load_lds_dwordx4 v[146:147], off
	v_lshl_add_u64 v[146:147], s[34:35], 0, v[140:141]
	s_add_i32 m0, s31, 0xe000
	s_nop 0
	global_load_lds_dwordx4 v[146:147], off
	s_waitcnt vmcnt(8)
	s_waitcnt lgkmcnt(0)
	s_barrier
	s_setprio 1
	s_waitcnt lgkmcnt(0)
	v_mfma_f32_16x16x32_bf16 v[126:129], v[154:157], v[188:191], v[126:129]
	v_mfma_f32_16x16x32_bf16 v[122:125], v[164:167], v[188:191], v[122:125]
	v_mfma_f32_16x16x32_bf16 v[106:109], v[164:167], v[196:199], v[106:109]
	v_mfma_f32_16x16x32_bf16 v[110:113], v[154:157], v[196:199], v[110:113]
	v_mfma_f32_16x16x32_bf16 v[94:97], v[154:157], v[204:207], v[94:97]
	v_mfma_f32_16x16x32_bf16 v[90:93], v[164:167], v[204:207], v[90:93]
	v_mfma_f32_16x16x32_bf16 v[74:77], v[164:167], v[212:215], v[74:77]
	v_mfma_f32_16x16x32_bf16 v[78:81], v[154:157], v[212:215], v[78:81]
	v_mfma_f32_16x16x32_bf16 v[126:129], v[158:161], v[192:195], v[126:129]
	v_mfma_f32_16x16x32_bf16 v[122:125], v[168:171], v[192:195], v[122:125]
	v_mfma_f32_16x16x32_bf16 v[106:109], v[168:171], v[200:203], v[106:109]
	v_mfma_f32_16x16x32_bf16 v[110:113], v[158:161], v[200:203], v[110:113]
	v_mfma_f32_16x16x32_bf16 v[94:97], v[158:161], v[208:211], v[94:97]
	v_mfma_f32_16x16x32_bf16 v[90:93], v[168:171], v[208:211], v[90:93]
	v_mfma_f32_16x16x32_bf16 v[74:77], v[168:171], v[216:219], v[74:77]
	v_mfma_f32_16x16x32_bf16 v[78:81], v[158:161], v[216:219], v[78:81]
	s_setprio 0
	s_setprio 1
	v_mfma_f32_16x16x32_bf16 v[118:121], v[172:175], v[188:191], v[118:121]
	v_mfma_f32_16x16x32_bf16 v[114:117], v[180:183], v[188:191], v[114:117]
	v_mfma_f32_16x16x32_bf16 v[98:101], v[180:183], v[196:199], v[98:101]
	v_mfma_f32_16x16x32_bf16 v[102:105], v[172:175], v[196:199], v[102:105]
	v_mfma_f32_16x16x32_bf16 v[86:89], v[172:175], v[204:207], v[86:89]
	v_mfma_f32_16x16x32_bf16 v[82:85], v[180:183], v[204:207], v[82:85]
	v_mfma_f32_16x16x32_bf16 v[66:69], v[180:183], v[212:215], v[66:69]
	v_mfma_f32_16x16x32_bf16 v[70:73], v[172:175], v[212:215], v[70:73]
	v_mfma_f32_16x16x32_bf16 v[118:121], v[176:179], v[192:195], v[118:121]
	v_mfma_f32_16x16x32_bf16 v[114:117], v[184:187], v[192:195], v[114:117]
	v_mfma_f32_16x16x32_bf16 v[98:101], v[184:187], v[200:203], v[98:101]
	v_mfma_f32_16x16x32_bf16 v[102:105], v[176:179], v[200:203], v[102:105]
	v_mfma_f32_16x16x32_bf16 v[86:89], v[176:179], v[208:211], v[86:89]
	v_mfma_f32_16x16x32_bf16 v[82:85], v[184:187], v[208:211], v[82:85]
	v_mfma_f32_16x16x32_bf16 v[66:69], v[184:187], v[216:219], v[66:69]
	v_mfma_f32_16x16x32_bf16 v[70:73], v[176:179], v[216:219], v[70:73]
	s_setprio 0
	s_barrier
	s_add_i32 s0, s15, s44
	v_lshl_add_u64 v[146:147], s[36:37], 0, v[134:135]
	s_mov_b32 m0, s0
	ds_read_b128 v[188:191], v153 offset:16384
	ds_read_b128 v[192:195], v153 offset:17408
	ds_read_b128 v[196:199], v153 offset:18432
	ds_read_b128 v[200:203], v153 offset:19456
	ds_read_b128 v[204:207], v153 offset:20480
	ds_read_b128 v[208:211], v153 offset:21504
	ds_read_b128 v[212:215], v153 offset:22528
	ds_read_b128 v[216:219], v153 offset:23552
	global_load_lds_dwordx4 v[146:147], off
	s_add_i32 m0, s0, 0x2000
	s_add_u32 s54, s36, 0x80000
	v_lshl_add_u64 v[220:221], s[36:37], 0, v[130:131]
	s_addc_u32 s55, s37, 0
	s_add_i32 s0, s51, s44
	global_load_lds_dwordx4 v[220:221], off
	v_lshl_add_u64 v[222:223], s[54:55], 0, v[134:135]
	s_mov_b32 m0, s0
	v_lshl_add_u64 v[224:225], s[38:39], 0, v[132:133]
	global_load_lds_dwordx4 v[222:223], off
	v_lshl_add_u64 v[222:223], s[54:55], 0, v[130:131]
	s_add_i32 m0, s0, 0x2000
	s_nop 0
	global_load_lds_dwordx4 v[222:223], off
	v_lshl_add_u64 v[222:223], s[38:39], 0, v[136:137]
	s_mov_b32 m0, s31
	s_nop 0
	global_load_lds_dwordx4 v[222:223], off
	s_mov_b32 m0, s47
	s_nop 0
	global_load_lds_dwordx4 v[224:225], off
	s_waitcnt vmcnt(8)
	s_waitcnt lgkmcnt(0)
	s_barrier
	s_setprio 1
	s_waitcnt lgkmcnt(0)
	v_mfma_f32_16x16x32_bf16 v[62:65], v[154:157], v[188:191], v[62:65]
	v_mfma_f32_16x16x32_bf16 v[58:61], v[164:167], v[188:191], v[58:61]
	v_mfma_f32_16x16x32_bf16 v[42:45], v[164:167], v[196:199], v[42:45]
	v_mfma_f32_16x16x32_bf16 v[46:49], v[154:157], v[196:199], v[46:49]
	v_mfma_f32_16x16x32_bf16 v[30:33], v[154:157], v[204:207], v[30:33]
	v_mfma_f32_16x16x32_bf16 v[26:29], v[164:167], v[204:207], v[26:29]
	v_mfma_f32_16x16x32_bf16 v[10:13], v[164:167], v[212:215], v[10:13]
	v_mfma_f32_16x16x32_bf16 v[14:17], v[154:157], v[212:215], v[14:17]
	v_mfma_f32_16x16x32_bf16 v[62:65], v[158:161], v[192:195], v[62:65]
	v_mfma_f32_16x16x32_bf16 v[58:61], v[168:171], v[192:195], v[58:61]
	v_mfma_f32_16x16x32_bf16 v[42:45], v[168:171], v[200:203], v[42:45]
	v_mfma_f32_16x16x32_bf16 v[46:49], v[158:161], v[200:203], v[46:49]
	v_mfma_f32_16x16x32_bf16 v[30:33], v[158:161], v[208:211], v[30:33]
	v_mfma_f32_16x16x32_bf16 v[26:29], v[168:171], v[208:211], v[26:29]
	v_mfma_f32_16x16x32_bf16 v[10:13], v[168:171], v[216:219], v[10:13]
	v_mfma_f32_16x16x32_bf16 v[14:17], v[158:161], v[216:219], v[14:17]
	s_setprio 0
	s_setprio 1
	v_mfma_f32_16x16x32_bf16 v[54:57], v[172:175], v[188:191], v[54:57]
	v_mfma_f32_16x16x32_bf16 v[50:53], v[180:183], v[188:191], v[50:53]
	v_mfma_f32_16x16x32_bf16 v[34:37], v[180:183], v[196:199], v[34:37]
	v_mfma_f32_16x16x32_bf16 v[38:41], v[172:175], v[196:199], v[38:41]
	v_mfma_f32_16x16x32_bf16 v[22:25], v[172:175], v[204:207], v[22:25]
	v_mfma_f32_16x16x32_bf16 v[18:21], v[180:183], v[204:207], v[18:21]
	v_mfma_f32_16x16x32_bf16 v[2:5], v[180:183], v[212:215], v[2:5]
	v_mfma_f32_16x16x32_bf16 v[6:9], v[172:175], v[212:215], v[6:9]
	v_mfma_f32_16x16x32_bf16 v[54:57], v[176:179], v[192:195], v[54:57]
	v_mfma_f32_16x16x32_bf16 v[50:53], v[184:187], v[192:195], v[50:53]
	v_mfma_f32_16x16x32_bf16 v[34:37], v[184:187], v[200:203], v[34:37]
	v_mfma_f32_16x16x32_bf16 v[38:41], v[176:179], v[200:203], v[38:41]
	v_mfma_f32_16x16x32_bf16 v[22:25], v[176:179], v[208:211], v[22:25]
	v_mfma_f32_16x16x32_bf16 v[18:21], v[184:187], v[208:211], v[18:21]
	v_mfma_f32_16x16x32_bf16 v[2:5], v[184:187], v[216:219], v[2:5]
	v_mfma_f32_16x16x32_bf16 v[6:9], v[176:179], v[216:219], v[6:9]
	s_setprio 0
	s_barrier
	s_add_i32 s0, 0, 0x18000
	v_add_u32_e32 v163, s0, v149
	s_add_i32 s1, 0, 0x1c000
	ds_read_b128 v[154:157], v163
	ds_read_b128 v[158:161], v163 offset:1024
	ds_read_b128 v[164:167], v163 offset:2048
	ds_read_b128 v[168:171], v163 offset:3072
	v_add_u32_e32 v163, s1, v149
	ds_read_b128 v[172:175], v163
	ds_read_b128 v[176:179], v163 offset:1024
	ds_read_b128 v[180:183], v163 offset:2048
	ds_read_b128 v[184:187], v163 offset:3072
	s_add_u32 s38, s38, 0x80000
	s_addc_u32 s39, s39, 0
	s_mov_b32 m0, s48
	v_lshl_add_u64 v[226:227], s[38:39], 0, v[136:137]
	ds_read_b128 v[188:191], v153 offset:32768
	ds_read_b128 v[192:195], v153 offset:33792
	ds_read_b128 v[196:199], v153 offset:34816
	ds_read_b128 v[200:203], v153 offset:35840
	ds_read_b128 v[204:207], v153 offset:36864
	ds_read_b128 v[208:211], v153 offset:37888
	ds_read_b128 v[212:215], v153 offset:38912
	ds_read_b128 v[216:219], v153 offset:39936
	global_load_lds_dwordx4 v[226:227], off
	v_lshl_add_u64 v[226:227], s[38:39], 0, v[132:133]
	s_mov_b32 m0, s49
	s_nop 0
	global_load_lds_dwordx4 v[226:227], off
	s_waitcnt vmcnt(8)
	s_waitcnt lgkmcnt(0)
	s_barrier
	s_setprio 1
	s_waitcnt lgkmcnt(0)
	v_mfma_f32_16x16x32_bf16 v[126:129], v[154:157], v[188:191], v[126:129]
	v_mfma_f32_16x16x32_bf16 v[122:125], v[164:167], v[188:191], v[122:125]
	v_mfma_f32_16x16x32_bf16 v[106:109], v[164:167], v[196:199], v[106:109]
	v_mfma_f32_16x16x32_bf16 v[110:113], v[154:157], v[196:199], v[110:113]
	v_mfma_f32_16x16x32_bf16 v[94:97], v[154:157], v[204:207], v[94:97]
	v_mfma_f32_16x16x32_bf16 v[90:93], v[164:167], v[204:207], v[90:93]
	v_mfma_f32_16x16x32_bf16 v[74:77], v[164:167], v[212:215], v[74:77]
	v_mfma_f32_16x16x32_bf16 v[78:81], v[154:157], v[212:215], v[78:81]
	v_mfma_f32_16x16x32_bf16 v[126:129], v[158:161], v[192:195], v[126:129]
	v_mfma_f32_16x16x32_bf16 v[122:125], v[168:171], v[192:195], v[122:125]
	v_mfma_f32_16x16x32_bf16 v[106:109], v[168:171], v[200:203], v[106:109]
	v_mfma_f32_16x16x32_bf16 v[110:113], v[158:161], v[200:203], v[110:113]
	v_mfma_f32_16x16x32_bf16 v[94:97], v[158:161], v[208:211], v[94:97]
	v_mfma_f32_16x16x32_bf16 v[90:93], v[168:171], v[208:211], v[90:93]
	v_mfma_f32_16x16x32_bf16 v[74:77], v[168:171], v[216:219], v[74:77]
	v_mfma_f32_16x16x32_bf16 v[78:81], v[158:161], v[216:219], v[78:81]
	s_setprio 0
	s_setprio 1
	v_mfma_f32_16x16x32_bf16 v[118:121], v[172:175], v[188:191], v[118:121]
	v_mfma_f32_16x16x32_bf16 v[114:117], v[180:183], v[188:191], v[114:117]
	v_mfma_f32_16x16x32_bf16 v[98:101], v[180:183], v[196:199], v[98:101]
	v_mfma_f32_16x16x32_bf16 v[102:105], v[172:175], v[196:199], v[102:105]
	v_mfma_f32_16x16x32_bf16 v[86:89], v[172:175], v[204:207], v[86:89]
	v_mfma_f32_16x16x32_bf16 v[82:85], v[180:183], v[204:207], v[82:85]
	v_mfma_f32_16x16x32_bf16 v[66:69], v[180:183], v[212:215], v[66:69]
	v_mfma_f32_16x16x32_bf16 v[70:73], v[172:175], v[212:215], v[70:73]
	v_mfma_f32_16x16x32_bf16 v[118:121], v[176:179], v[192:195], v[118:121]
	v_mfma_f32_16x16x32_bf16 v[114:117], v[184:187], v[192:195], v[114:117]
	v_mfma_f32_16x16x32_bf16 v[98:101], v[184:187], v[200:203], v[98:101]
	v_mfma_f32_16x16x32_bf16 v[102:105], v[176:179], v[200:203], v[102:105]
	v_mfma_f32_16x16x32_bf16 v[86:89], v[176:179], v[208:211], v[86:89]
	v_mfma_f32_16x16x32_bf16 v[82:85], v[184:187], v[208:211], v[82:85]
	v_mfma_f32_16x16x32_bf16 v[66:69], v[184:187], v[216:219], v[66:69]
	v_mfma_f32_16x16x32_bf16 v[70:73], v[176:179], v[216:219], v[70:73]
	s_setprio 0
	s_barrier
	s_add_i32 s0, s0, s44
	v_lshl_add_u64 v[146:147], v[146:147], 0, s[10:11]
	s_mov_b32 m0, s0
	ds_read_b128 v[188:191], v153 offset:49152
	ds_read_b128 v[192:195], v153 offset:50176
	ds_read_b128 v[196:199], v153 offset:51200
	ds_read_b128 v[200:203], v153 offset:52224
	ds_read_b128 v[204:207], v153 offset:53248
	ds_read_b128 v[208:211], v153 offset:54272
	ds_read_b128 v[212:215], v153 offset:55296
	ds_read_b128 v[216:219], v153 offset:56320
	global_load_lds_dwordx4 v[146:147], off
	s_add_i32 m0, s0, 0x2000
	s_add_u32 s36, s36, 0x80080
	v_lshl_add_u64 v[146:147], v[220:221], 0, s[10:11]
	s_addc_u32 s37, s37, 0
	s_add_i32 s0, s1, s44
	global_load_lds_dwordx4 v[146:147], off
	v_lshl_add_u64 v[146:147], s[36:37], 0, v[134:135]
	s_mov_b32 m0, s0
	s_nop 0
	global_load_lds_dwordx4 v[146:147], off
	v_lshl_add_u64 v[146:147], s[36:37], 0, v[130:131]
	s_add_i32 m0, s0, 0x2000
	s_nop 0
	global_load_lds_dwordx4 v[146:147], off
	v_lshl_add_u64 v[146:147], v[222:223], 0, s[10:11]
	s_mov_b32 m0, s20
	s_nop 0
	global_load_lds_dwordx4 v[146:147], off
	v_lshl_add_u64 v[146:147], v[224:225], 0, s[10:11]
	s_mov_b32 m0, s21
	s_nop 0
	global_load_lds_dwordx4 v[146:147], off
	s_waitcnt vmcnt(8)
	s_waitcnt lgkmcnt(0)
	s_barrier
	s_setprio 1
	s_waitcnt lgkmcnt(0)
	v_mfma_f32_16x16x32_bf16 v[62:65], v[154:157], v[188:191], v[62:65]
	v_mfma_f32_16x16x32_bf16 v[58:61], v[164:167], v[188:191], v[58:61]
	v_mfma_f32_16x16x32_bf16 v[42:45], v[164:167], v[196:199], v[42:45]
	v_mfma_f32_16x16x32_bf16 v[46:49], v[154:157], v[196:199], v[46:49]
	v_mfma_f32_16x16x32_bf16 v[30:33], v[154:157], v[204:207], v[30:33]
	v_mfma_f32_16x16x32_bf16 v[26:29], v[164:167], v[204:207], v[26:29]
	v_mfma_f32_16x16x32_bf16 v[10:13], v[164:167], v[212:215], v[10:13]
	v_mfma_f32_16x16x32_bf16 v[14:17], v[154:157], v[212:215], v[14:17]
	v_mfma_f32_16x16x32_bf16 v[62:65], v[158:161], v[192:195], v[62:65]
	v_mfma_f32_16x16x32_bf16 v[58:61], v[168:171], v[192:195], v[58:61]
	v_mfma_f32_16x16x32_bf16 v[42:45], v[168:171], v[200:203], v[42:45]
	v_mfma_f32_16x16x32_bf16 v[46:49], v[158:161], v[200:203], v[46:49]
	v_mfma_f32_16x16x32_bf16 v[30:33], v[158:161], v[208:211], v[30:33]
	v_mfma_f32_16x16x32_bf16 v[26:29], v[168:171], v[208:211], v[26:29]
	v_mfma_f32_16x16x32_bf16 v[10:13], v[168:171], v[216:219], v[10:13]
	v_mfma_f32_16x16x32_bf16 v[14:17], v[158:161], v[216:219], v[14:17]
	s_setprio 0
	s_setprio 1
	v_mfma_f32_16x16x32_bf16 v[54:57], v[172:175], v[188:191], v[54:57]
	v_mfma_f32_16x16x32_bf16 v[50:53], v[180:183], v[188:191], v[50:53]
	v_mfma_f32_16x16x32_bf16 v[34:37], v[180:183], v[196:199], v[34:37]
	v_mfma_f32_16x16x32_bf16 v[38:41], v[172:175], v[196:199], v[38:41]
	v_mfma_f32_16x16x32_bf16 v[22:25], v[172:175], v[204:207], v[22:25]
	v_mfma_f32_16x16x32_bf16 v[18:21], v[180:183], v[204:207], v[18:21]
	v_mfma_f32_16x16x32_bf16 v[2:5], v[180:183], v[212:215], v[2:5]
	v_mfma_f32_16x16x32_bf16 v[6:9], v[172:175], v[212:215], v[6:9]
	v_mfma_f32_16x16x32_bf16 v[54:57], v[176:179], v[192:195], v[54:57]
	v_mfma_f32_16x16x32_bf16 v[50:53], v[184:187], v[192:195], v[50:53]
	v_mfma_f32_16x16x32_bf16 v[34:37], v[184:187], v[200:203], v[34:37]
	v_mfma_f32_16x16x32_bf16 v[38:41], v[176:179], v[200:203], v[38:41]
	v_mfma_f32_16x16x32_bf16 v[22:25], v[176:179], v[208:211], v[22:25]
	v_mfma_f32_16x16x32_bf16 v[18:21], v[184:187], v[208:211], v[18:21]
	v_mfma_f32_16x16x32_bf16 v[2:5], v[184:187], v[216:219], v[2:5]
	v_mfma_f32_16x16x32_bf16 v[6:9], v[176:179], v[216:219], v[6:9]
	s_setprio 0
	s_barrier
	s_add_i32 s53, s53, 2
	s_add_u32 s34, s34, 0x100
	s_addc_u32 s35, s35, 0
	s_add_u32 s23, s23, 0x100
	s_addc_u32 s25, s25, 0
	s_cmp_gt_u32 s53, 29
	s_cbranch_scc0 .LBB0_1604
	s_and_b64 vcc, exec, s[12:13]
	s_cbranch_vccz .LBB0_1607
	s_barrier

.LBB0_1675:
	ds_read_b128 v[156:159], v191
	ds_read_b128 v[160:163], v191 offset:1024
	ds_read_b128 v[164:167], v191 offset:2048
	ds_read_b128 v[168:171], v191 offset:3072
	ds_read_b128 v[172:175], v192
	ds_read_b128 v[176:179], v192 offset:1024
	ds_read_b128 v[180:183], v192 offset:2048
	ds_read_b128 v[184:187], v192 offset:3072
	s_add_u32 s36, s30, 0xffea0080
	s_addc_u32 s37, s31, -1
	s_cmpk_eq_i32 s29, 0x54
	s_cselect_b32 s39, s25, s37
	s_cselect_b32 s38, s24, s36
	s_cselect_b32 s37, s5, s35
	s_cselect_b32 s36, s4, s34
	s_mov_b32 m0, s57
	v_lshl_add_u64 v[234:235], s[30:31], 0, v[150:151]
	ds_read_b128 v[202:205], v193
	ds_read_b128 v[206:209], v193 offset:1024
	ds_read_b128 v[210:213], v193 offset:2048
	ds_read_b128 v[214:217], v193 offset:3072
	ds_read_b128 v[218:221], v193 offset:4096
	ds_read_b128 v[222:225], v193 offset:5120
	ds_read_b128 v[226:229], v193 offset:6144
	ds_read_b128 v[230:233], v193 offset:7168
	global_load_lds_dwordx4 v[234:235], off
	v_lshl_add_u64 v[234:235], s[30:31], 0, v[152:153]
	s_mov_b32 m0, s58
	s_nop 0
	global_load_lds_dwordx4 v[234:235], off
	s_waitcnt vmcnt(8)
	s_waitcnt lgkmcnt(0)
	s_barrier
	s_setprio 1
	s_waitcnt lgkmcnt(0)
	v_mfma_f32_16x16x32_bf16 v[126:129], v[156:159], v[202:205], v[126:129]
	v_mfma_f32_16x16x32_bf16 v[122:125], v[164:167], v[202:205], v[122:125]
	v_mfma_f32_16x16x32_bf16 v[106:109], v[164:167], v[210:213], v[106:109]
	v_mfma_f32_16x16x32_bf16 v[110:113], v[156:159], v[210:213], v[110:113]
	v_mfma_f32_16x16x32_bf16 v[94:97], v[156:159], v[218:221], v[94:97]
	v_mfma_f32_16x16x32_bf16 v[90:93], v[164:167], v[218:221], v[90:93]
	v_mfma_f32_16x16x32_bf16 v[74:77], v[164:167], v[226:229], v[74:77]
	v_mfma_f32_16x16x32_bf16 v[78:81], v[156:159], v[226:229], v[78:81]
	v_mfma_f32_16x16x32_bf16 v[126:129], v[160:163], v[206:209], v[126:129]
	v_mfma_f32_16x16x32_bf16 v[122:125], v[168:171], v[206:209], v[122:125]
	v_mfma_f32_16x16x32_bf16 v[106:109], v[168:171], v[214:217], v[106:109]
	v_mfma_f32_16x16x32_bf16 v[110:113], v[160:163], v[214:217], v[110:113]
	v_mfma_f32_16x16x32_bf16 v[94:97], v[160:163], v[222:225], v[94:97]
	v_mfma_f32_16x16x32_bf16 v[90:93], v[168:171], v[222:225], v[90:93]
	v_mfma_f32_16x16x32_bf16 v[74:77], v[168:171], v[230:233], v[74:77]
	v_mfma_f32_16x16x32_bf16 v[78:81], v[160:163], v[230:233], v[78:81]
	s_setprio 0
	s_setprio 1
	v_mfma_f32_16x16x32_bf16 v[118:121], v[172:175], v[202:205], v[118:121]
	v_mfma_f32_16x16x32_bf16 v[114:117], v[180:183], v[202:205], v[114:117]
	v_mfma_f32_16x16x32_bf16 v[98:101], v[180:183], v[210:213], v[98:101]
	v_mfma_f32_16x16x32_bf16 v[102:105], v[172:175], v[210:213], v[102:105]
	v_mfma_f32_16x16x32_bf16 v[86:89], v[172:175], v[218:221], v[86:89]
	v_mfma_f32_16x16x32_bf16 v[82:85], v[180:183], v[218:221], v[82:85]
	v_mfma_f32_16x16x32_bf16 v[66:69], v[180:183], v[226:229], v[66:69]
	v_mfma_f32_16x16x32_bf16 v[70:73], v[172:175], v[226:229], v[70:73]
	v_mfma_f32_16x16x32_bf16 v[118:121], v[176:179], v[206:209], v[118:121]
	v_mfma_f32_16x16x32_bf16 v[114:117], v[184:187], v[206:209], v[114:117]
	v_mfma_f32_16x16x32_bf16 v[98:101], v[184:187], v[214:217], v[98:101]
	v_mfma_f32_16x16x32_bf16 v[102:105], v[176:179], v[214:217], v[102:105]
	v_mfma_f32_16x16x32_bf16 v[86:89], v[176:179], v[222:225], v[86:89]
	v_mfma_f32_16x16x32_bf16 v[82:85], v[184:187], v[222:225], v[82:85]
	v_mfma_f32_16x16x32_bf16 v[66:69], v[184:187], v[230:233], v[66:69]
	v_mfma_f32_16x16x32_bf16 v[70:73], v[176:179], v[230:233], v[70:73]
	s_setprio 0
	s_barrier
	s_mov_b32 m0, s59
	v_lshl_add_u64 v[234:235], s[36:37], 0, v[134:135]
	s_add_u32 s40, s36, 0x160000
	ds_read_b128 v[202:205], v193 offset:16384
	ds_read_b128 v[206:209], v193 offset:17408
	ds_read_b128 v[210:213], v193 offset:18432
	ds_read_b128 v[214:217], v193 offset:19456
	ds_read_b128 v[218:221], v193 offset:20480
	ds_read_b128 v[222:225], v193 offset:21504
	ds_read_b128 v[226:229], v193 offset:22528
	ds_read_b128 v[230:233], v193 offset:23552
	global_load_lds_dwordx4 v[234:235], off
	v_lshl_add_u64 v[236:237], s[36:37], 0, v[130:131]
	s_mov_b32 m0, s60
	s_addc_u32 s41, s37, 0
	global_load_lds_dwordx4 v[236:237], off
	v_lshl_add_u64 v[238:239], s[40:41], 0, v[134:135]
	s_mov_b32 m0, s61
	v_lshl_add_u64 v[240:241], s[38:39], 0, v[132:133]
	global_load_lds_dwordx4 v[238:239], off
	v_lshl_add_u64 v[238:239], s[40:41], 0, v[130:131]
	s_mov_b32 m0, s62
	s_nop 0
	global_load_lds_dwordx4 v[238:239], off
	v_lshl_add_u64 v[238:239], s[38:39], 0, v[136:137]
	s_mov_b32 m0, s48
	s_nop 0
	global_load_lds_dwordx4 v[238:239], off
	s_mov_b32 m0, s49
	s_nop 0
	global_load_lds_dwordx4 v[240:241], off
	s_waitcnt vmcnt(8)
	s_waitcnt lgkmcnt(0)
	s_barrier
	s_setprio 1
	s_waitcnt lgkmcnt(0)
	v_mfma_f32_16x16x32_bf16 v[62:65], v[156:159], v[202:205], v[62:65]
	v_mfma_f32_16x16x32_bf16 v[58:61], v[164:167], v[202:205], v[58:61]
	v_mfma_f32_16x16x32_bf16 v[42:45], v[164:167], v[210:213], v[42:45]
	v_mfma_f32_16x16x32_bf16 v[46:49], v[156:159], v[210:213], v[46:49]
	v_mfma_f32_16x16x32_bf16 v[30:33], v[156:159], v[218:221], v[30:33]
	v_mfma_f32_16x16x32_bf16 v[26:29], v[164:167], v[218:221], v[26:29]
	v_mfma_f32_16x16x32_bf16 v[10:13], v[164:167], v[226:229], v[10:13]
	v_mfma_f32_16x16x32_bf16 v[14:17], v[156:159], v[226:229], v[14:17]
	v_mfma_f32_16x16x32_bf16 v[62:65], v[160:163], v[206:209], v[62:65]
	v_mfma_f32_16x16x32_bf16 v[58:61], v[168:171], v[206:209], v[58:61]
	v_mfma_f32_16x16x32_bf16 v[42:45], v[168:171], v[214:217], v[42:45]
	v_mfma_f32_16x16x32_bf16 v[46:49], v[160:163], v[214:217], v[46:49]
	v_mfma_f32_16x16x32_bf16 v[30:33], v[160:163], v[222:225], v[30:33]
	v_mfma_f32_16x16x32_bf16 v[26:29], v[168:171], v[222:225], v[26:29]
	v_mfma_f32_16x16x32_bf16 v[10:13], v[168:171], v[230:233], v[10:13]
	v_mfma_f32_16x16x32_bf16 v[14:17], v[160:163], v[230:233], v[14:17]
	s_setprio 0
	s_setprio 1
	v_mfma_f32_16x16x32_bf16 v[54:57], v[172:175], v[202:205], v[54:57]
	v_mfma_f32_16x16x32_bf16 v[50:53], v[180:183], v[202:205], v[50:53]
	v_mfma_f32_16x16x32_bf16 v[34:37], v[180:183], v[210:213], v[34:37]
	v_mfma_f32_16x16x32_bf16 v[38:41], v[172:175], v[210:213], v[38:41]
	v_mfma_f32_16x16x32_bf16 v[22:25], v[172:175], v[218:221], v[22:25]
	v_mfma_f32_16x16x32_bf16 v[18:21], v[180:183], v[218:221], v[18:21]
	v_mfma_f32_16x16x32_bf16 v[2:5], v[180:183], v[226:229], v[2:5]
	v_mfma_f32_16x16x32_bf16 v[6:9], v[172:175], v[226:229], v[6:9]
	v_mfma_f32_16x16x32_bf16 v[54:57], v[176:179], v[206:209], v[54:57]
	v_mfma_f32_16x16x32_bf16 v[50:53], v[184:187], v[206:209], v[50:53]
	v_mfma_f32_16x16x32_bf16 v[34:37], v[184:187], v[214:217], v[34:37]
	v_mfma_f32_16x16x32_bf16 v[38:41], v[176:179], v[214:217], v[38:41]
	v_mfma_f32_16x16x32_bf16 v[22:25], v[176:179], v[222:225], v[22:25]
	v_mfma_f32_16x16x32_bf16 v[18:21], v[184:187], v[222:225], v[18:21]
	v_mfma_f32_16x16x32_bf16 v[2:5], v[184:187], v[230:233], v[2:5]
	v_mfma_f32_16x16x32_bf16 v[6:9], v[176:179], v[230:233], v[6:9]
	s_setprio 0
	s_barrier
	ds_read_b128 v[156:159], v197
	ds_read_b128 v[160:163], v197 offset:1024
	ds_read_b128 v[164:167], v197 offset:2048
	ds_read_b128 v[168:171], v197 offset:3072
	ds_read_b128 v[172:175], v198
	ds_read_b128 v[176:179], v198 offset:1024
	ds_read_b128 v[180:183], v198 offset:2048
	ds_read_b128 v[184:187], v198 offset:3072
	s_add_u32 s38, s38, 0x160000
	s_addc_u32 s39, s39, 0
	s_mov_b32 m0, s50
	v_lshl_add_u64 v[242:243], s[38:39], 0, v[136:137]
	ds_read_b128 v[202:205], v193 offset:32768
	ds_read_b128 v[206:209], v193 offset:33792
	ds_read_b128 v[210:213], v193 offset:34816
	ds_read_b128 v[214:217], v193 offset:35840
	ds_read_b128 v[218:221], v193 offset:36864
	ds_read_b128 v[222:225], v193 offset:37888
	ds_read_b128 v[226:229], v193 offset:38912
	ds_read_b128 v[230:233], v193 offset:39936
	global_load_lds_dwordx4 v[242:243], off
	v_lshl_add_u64 v[242:243], s[38:39], 0, v[132:133]
	s_mov_b32 m0, s51
	s_nop 0
	global_load_lds_dwordx4 v[242:243], off
	s_waitcnt vmcnt(8)
	s_waitcnt lgkmcnt(0)
	s_barrier
	s_setprio 1
	s_waitcnt lgkmcnt(0)
	v_mfma_f32_16x16x32_bf16 v[126:129], v[156:159], v[202:205], v[126:129]
	v_mfma_f32_16x16x32_bf16 v[122:125], v[164:167], v[202:205], v[122:125]
	v_mfma_f32_16x16x32_bf16 v[106:109], v[164:167], v[210:213], v[106:109]
	v_mfma_f32_16x16x32_bf16 v[110:113], v[156:159], v[210:213], v[110:113]
	v_mfma_f32_16x16x32_bf16 v[94:97], v[156:159], v[218:221], v[94:97]
	v_mfma_f32_16x16x32_bf16 v[90:93], v[164:167], v[218:221], v[90:93]
	v_mfma_f32_16x16x32_bf16 v[74:77], v[164:167], v[226:229], v[74:77]
	v_mfma_f32_16x16x32_bf16 v[78:81], v[156:159], v[226:229], v[78:81]
	v_mfma_f32_16x16x32_bf16 v[126:129], v[160:163], v[206:209], v[126:129]
	v_mfma_f32_16x16x32_bf16 v[122:125], v[168:171], v[206:209], v[122:125]
	v_mfma_f32_16x16x32_bf16 v[106:109], v[168:171], v[214:217], v[106:109]
	v_mfma_f32_16x16x32_bf16 v[110:113], v[160:163], v[214:217], v[110:113]
	v_mfma_f32_16x16x32_bf16 v[94:97], v[160:163], v[222:225], v[94:97]
	v_mfma_f32_16x16x32_bf16 v[90:93], v[168:171], v[222:225], v[90:93]
	v_mfma_f32_16x16x32_bf16 v[74:77], v[168:171], v[230:233], v[74:77]
	v_mfma_f32_16x16x32_bf16 v[78:81], v[160:163], v[230:233], v[78:81]
	s_setprio 0
	s_setprio 1
	v_mfma_f32_16x16x32_bf16 v[118:121], v[172:175], v[202:205], v[118:121]
	v_mfma_f32_16x16x32_bf16 v[114:117], v[180:183], v[202:205], v[114:117]
	v_mfma_f32_16x16x32_bf16 v[98:101], v[180:183], v[210:213], v[98:101]
	v_mfma_f32_16x16x32_bf16 v[102:105], v[172:175], v[210:213], v[102:105]
	v_mfma_f32_16x16x32_bf16 v[86:89], v[172:175], v[218:221], v[86:89]
	v_mfma_f32_16x16x32_bf16 v[82:85], v[180:183], v[218:221], v[82:85]
	v_mfma_f32_16x16x32_bf16 v[66:69], v[180:183], v[226:229], v[66:69]
	v_mfma_f32_16x16x32_bf16 v[70:73], v[172:175], v[226:229], v[70:73]
	v_mfma_f32_16x16x32_bf16 v[118:121], v[176:179], v[206:209], v[118:121]
	v_mfma_f32_16x16x32_bf16 v[114:117], v[184:187], v[206:209], v[114:117]
	v_mfma_f32_16x16x32_bf16 v[98:101], v[184:187], v[214:217], v[98:101]
	v_mfma_f32_16x16x32_bf16 v[102:105], v[176:179], v[214:217], v[102:105]
	v_mfma_f32_16x16x32_bf16 v[86:89], v[176:179], v[222:225], v[86:89]
	v_mfma_f32_16x16x32_bf16 v[82:85], v[184:187], v[222:225], v[82:85]
	v_mfma_f32_16x16x32_bf16 v[66:69], v[184:187], v[230:233], v[66:69]
	v_mfma_f32_16x16x32_bf16 v[70:73], v[176:179], v[230:233], v[70:73]
	s_setprio 0
	s_barrier
	s_mov_b32 m0, s64
	v_lshl_add_u64 v[234:235], v[234:235], 0, s[12:13]
	s_add_u32 s36, s36, 0x160080
	ds_read_b128 v[202:205], v193 offset:49152
	ds_read_b128 v[206:209], v193 offset:50176
	ds_read_b128 v[210:213], v193 offset:51200
	ds_read_b128 v[214:217], v193 offset:52224
	ds_read_b128 v[218:221], v193 offset:53248
	ds_read_b128 v[222:225], v193 offset:54272
	ds_read_b128 v[226:229], v193 offset:55296
	ds_read_b128 v[230:233], v193 offset:56320
	global_load_lds_dwordx4 v[234:235], off
	v_lshl_add_u64 v[234:235], v[236:237], 0, s[12:13]
	s_mov_b32 m0, s65
	s_addc_u32 s37, s37, 0
	s_add_i32 s38, s63, s47
	global_load_lds_dwordx4 v[234:235], off
	v_lshl_add_u64 v[234:235], s[36:37], 0, v[134:135]
	s_mov_b32 m0, s38
	s_nop 0
	global_load_lds_dwordx4 v[234:235], off
	v_lshl_add_u64 v[234:235], s[36:37], 0, v[130:131]
	s_add_i32 m0, s38, 0x2000
	s_nop 0
	global_load_lds_dwordx4 v[234:235], off
	v_lshl_add_u64 v[234:235], v[238:239], 0, s[12:13]
	s_mov_b32 m0, s55
	s_nop 0
	global_load_lds_dwordx4 v[234:235], off
	v_lshl_add_u64 v[234:235], v[240:241], 0, s[12:13]
	s_mov_b32 m0, s56
	s_nop 0
	global_load_lds_dwordx4 v[234:235], off
	s_waitcnt vmcnt(8)
	s_waitcnt lgkmcnt(0)
	s_barrier
	s_setprio 1
	s_waitcnt lgkmcnt(0)
	v_mfma_f32_16x16x32_bf16 v[62:65], v[156:159], v[202:205], v[62:65]
	v_mfma_f32_16x16x32_bf16 v[58:61], v[164:167], v[202:205], v[58:61]
	v_mfma_f32_16x16x32_bf16 v[42:45], v[164:167], v[210:213], v[42:45]
	v_mfma_f32_16x16x32_bf16 v[46:49], v[156:159], v[210:213], v[46:49]
	v_mfma_f32_16x16x32_bf16 v[30:33], v[156:159], v[218:221], v[30:33]
	v_mfma_f32_16x16x32_bf16 v[26:29], v[164:167], v[218:221], v[26:29]
	v_mfma_f32_16x16x32_bf16 v[10:13], v[164:167], v[226:229], v[10:13]
	v_mfma_f32_16x16x32_bf16 v[14:17], v[156:159], v[226:229], v[14:17]
	v_mfma_f32_16x16x32_bf16 v[62:65], v[160:163], v[206:209], v[62:65]
	v_mfma_f32_16x16x32_bf16 v[58:61], v[168:171], v[206:209], v[58:61]
	v_mfma_f32_16x16x32_bf16 v[42:45], v[168:171], v[214:217], v[42:45]
	v_mfma_f32_16x16x32_bf16 v[46:49], v[160:163], v[214:217], v[46:49]
	v_mfma_f32_16x16x32_bf16 v[30:33], v[160:163], v[222:225], v[30:33]
	v_mfma_f32_16x16x32_bf16 v[26:29], v[168:171], v[222:225], v[26:29]
	v_mfma_f32_16x16x32_bf16 v[10:13], v[168:171], v[230:233], v[10:13]
	v_mfma_f32_16x16x32_bf16 v[14:17], v[160:163], v[230:233], v[14:17]
	s_setprio 0
	s_setprio 1
	v_mfma_f32_16x16x32_bf16 v[54:57], v[172:175], v[202:205], v[54:57]
	v_mfma_f32_16x16x32_bf16 v[50:53], v[180:183], v[202:205], v[50:53]
	v_mfma_f32_16x16x32_bf16 v[34:37], v[180:183], v[210:213], v[34:37]
	v_mfma_f32_16x16x32_bf16 v[38:41], v[172:175], v[210:213], v[38:41]
	v_mfma_f32_16x16x32_bf16 v[22:25], v[172:175], v[218:221], v[22:25]
	v_mfma_f32_16x16x32_bf16 v[18:21], v[180:183], v[218:221], v[18:21]
	v_mfma_f32_16x16x32_bf16 v[2:5], v[180:183], v[226:229], v[2:5]
	v_mfma_f32_16x16x32_bf16 v[6:9], v[172:175], v[226:229], v[6:9]
	v_mfma_f32_16x16x32_bf16 v[54:57], v[176:179], v[206:209], v[54:57]
	v_mfma_f32_16x16x32_bf16 v[50:53], v[184:187], v[206:209], v[50:53]
	v_mfma_f32_16x16x32_bf16 v[34:37], v[184:187], v[214:217], v[34:37]
	v_mfma_f32_16x16x32_bf16 v[38:41], v[176:179], v[214:217], v[38:41]
	v_mfma_f32_16x16x32_bf16 v[22:25], v[176:179], v[222:225], v[22:25]
	v_mfma_f32_16x16x32_bf16 v[18:21], v[184:187], v[222:225], v[18:21]
	v_mfma_f32_16x16x32_bf16 v[2:5], v[184:187], v[230:233], v[2:5]
	v_mfma_f32_16x16x32_bf16 v[6:9], v[176:179], v[230:233], v[6:9]
	s_setprio 0
	s_barrier
	s_add_i32 s29, s29, 2
	s_add_u32 s30, s30, 0x100
	s_addc_u32 s31, s31, 0
	s_add_u32 s34, s34, 0x100
	s_addc_u32 s35, s35, 0
	s_cmpk_gt_u32 s29, 0x55
	s_cbranch_scc0 .LBB0_1675
	s_and_b64 vcc, exec, s[14:15]
	s_cbranch_vccz .LBB0_1678
	s_barrier
